# v83 + K-loop scalar tail issued in the shadow of the phase-8 MFMAs instead of behind the last one
# speedup vs baseline: 1.0060x; 1.0049x over previous
.LBB0_266:
	s_xor_b64 s[2:3], s[2:3], -1
	s_mov_b32 s34, s74
	s_add_i32 s74, s74, 1
	s_cmp_lt_u32 s34, 5
	s_mov_b64 s[4:5], s[10:11]
	s_mov_b32 s10, s75
	s_cselect_b64 s[14:15], -1, 0
	s_add_i32 s75, s74, s16
	s_mov_b64 s[12:13], s[8:9]
	s_and_b64 s[8:9], s[14:15], exec
	s_cselect_b32 s8, s75, s10
	s_cselect_b32 s10, s6, s6
	s_ashr_i32 s11, s10, 31
	s_lshl_b64 s[10:11], s[10:11], 19
	s_add_u32 s10, s80, s10
	s_addc_u32 s11, s81, s11
	s_and_b64 s[44:45], s[14:15], exec
	s_cselect_b32 s44, s11, s5
	s_cselect_b32 s45, s10, s4
	s_ashr_i32 s9, s8, 31
	s_lshl_b64 s[8:9], s[8:9], 19
	v_readlane_b32 s47, v255, 14
	s_add_u32 s8, s47, s8
	v_readlane_b32 s47, v255, 15
	s_addc_u32 s9, s47, s9
	s_and_b64 s[14:15], s[14:15], exec
	s_cselect_b32 s47, s9, s13
	s_cselect_b32 s55, s8, s12
	s_add_u32 s4, s4, 0x40080
	s_addc_u32 s5, s5, 0
	s_add_u32 s78, s12, 0x100
	s_addc_u32 s79, s13, 0
	s_mov_b32 s85, -2
	s_waitcnt lgkmcnt(0)
	s_add_i32 s86, 0, 0x10000
	v_add_u32_e32 v0, s86, v150
	v_add_u32_e32 v189, 0x10000, v150
	ds_read_b128 v[142:145], v0
	ds_read_b128 v[146:149], v0 offset:1024
	ds_read_b128 v[152:155], v0 offset:2048
	ds_read_b128 v[156:159], v0 offset:3072
	s_add_u32 s12, s4, 0xfffc0080
	s_addc_u32 s13, s5, -1
	s_cmp_eq_u32 s85, 12
	s_cselect_b32 s15, s44, s13
	s_cselect_b32 s14, s45, s12
	s_cselect_b32 s13, s47, s79
	s_cselect_b32 s12, s55, s78
	s_add_i32 m0, s7, 0xc000
	ds_read_b128 v[160:163], v151
	ds_read_b128 v[164:167], v151 offset:1024
	ds_read_b128 v[168:171], v151 offset:2048
	ds_read_b128 v[172:175], v151 offset:3072
	ds_read_b128 v[176:179], v151 offset:4096
	ds_read_b128 v[180:183], v151 offset:5120
	ds_read_b128 v[184:187], v151 offset:6144
	global_load_lds_dwordx4 v138, s[4:5]
	s_add_i32 m0, s7, 0xe000
	ds_read_b128 v[190:193], v151 offset:7168
	global_load_lds_dwordx4 v140, s[4:5]
	s_waitcnt lgkmcnt(8)
	s_barrier
	s_waitcnt lgkmcnt(0)
	v_mfma_f32_16x16x32_bf16 v[126:129], v[142:145], v[160:163], 0
	v_mfma_f32_16x16x32_bf16 v[122:125], v[152:155], v[160:163], 0
	v_mfma_f32_16x16x32_bf16 v[110:113], v[142:145], v[168:171], 0
	v_mfma_f32_16x16x32_bf16 v[106:109], v[152:155], v[168:171], 0
	v_mfma_f32_16x16x32_bf16 v[94:97], v[142:145], v[176:179], 0
	v_mfma_f32_16x16x32_bf16 v[90:93], v[152:155], v[176:179], 0
	v_mfma_f32_16x16x32_bf16 v[78:81], v[142:145], v[184:187], 0
	v_mfma_f32_16x16x32_bf16 v[74:77], v[152:155], v[184:187], 0
	v_mfma_f32_16x16x32_bf16 v[126:129], v[146:149], v[164:167], v[126:129]
	v_mfma_f32_16x16x32_bf16 v[122:125], v[156:159], v[164:167], v[122:125]
	v_mfma_f32_16x16x32_bf16 v[110:113], v[146:149], v[172:175], v[110:113]
	v_mfma_f32_16x16x32_bf16 v[106:109], v[156:159], v[172:175], v[106:109]
	v_mfma_f32_16x16x32_bf16 v[94:97], v[146:149], v[180:183], v[94:97]
	v_mfma_f32_16x16x32_bf16 v[90:93], v[156:159], v[180:183], v[90:93]
	v_mfma_f32_16x16x32_bf16 v[78:81], v[146:149], v[190:193], v[78:81]
	v_mfma_f32_16x16x32_bf16 v[74:77], v[156:159], v[190:193], v[74:77]
	s_barrier
	s_add_i32 m0, s22, 0x10000
	ds_read_b128 v[194:197], v189 offset:16384
	ds_read_b128 v[198:201], v189 offset:17408
	ds_read_b128 v[202:205], v189 offset:18432
	global_load_lds_dwordx4 v134, s[12:13]
	s_add_i32 m0, s22, 0x12000
	ds_read_b128 v[206:209], v189 offset:19456
	global_load_lds_dwordx4 v130, s[12:13]
	s_barrier
	s_waitcnt lgkmcnt(0)
	v_mfma_f32_16x16x32_bf16 v[118:121], v[194:197], v[160:163], 0
	v_mfma_f32_16x16x32_bf16 v[114:117], v[202:205], v[160:163], 0
	v_mfma_f32_16x16x32_bf16 v[102:105], v[194:197], v[168:171], 0
	v_mfma_f32_16x16x32_bf16 v[98:101], v[202:205], v[168:171], 0
	v_mfma_f32_16x16x32_bf16 v[86:89], v[194:197], v[176:179], 0
	v_mfma_f32_16x16x32_bf16 v[82:85], v[202:205], v[176:179], 0
	v_mfma_f32_16x16x32_bf16 v[70:73], v[194:197], v[184:187], 0
	v_mfma_f32_16x16x32_bf16 v[66:69], v[202:205], v[184:187], 0
	v_mfma_f32_16x16x32_bf16 v[118:121], v[198:201], v[164:167], v[118:121]
	v_mfma_f32_16x16x32_bf16 v[114:117], v[206:209], v[164:167], v[114:117]
	v_mfma_f32_16x16x32_bf16 v[102:105], v[198:201], v[172:175], v[102:105]
	v_mfma_f32_16x16x32_bf16 v[98:101], v[206:209], v[172:175], v[98:101]
	v_mfma_f32_16x16x32_bf16 v[86:89], v[198:201], v[180:183], v[86:89]
	v_mfma_f32_16x16x32_bf16 v[82:85], v[206:209], v[180:183], v[82:85]
	v_mfma_f32_16x16x32_bf16 v[70:73], v[198:201], v[190:193], v[70:73]
	v_mfma_f32_16x16x32_bf16 v[66:69], v[206:209], v[190:193], v[66:69]
	s_mov_b32 m0, s7
	s_mov_b64 s[100:101], s[14:15]
	s_barrier
	ds_read_b128 v[160:163], v151 offset:16384
	ds_read_b128 v[164:167], v151 offset:17408
	ds_read_b128 v[168:171], v151 offset:18432
	ds_read_b128 v[172:175], v151 offset:19456
	ds_read_b128 v[176:179], v151 offset:20480
	ds_read_b128 v[180:183], v151 offset:21504
	ds_read_b128 v[184:187], v151 offset:22528
	global_load_lds_dwordx4 v136, s[100:101]
	s_mov_b32 m0, s23
	ds_read_b128 v[190:193], v151 offset:23552
	global_load_lds_dwordx4 v132, s[100:101]
	s_waitcnt vmcnt(10)
	s_barrier
	s_waitcnt lgkmcnt(0)
	v_mfma_f32_16x16x32_bf16 v[62:65], v[142:145], v[160:163], 0
	v_mfma_f32_16x16x32_bf16 v[58:61], v[152:155], v[160:163], 0
	v_mfma_f32_16x16x32_bf16 v[46:49], v[142:145], v[168:171], 0
	v_mfma_f32_16x16x32_bf16 v[42:45], v[152:155], v[168:171], 0
	v_mfma_f32_16x16x32_bf16 v[30:33], v[142:145], v[176:179], 0
	v_mfma_f32_16x16x32_bf16 v[26:29], v[152:155], v[176:179], 0
	v_mfma_f32_16x16x32_bf16 v[14:17], v[142:145], v[184:187], 0
	v_mfma_f32_16x16x32_bf16 v[10:13], v[152:155], v[184:187], 0
	v_mfma_f32_16x16x32_bf16 v[62:65], v[146:149], v[164:167], v[62:65]
	v_mfma_f32_16x16x32_bf16 v[58:61], v[156:159], v[164:167], v[58:61]
	v_mfma_f32_16x16x32_bf16 v[46:49], v[146:149], v[172:175], v[46:49]
	v_mfma_f32_16x16x32_bf16 v[42:45], v[156:159], v[172:175], v[42:45]
	v_mfma_f32_16x16x32_bf16 v[30:33], v[146:149], v[180:183], v[30:33]
	v_mfma_f32_16x16x32_bf16 v[26:29], v[156:159], v[180:183], v[26:29]
	v_mfma_f32_16x16x32_bf16 v[14:17], v[146:149], v[190:193], v[14:17]
	v_mfma_f32_16x16x32_bf16 v[10:13], v[156:159], v[190:193], v[10:13]
	s_barrier
	s_add_u32 s86, s12, 0x40000
	s_addc_u32 s87, s13, 0
	s_add_i32 m0, s22, 0x14000
	s_nop 0
	global_load_lds_dwordx4 v134, s[86:87]
	s_add_i32 m0, s22, 0x16000
	s_nop 0
	global_load_lds_dwordx4 v130, s[86:87]
	ds_read_b128 v[142:145], v189 offset:32768
	ds_read_b128 v[146:149], v189 offset:33792
	ds_read_b128 v[152:155], v189 offset:34816
	ds_read_b128 v[156:159], v189 offset:35840
	s_waitcnt vmcnt(6)
	s_barrier
	v_mfma_f32_16x16x32_bf16 v[54:57], v[194:197], v[160:163], 0
	v_mfma_f32_16x16x32_bf16 v[50:53], v[202:205], v[160:163], 0
	v_mfma_f32_16x16x32_bf16 v[38:41], v[194:197], v[168:171], 0
	v_mfma_f32_16x16x32_bf16 v[34:37], v[202:205], v[168:171], 0
	v_mfma_f32_16x16x32_bf16 v[22:25], v[194:197], v[176:179], 0
	v_mfma_f32_16x16x32_bf16 v[18:21], v[202:205], v[176:179], 0
	v_mfma_f32_16x16x32_bf16 v[6:9], v[194:197], v[184:187], 0
	v_mfma_f32_16x16x32_bf16 v[2:5], v[202:205], v[184:187], 0
	v_mfma_f32_16x16x32_bf16 v[54:57], v[198:201], v[164:167], v[54:57]
	v_mfma_f32_16x16x32_bf16 v[50:53], v[206:209], v[164:167], v[50:53]
	v_mfma_f32_16x16x32_bf16 v[38:41], v[198:201], v[172:175], v[38:41]
	v_mfma_f32_16x16x32_bf16 v[34:37], v[206:209], v[172:175], v[34:37]
	v_mfma_f32_16x16x32_bf16 v[22:25], v[198:201], v[180:183], v[22:25]
	v_mfma_f32_16x16x32_bf16 v[18:21], v[206:209], v[180:183], v[18:21]
	v_mfma_f32_16x16x32_bf16 v[6:9], v[198:201], v[190:193], v[6:9]
	v_mfma_f32_16x16x32_bf16 v[2:5], v[206:209], v[190:193], v[2:5]
	s_barrier
	s_add_u32 s14, s14, 0x40000
	s_addc_u32 s15, s15, 0
	s_mov_b32 m0, s28
	ds_read_b128 v[160:163], v151 offset:32768
	ds_read_b128 v[164:167], v151 offset:33792
	ds_read_b128 v[168:171], v151 offset:34816
	ds_read_b128 v[172:175], v151 offset:35840
	ds_read_b128 v[176:179], v151 offset:36864
	ds_read_b128 v[180:183], v151 offset:37888
	ds_read_b128 v[184:187], v151 offset:38912
	global_load_lds_dwordx4 v136, s[14:15]
	s_mov_b32 m0, s29
	ds_read_b128 v[190:193], v151 offset:39936
	global_load_lds_dwordx4 v132, s[14:15]
	s_waitcnt lgkmcnt(8)
	s_barrier
	s_waitcnt lgkmcnt(0)
	v_mfma_f32_16x16x32_bf16 v[126:129], v[142:145], v[160:163], v[126:129]
	v_mfma_f32_16x16x32_bf16 v[122:125], v[152:155], v[160:163], v[122:125]
	v_mfma_f32_16x16x32_bf16 v[110:113], v[142:145], v[168:171], v[110:113]
	v_mfma_f32_16x16x32_bf16 v[106:109], v[152:155], v[168:171], v[106:109]
	v_mfma_f32_16x16x32_bf16 v[94:97], v[142:145], v[176:179], v[94:97]
	v_mfma_f32_16x16x32_bf16 v[90:93], v[152:155], v[176:179], v[90:93]
	v_mfma_f32_16x16x32_bf16 v[78:81], v[142:145], v[184:187], v[78:81]
	v_mfma_f32_16x16x32_bf16 v[74:77], v[152:155], v[184:187], v[74:77]
	v_mfma_f32_16x16x32_bf16 v[126:129], v[146:149], v[164:167], v[126:129]
	v_mfma_f32_16x16x32_bf16 v[122:125], v[156:159], v[164:167], v[122:125]
	v_mfma_f32_16x16x32_bf16 v[110:113], v[146:149], v[172:175], v[110:113]
	v_mfma_f32_16x16x32_bf16 v[106:109], v[156:159], v[172:175], v[106:109]
	v_mfma_f32_16x16x32_bf16 v[94:97], v[146:149], v[180:183], v[94:97]
	v_mfma_f32_16x16x32_bf16 v[90:93], v[156:159], v[180:183], v[90:93]
	v_mfma_f32_16x16x32_bf16 v[78:81], v[146:149], v[190:193], v[78:81]
	v_mfma_f32_16x16x32_bf16 v[74:77], v[156:159], v[190:193], v[74:77]
	s_barrier
	s_add_i32 m0, s22, 0x18000
	ds_read_b128 v[194:197], v189 offset:49152
	ds_read_b128 v[198:201], v189 offset:50176
	ds_read_b128 v[202:205], v189 offset:51200
	ds_read_b128 v[206:209], v189 offset:52224
	s_add_u32 s98, s12, s40
	s_addc_u32 s99, s13, s41
	global_load_lds_dwordx4 v134, s[98:99]
	s_add_i32 m0, s22, 0x1a000
	s_nop 0
	global_load_lds_dwordx4 v130, s[98:99]
	s_barrier
	s_waitcnt lgkmcnt(0)
	v_mfma_f32_16x16x32_bf16 v[118:121], v[194:197], v[160:163], v[118:121]
	v_mfma_f32_16x16x32_bf16 v[114:117], v[202:205], v[160:163], v[114:117]
	v_mfma_f32_16x16x32_bf16 v[102:105], v[194:197], v[168:171], v[102:105]
	v_mfma_f32_16x16x32_bf16 v[98:101], v[202:205], v[168:171], v[98:101]
	v_mfma_f32_16x16x32_bf16 v[86:89], v[194:197], v[176:179], v[86:89]
	v_mfma_f32_16x16x32_bf16 v[82:85], v[202:205], v[176:179], v[82:85]
	v_mfma_f32_16x16x32_bf16 v[70:73], v[194:197], v[184:187], v[70:73]
	v_mfma_f32_16x16x32_bf16 v[66:69], v[202:205], v[184:187], v[66:69]
	v_mfma_f32_16x16x32_bf16 v[118:121], v[198:201], v[164:167], v[118:121]
	v_mfma_f32_16x16x32_bf16 v[114:117], v[206:209], v[164:167], v[114:117]
	v_mfma_f32_16x16x32_bf16 v[102:105], v[198:201], v[172:175], v[102:105]
	v_mfma_f32_16x16x32_bf16 v[98:101], v[206:209], v[172:175], v[98:101]
	v_mfma_f32_16x16x32_bf16 v[86:89], v[198:201], v[180:183], v[86:89]
	v_mfma_f32_16x16x32_bf16 v[82:85], v[206:209], v[180:183], v[82:85]
	v_mfma_f32_16x16x32_bf16 v[70:73], v[198:201], v[190:193], v[70:73]
	v_mfma_f32_16x16x32_bf16 v[66:69], v[206:209], v[190:193], v[66:69]
	s_mov_b32 m0, s38
	s_barrier
	ds_read_b128 v[160:163], v151 offset:49152
	ds_read_b128 v[164:167], v151 offset:50176
	ds_read_b128 v[168:171], v151 offset:51200
	ds_read_b128 v[172:175], v151 offset:52224
	ds_read_b128 v[176:179], v151 offset:53248
	ds_read_b128 v[180:183], v151 offset:54272
	ds_read_b128 v[184:187], v151 offset:55296
	ds_read_b128 v[190:193], v151 offset:56320
	s_add_u32 s98, s100, s40
	s_addc_u32 s99, s101, s41
	global_load_lds_dwordx4 v136, s[98:99]
	s_mov_b32 m0, s39
	s_nop 0
	global_load_lds_dwordx4 v132, s[98:99]
	s_waitcnt vmcnt(10)
	s_barrier
	s_waitcnt lgkmcnt(0)
	v_mfma_f32_16x16x32_bf16 v[62:65], v[142:145], v[160:163], v[62:65]
	v_mfma_f32_16x16x32_bf16 v[58:61], v[152:155], v[160:163], v[58:61]
	v_mfma_f32_16x16x32_bf16 v[46:49], v[142:145], v[168:171], v[46:49]
	v_mfma_f32_16x16x32_bf16 v[42:45], v[152:155], v[168:171], v[42:45]
	v_mfma_f32_16x16x32_bf16 v[30:33], v[142:145], v[176:179], v[30:33]
	v_mfma_f32_16x16x32_bf16 v[26:29], v[152:155], v[176:179], v[26:29]
	v_mfma_f32_16x16x32_bf16 v[14:17], v[142:145], v[184:187], v[14:17]
	v_mfma_f32_16x16x32_bf16 v[10:13], v[152:155], v[184:187], v[10:13]
	v_mfma_f32_16x16x32_bf16 v[62:65], v[146:149], v[164:167], v[62:65]
	v_mfma_f32_16x16x32_bf16 v[58:61], v[156:159], v[164:167], v[58:61]
	v_mfma_f32_16x16x32_bf16 v[46:49], v[146:149], v[172:175], v[46:49]
	v_mfma_f32_16x16x32_bf16 v[42:45], v[156:159], v[172:175], v[42:45]
	v_mfma_f32_16x16x32_bf16 v[30:33], v[146:149], v[180:183], v[30:33]
	v_mfma_f32_16x16x32_bf16 v[26:29], v[156:159], v[180:183], v[26:29]
	v_mfma_f32_16x16x32_bf16 v[14:17], v[146:149], v[190:193], v[14:17]
	v_mfma_f32_16x16x32_bf16 v[10:13], v[156:159], v[190:193], v[10:13]
	s_barrier
	s_add_u32 s12, s12, 0x40080
	s_addc_u32 s13, s13, 0
	s_add_i32 m0, s22, 0x1c000
	s_nop 0
	global_load_lds_dwordx4 v134, s[12:13]
	s_add_i32 m0, s22, 0x1e000
	s_nop 0
	global_load_lds_dwordx4 v130, s[12:13]
	ds_read_b128 v[142:145], v189
	ds_read_b128 v[146:149], v189 offset:1024
	ds_read_b128 v[152:155], v189 offset:2048
	ds_read_b128 v[156:159], v189 offset:3072
	s_waitcnt vmcnt(6)
	s_barrier
	v_mfma_f32_16x16x32_bf16 v[54:57], v[194:197], v[160:163], v[54:57]
	v_mfma_f32_16x16x32_bf16 v[50:53], v[202:205], v[160:163], v[50:53]
	v_mfma_f32_16x16x32_bf16 v[38:41], v[194:197], v[168:171], v[38:41]
	v_mfma_f32_16x16x32_bf16 v[34:37], v[202:205], v[168:171], v[34:37]
	v_mfma_f32_16x16x32_bf16 v[22:25], v[194:197], v[176:179], v[22:25]
	v_mfma_f32_16x16x32_bf16 v[18:21], v[202:205], v[176:179], v[18:21]
	v_mfma_f32_16x16x32_bf16 v[6:9], v[194:197], v[184:187], v[6:9]
	v_mfma_f32_16x16x32_bf16 v[2:5], v[202:205], v[184:187], v[2:5]
	v_mfma_f32_16x16x32_bf16 v[54:57], v[198:201], v[164:167], v[54:57]
	s_add_i32 s85, s85, 2
	s_add_u32 s4, s4, 0x100
	v_mfma_f32_16x16x32_bf16 v[50:53], v[206:209], v[164:167], v[50:53]
	s_addc_u32 s5, s5, 0
	s_add_u32 s78, s78, 0x100
	v_mfma_f32_16x16x32_bf16 v[38:41], v[198:201], v[172:175], v[38:41]
	s_addc_u32 s79, s79, 0
	s_add_u32 s12, s4, 0xfffc0080
	v_mfma_f32_16x16x32_bf16 v[34:37], v[206:209], v[172:175], v[34:37]
	s_addc_u32 s13, s5, -1
	s_cmp_eq_u32 s85, 12
	v_mfma_f32_16x16x32_bf16 v[22:25], v[198:201], v[180:183], v[22:25]
	s_cselect_b32 s15, s44, s13
	s_cselect_b32 s14, s45, s12
	v_mfma_f32_16x16x32_bf16 v[18:21], v[206:209], v[180:183], v[18:21]
	s_cselect_b32 s13, s47, s79
	s_cselect_b32 s12, s55, s78
	v_mfma_f32_16x16x32_bf16 v[6:9], v[198:201], v[190:193], v[6:9]
	s_cmp_gt_u32 s85, 13
	v_mfma_f32_16x16x32_bf16 v[2:5], v[206:209], v[190:193], v[2:5]
	s_barrier
	.p2align 3
.LBB0_267:
	s_add_i32 m0, s7, 0xc000
	ds_read_b128 v[160:163], v151
	ds_read_b128 v[164:167], v151 offset:1024
	ds_read_b128 v[168:171], v151 offset:2048
	ds_read_b128 v[172:175], v151 offset:3072
	ds_read_b128 v[176:179], v151 offset:4096
	ds_read_b128 v[180:183], v151 offset:5120
	ds_read_b128 v[184:187], v151 offset:6144
	global_load_lds_dwordx4 v138, s[4:5]
	s_add_i32 m0, s7, 0xe000
	ds_read_b128 v[190:193], v151 offset:7168
	global_load_lds_dwordx4 v140, s[4:5]
	s_waitcnt lgkmcnt(8)
	s_barrier
	s_waitcnt lgkmcnt(0)
	v_mfma_f32_16x16x32_bf16 v[126:129], v[142:145], v[160:163], v[126:129]
	v_mfma_f32_16x16x32_bf16 v[122:125], v[152:155], v[160:163], v[122:125]
	v_mfma_f32_16x16x32_bf16 v[110:113], v[142:145], v[168:171], v[110:113]
	v_mfma_f32_16x16x32_bf16 v[106:109], v[152:155], v[168:171], v[106:109]
	v_mfma_f32_16x16x32_bf16 v[94:97], v[142:145], v[176:179], v[94:97]
	v_mfma_f32_16x16x32_bf16 v[90:93], v[152:155], v[176:179], v[90:93]
	v_mfma_f32_16x16x32_bf16 v[78:81], v[142:145], v[184:187], v[78:81]
	v_mfma_f32_16x16x32_bf16 v[74:77], v[152:155], v[184:187], v[74:77]
	v_mfma_f32_16x16x32_bf16 v[126:129], v[146:149], v[164:167], v[126:129]
	v_mfma_f32_16x16x32_bf16 v[122:125], v[156:159], v[164:167], v[122:125]
	v_mfma_f32_16x16x32_bf16 v[110:113], v[146:149], v[172:175], v[110:113]
	v_mfma_f32_16x16x32_bf16 v[106:109], v[156:159], v[172:175], v[106:109]
	v_mfma_f32_16x16x32_bf16 v[94:97], v[146:149], v[180:183], v[94:97]
	v_mfma_f32_16x16x32_bf16 v[90:93], v[156:159], v[180:183], v[90:93]
	v_mfma_f32_16x16x32_bf16 v[78:81], v[146:149], v[190:193], v[78:81]
	v_mfma_f32_16x16x32_bf16 v[74:77], v[156:159], v[190:193], v[74:77]
	s_barrier
	s_add_i32 m0, s22, 0x10000
	ds_read_b128 v[194:197], v189 offset:16384
	ds_read_b128 v[198:201], v189 offset:17408
	ds_read_b128 v[202:205], v189 offset:18432
	global_load_lds_dwordx4 v134, s[12:13]
	s_add_i32 m0, s22, 0x12000
	ds_read_b128 v[206:209], v189 offset:19456
	global_load_lds_dwordx4 v130, s[12:13]
	s_barrier
	s_waitcnt lgkmcnt(0)
	v_mfma_f32_16x16x32_bf16 v[118:121], v[194:197], v[160:163], v[118:121]
	v_mfma_f32_16x16x32_bf16 v[114:117], v[202:205], v[160:163], v[114:117]
	v_mfma_f32_16x16x32_bf16 v[102:105], v[194:197], v[168:171], v[102:105]
	v_mfma_f32_16x16x32_bf16 v[98:101], v[202:205], v[168:171], v[98:101]
	v_mfma_f32_16x16x32_bf16 v[86:89], v[194:197], v[176:179], v[86:89]
	v_mfma_f32_16x16x32_bf16 v[82:85], v[202:205], v[176:179], v[82:85]
	v_mfma_f32_16x16x32_bf16 v[70:73], v[194:197], v[184:187], v[70:73]
	v_mfma_f32_16x16x32_bf16 v[66:69], v[202:205], v[184:187], v[66:69]
	v_mfma_f32_16x16x32_bf16 v[118:121], v[198:201], v[164:167], v[118:121]
	v_mfma_f32_16x16x32_bf16 v[114:117], v[206:209], v[164:167], v[114:117]
	v_mfma_f32_16x16x32_bf16 v[102:105], v[198:201], v[172:175], v[102:105]
	v_mfma_f32_16x16x32_bf16 v[98:101], v[206:209], v[172:175], v[98:101]
	v_mfma_f32_16x16x32_bf16 v[86:89], v[198:201], v[180:183], v[86:89]
	v_mfma_f32_16x16x32_bf16 v[82:85], v[206:209], v[180:183], v[82:85]
	v_mfma_f32_16x16x32_bf16 v[70:73], v[198:201], v[190:193], v[70:73]
	v_mfma_f32_16x16x32_bf16 v[66:69], v[206:209], v[190:193], v[66:69]
	s_mov_b32 m0, s7
	s_mov_b64 s[100:101], s[14:15]
	s_barrier
	ds_read_b128 v[160:163], v151 offset:16384
	ds_read_b128 v[164:167], v151 offset:17408
	ds_read_b128 v[168:171], v151 offset:18432
	ds_read_b128 v[172:175], v151 offset:19456
	ds_read_b128 v[176:179], v151 offset:20480
	ds_read_b128 v[180:183], v151 offset:21504
	ds_read_b128 v[184:187], v151 offset:22528
	global_load_lds_dwordx4 v136, s[100:101]
	s_mov_b32 m0, s23
	ds_read_b128 v[190:193], v151 offset:23552
	global_load_lds_dwordx4 v132, s[100:101]
	s_waitcnt vmcnt(10)
	s_barrier
	s_waitcnt lgkmcnt(0)
	v_mfma_f32_16x16x32_bf16 v[62:65], v[142:145], v[160:163], v[62:65]
	v_mfma_f32_16x16x32_bf16 v[58:61], v[152:155], v[160:163], v[58:61]
	v_mfma_f32_16x16x32_bf16 v[46:49], v[142:145], v[168:171], v[46:49]
	v_mfma_f32_16x16x32_bf16 v[42:45], v[152:155], v[168:171], v[42:45]
	v_mfma_f32_16x16x32_bf16 v[30:33], v[142:145], v[176:179], v[30:33]
	v_mfma_f32_16x16x32_bf16 v[26:29], v[152:155], v[176:179], v[26:29]
	v_mfma_f32_16x16x32_bf16 v[14:17], v[142:145], v[184:187], v[14:17]
	v_mfma_f32_16x16x32_bf16 v[10:13], v[152:155], v[184:187], v[10:13]
	v_mfma_f32_16x16x32_bf16 v[62:65], v[146:149], v[164:167], v[62:65]
	v_mfma_f32_16x16x32_bf16 v[58:61], v[156:159], v[164:167], v[58:61]
	v_mfma_f32_16x16x32_bf16 v[46:49], v[146:149], v[172:175], v[46:49]
	v_mfma_f32_16x16x32_bf16 v[42:45], v[156:159], v[172:175], v[42:45]
	v_mfma_f32_16x16x32_bf16 v[30:33], v[146:149], v[180:183], v[30:33]
	v_mfma_f32_16x16x32_bf16 v[26:29], v[156:159], v[180:183], v[26:29]
	v_mfma_f32_16x16x32_bf16 v[14:17], v[146:149], v[190:193], v[14:17]
	v_mfma_f32_16x16x32_bf16 v[10:13], v[156:159], v[190:193], v[10:13]
	s_barrier
	s_add_u32 s86, s12, 0x40000
	s_addc_u32 s87, s13, 0
	s_add_i32 m0, s22, 0x14000
	s_nop 0
	global_load_lds_dwordx4 v134, s[86:87]
	s_add_i32 m0, s22, 0x16000
	s_nop 0
	global_load_lds_dwordx4 v130, s[86:87]
	ds_read_b128 v[142:145], v189 offset:32768
	ds_read_b128 v[146:149], v189 offset:33792
	ds_read_b128 v[152:155], v189 offset:34816
	ds_read_b128 v[156:159], v189 offset:35840
	s_waitcnt vmcnt(6)
	s_barrier
	v_mfma_f32_16x16x32_bf16 v[54:57], v[194:197], v[160:163], v[54:57]
	v_mfma_f32_16x16x32_bf16 v[50:53], v[202:205], v[160:163], v[50:53]
	v_mfma_f32_16x16x32_bf16 v[38:41], v[194:197], v[168:171], v[38:41]
	v_mfma_f32_16x16x32_bf16 v[34:37], v[202:205], v[168:171], v[34:37]
	v_mfma_f32_16x16x32_bf16 v[22:25], v[194:197], v[176:179], v[22:25]
	v_mfma_f32_16x16x32_bf16 v[18:21], v[202:205], v[176:179], v[18:21]
	v_mfma_f32_16x16x32_bf16 v[6:9], v[194:197], v[184:187], v[6:9]
	v_mfma_f32_16x16x32_bf16 v[2:5], v[202:205], v[184:187], v[2:5]
	v_mfma_f32_16x16x32_bf16 v[54:57], v[198:201], v[164:167], v[54:57]
	v_mfma_f32_16x16x32_bf16 v[50:53], v[206:209], v[164:167], v[50:53]
	v_mfma_f32_16x16x32_bf16 v[38:41], v[198:201], v[172:175], v[38:41]
	v_mfma_f32_16x16x32_bf16 v[34:37], v[206:209], v[172:175], v[34:37]
	v_mfma_f32_16x16x32_bf16 v[22:25], v[198:201], v[180:183], v[22:25]
	v_mfma_f32_16x16x32_bf16 v[18:21], v[206:209], v[180:183], v[18:21]
	v_mfma_f32_16x16x32_bf16 v[6:9], v[198:201], v[190:193], v[6:9]
	v_mfma_f32_16x16x32_bf16 v[2:5], v[206:209], v[190:193], v[2:5]
	s_barrier
	s_add_u32 s14, s14, 0x40000
	s_addc_u32 s15, s15, 0
	s_mov_b32 m0, s28
	ds_read_b128 v[160:163], v151 offset:32768
	ds_read_b128 v[164:167], v151 offset:33792
	ds_read_b128 v[168:171], v151 offset:34816
	ds_read_b128 v[172:175], v151 offset:35840
	ds_read_b128 v[176:179], v151 offset:36864
	ds_read_b128 v[180:183], v151 offset:37888
	ds_read_b128 v[184:187], v151 offset:38912
	global_load_lds_dwordx4 v136, s[14:15]
	s_mov_b32 m0, s29
	ds_read_b128 v[190:193], v151 offset:39936
	global_load_lds_dwordx4 v132, s[14:15]
	s_waitcnt lgkmcnt(8)
	s_barrier
	s_waitcnt lgkmcnt(0)
	v_mfma_f32_16x16x32_bf16 v[126:129], v[142:145], v[160:163], v[126:129]
	v_mfma_f32_16x16x32_bf16 v[122:125], v[152:155], v[160:163], v[122:125]
	v_mfma_f32_16x16x32_bf16 v[110:113], v[142:145], v[168:171], v[110:113]
	v_mfma_f32_16x16x32_bf16 v[106:109], v[152:155], v[168:171], v[106:109]
	v_mfma_f32_16x16x32_bf16 v[94:97], v[142:145], v[176:179], v[94:97]
	v_mfma_f32_16x16x32_bf16 v[90:93], v[152:155], v[176:179], v[90:93]
	v_mfma_f32_16x16x32_bf16 v[78:81], v[142:145], v[184:187], v[78:81]
	v_mfma_f32_16x16x32_bf16 v[74:77], v[152:155], v[184:187], v[74:77]
	v_mfma_f32_16x16x32_bf16 v[126:129], v[146:149], v[164:167], v[126:129]
	v_mfma_f32_16x16x32_bf16 v[122:125], v[156:159], v[164:167], v[122:125]
	v_mfma_f32_16x16x32_bf16 v[110:113], v[146:149], v[172:175], v[110:113]
	v_mfma_f32_16x16x32_bf16 v[106:109], v[156:159], v[172:175], v[106:109]
	v_mfma_f32_16x16x32_bf16 v[94:97], v[146:149], v[180:183], v[94:97]
	v_mfma_f32_16x16x32_bf16 v[90:93], v[156:159], v[180:183], v[90:93]
	v_mfma_f32_16x16x32_bf16 v[78:81], v[146:149], v[190:193], v[78:81]
	v_mfma_f32_16x16x32_bf16 v[74:77], v[156:159], v[190:193], v[74:77]
	s_barrier
	s_add_i32 m0, s22, 0x18000
	ds_read_b128 v[194:197], v189 offset:49152
	ds_read_b128 v[198:201], v189 offset:50176
	ds_read_b128 v[202:205], v189 offset:51200
	ds_read_b128 v[206:209], v189 offset:52224
	s_add_u32 s98, s12, s40
	s_addc_u32 s99, s13, s41
	global_load_lds_dwordx4 v134, s[98:99]
	s_add_i32 m0, s22, 0x1a000
	s_nop 0
	global_load_lds_dwordx4 v130, s[98:99]
	s_barrier
	s_waitcnt lgkmcnt(0)
	v_mfma_f32_16x16x32_bf16 v[118:121], v[194:197], v[160:163], v[118:121]
	v_mfma_f32_16x16x32_bf16 v[114:117], v[202:205], v[160:163], v[114:117]
	v_mfma_f32_16x16x32_bf16 v[102:105], v[194:197], v[168:171], v[102:105]
	v_mfma_f32_16x16x32_bf16 v[98:101], v[202:205], v[168:171], v[98:101]
	v_mfma_f32_16x16x32_bf16 v[86:89], v[194:197], v[176:179], v[86:89]
	v_mfma_f32_16x16x32_bf16 v[82:85], v[202:205], v[176:179], v[82:85]
	v_mfma_f32_16x16x32_bf16 v[70:73], v[194:197], v[184:187], v[70:73]
	v_mfma_f32_16x16x32_bf16 v[66:69], v[202:205], v[184:187], v[66:69]
	v_mfma_f32_16x16x32_bf16 v[118:121], v[198:201], v[164:167], v[118:121]
	v_mfma_f32_16x16x32_bf16 v[114:117], v[206:209], v[164:167], v[114:117]
	v_mfma_f32_16x16x32_bf16 v[102:105], v[198:201], v[172:175], v[102:105]
	v_mfma_f32_16x16x32_bf16 v[98:101], v[206:209], v[172:175], v[98:101]
	v_mfma_f32_16x16x32_bf16 v[86:89], v[198:201], v[180:183], v[86:89]
	v_mfma_f32_16x16x32_bf16 v[82:85], v[206:209], v[180:183], v[82:85]
	v_mfma_f32_16x16x32_bf16 v[70:73], v[198:201], v[190:193], v[70:73]
	v_mfma_f32_16x16x32_bf16 v[66:69], v[206:209], v[190:193], v[66:69]
	s_mov_b32 m0, s38
	s_barrier
	ds_read_b128 v[160:163], v151 offset:49152
	ds_read_b128 v[164:167], v151 offset:50176
	ds_read_b128 v[168:171], v151 offset:51200
	ds_read_b128 v[172:175], v151 offset:52224
	ds_read_b128 v[176:179], v151 offset:53248
	ds_read_b128 v[180:183], v151 offset:54272
	ds_read_b128 v[184:187], v151 offset:55296
	ds_read_b128 v[190:193], v151 offset:56320
	s_add_u32 s98, s100, s40
	s_addc_u32 s99, s101, s41
	global_load_lds_dwordx4 v136, s[98:99]
	s_mov_b32 m0, s39
	s_nop 0
	global_load_lds_dwordx4 v132, s[98:99]
	s_waitcnt vmcnt(10)
	s_barrier
	s_waitcnt lgkmcnt(0)
	v_mfma_f32_16x16x32_bf16 v[62:65], v[142:145], v[160:163], v[62:65]
	v_mfma_f32_16x16x32_bf16 v[58:61], v[152:155], v[160:163], v[58:61]
	v_mfma_f32_16x16x32_bf16 v[46:49], v[142:145], v[168:171], v[46:49]
	v_mfma_f32_16x16x32_bf16 v[42:45], v[152:155], v[168:171], v[42:45]
	v_mfma_f32_16x16x32_bf16 v[30:33], v[142:145], v[176:179], v[30:33]
	v_mfma_f32_16x16x32_bf16 v[26:29], v[152:155], v[176:179], v[26:29]
	v_mfma_f32_16x16x32_bf16 v[14:17], v[142:145], v[184:187], v[14:17]
	v_mfma_f32_16x16x32_bf16 v[10:13], v[152:155], v[184:187], v[10:13]
	v_mfma_f32_16x16x32_bf16 v[62:65], v[146:149], v[164:167], v[62:65]
	v_mfma_f32_16x16x32_bf16 v[58:61], v[156:159], v[164:167], v[58:61]
	v_mfma_f32_16x16x32_bf16 v[46:49], v[146:149], v[172:175], v[46:49]
	v_mfma_f32_16x16x32_bf16 v[42:45], v[156:159], v[172:175], v[42:45]
	v_mfma_f32_16x16x32_bf16 v[30:33], v[146:149], v[180:183], v[30:33]
	v_mfma_f32_16x16x32_bf16 v[26:29], v[156:159], v[180:183], v[26:29]
	v_mfma_f32_16x16x32_bf16 v[14:17], v[146:149], v[190:193], v[14:17]
	v_mfma_f32_16x16x32_bf16 v[10:13], v[156:159], v[190:193], v[10:13]
	s_barrier
	s_add_u32 s12, s12, 0x40080
	s_addc_u32 s13, s13, 0
	s_add_i32 m0, s22, 0x1c000
	s_nop 0
	global_load_lds_dwordx4 v134, s[12:13]
	s_add_i32 m0, s22, 0x1e000
	s_nop 0
	global_load_lds_dwordx4 v130, s[12:13]
	ds_read_b128 v[142:145], v189
	ds_read_b128 v[146:149], v189 offset:1024
	ds_read_b128 v[152:155], v189 offset:2048
	ds_read_b128 v[156:159], v189 offset:3072
	s_waitcnt vmcnt(6)
	s_barrier
	v_mfma_f32_16x16x32_bf16 v[54:57], v[194:197], v[160:163], v[54:57]
	v_mfma_f32_16x16x32_bf16 v[50:53], v[202:205], v[160:163], v[50:53]
	v_mfma_f32_16x16x32_bf16 v[38:41], v[194:197], v[168:171], v[38:41]
	v_mfma_f32_16x16x32_bf16 v[34:37], v[202:205], v[168:171], v[34:37]
	v_mfma_f32_16x16x32_bf16 v[22:25], v[194:197], v[176:179], v[22:25]
	v_mfma_f32_16x16x32_bf16 v[18:21], v[202:205], v[176:179], v[18:21]
	v_mfma_f32_16x16x32_bf16 v[6:9], v[194:197], v[184:187], v[6:9]
	v_mfma_f32_16x16x32_bf16 v[2:5], v[202:205], v[184:187], v[2:5]
	v_mfma_f32_16x16x32_bf16 v[54:57], v[198:201], v[164:167], v[54:57]
	s_add_i32 s85, s85, 2
	s_add_u32 s4, s4, 0x100
	v_mfma_f32_16x16x32_bf16 v[50:53], v[206:209], v[164:167], v[50:53]
	s_addc_u32 s5, s5, 0
	s_add_u32 s78, s78, 0x100
	v_mfma_f32_16x16x32_bf16 v[38:41], v[198:201], v[172:175], v[38:41]
	s_addc_u32 s79, s79, 0
	s_add_u32 s12, s4, 0xfffc0080
	v_mfma_f32_16x16x32_bf16 v[34:37], v[206:209], v[172:175], v[34:37]
	s_addc_u32 s13, s5, -1
	s_cmp_eq_u32 s85, 12
	v_mfma_f32_16x16x32_bf16 v[22:25], v[198:201], v[180:183], v[22:25]
	s_cselect_b32 s15, s44, s13
	s_cselect_b32 s14, s45, s12
	v_mfma_f32_16x16x32_bf16 v[18:21], v[206:209], v[180:183], v[18:21]
	s_cselect_b32 s13, s47, s79
	s_cselect_b32 s12, s55, s78
	v_mfma_f32_16x16x32_bf16 v[6:9], v[198:201], v[190:193], v[6:9]
	s_cmp_gt_u32 s85, 13
	v_mfma_f32_16x16x32_bf16 v[2:5], v[206:209], v[190:193], v[2:5]
	s_barrier
	s_cbranch_scc0 .LBB0_267
	s_waitcnt lgkmcnt(0)
	v_mov_b32_e32 v156, v252
	s_mov_b64 s[4:5], -1
	v_and_b32_e32 v154, 63, v156
	s_andn2_b64 vcc, exec, s[2:3]
	v_lshlrev_b32_e32 v142, 2, v154
	s_cbranch_vccnz .LBB0_270
	v_lshlrev_b32_e32 v155, 2, v154
	s_mov_b64 s[4:5], 0

.LBB0_837:
	s_ashr_i32 s15, s14, 31
	s_lshl_b64 s[78:79], s[14:15], 19
	s_add_u32 s84, s36, s78
	s_addc_u32 s85, s37, s79
	s_and_b64 s[4:5], s[4:5], exec
	s_cselect_b32 s15, s85, s91
	s_cselect_b32 s23, s84, s90
	s_add_u32 s34, s90, 0x100
	s_addc_u32 s75, s91, 0
	s_mov_b32 s78, -2
	s_waitcnt lgkmcnt(0)
	s_add_i32 s79, 0, 0x10000
	v_add_u32_e32 v142, s79, v212
	v_add_u32_e32 v189, 0x10000, v212
	ds_read_b128 v[130:133], v142
	ds_read_b128 v[134:137], v142 offset:1024
	ds_read_b128 v[138:141], v142 offset:2048
	ds_read_b128 v[142:145], v142 offset:3072
	s_add_u32 s4, s88, 0x100
	s_addc_u32 s5, s89, 0
	s_cmp_eq_u32 s78, 12
	s_cselect_b32 s93, s17, s5
	s_cselect_b32 s92, s16, s4
	s_cselect_b32 s91, s15, s75
	s_cselect_b32 s90, s23, s34
	v_lshl_add_u64 v[178:179], s[88:89], 0, v[196:197]
	s_add_i32 m0, s39, 0xc000
	ds_read_b128 v[146:149], v213
	ds_read_b128 v[150:153], v213 offset:1024
	ds_read_b128 v[154:157], v213 offset:2048
	ds_read_b128 v[158:161], v213 offset:3072
	ds_read_b128 v[162:165], v213 offset:4096
	ds_read_b128 v[166:169], v213 offset:5120
	ds_read_b128 v[170:173], v213 offset:6144
	ds_read_b128 v[174:177], v213 offset:7168
	global_load_lds_dwordx4 v[178:179], off
	s_add_i32 m0, s39, 0xe000
	v_lshl_add_u64 v[178:179], s[88:89], 0, v[198:199]
	global_load_lds_dwordx4 v[178:179], off
	s_waitcnt lgkmcnt(8)
	s_barrier
	s_waitcnt lgkmcnt(0)
	v_mfma_f32_16x16x32_bf16 v[126:129], v[130:133], v[146:149], 0
	v_mfma_f32_16x16x32_bf16 v[122:125], v[138:141], v[146:149], 0
	v_mfma_f32_16x16x32_bf16 v[110:113], v[130:133], v[154:157], 0
	v_mfma_f32_16x16x32_bf16 v[106:109], v[138:141], v[154:157], 0
	v_mfma_f32_16x16x32_bf16 v[94:97], v[130:133], v[162:165], 0
	v_mfma_f32_16x16x32_bf16 v[90:93], v[138:141], v[162:165], 0
	v_mfma_f32_16x16x32_bf16 v[78:81], v[130:133], v[170:173], 0
	v_mfma_f32_16x16x32_bf16 v[74:77], v[138:141], v[170:173], 0
	v_mfma_f32_16x16x32_bf16 v[126:129], v[134:137], v[150:153], v[126:129]
	v_mfma_f32_16x16x32_bf16 v[122:125], v[142:145], v[150:153], v[122:125]
	v_mfma_f32_16x16x32_bf16 v[110:113], v[134:137], v[158:161], v[110:113]
	v_mfma_f32_16x16x32_bf16 v[106:109], v[142:145], v[158:161], v[106:109]
	v_mfma_f32_16x16x32_bf16 v[94:97], v[134:137], v[166:169], v[94:97]
	v_mfma_f32_16x16x32_bf16 v[90:93], v[142:145], v[166:169], v[90:93]
	v_mfma_f32_16x16x32_bf16 v[78:81], v[134:137], v[174:177], v[78:81]
	v_mfma_f32_16x16x32_bf16 v[74:77], v[142:145], v[174:177], v[74:77]
	s_barrier
	ds_read_b128 v[178:181], v189 offset:16384
	ds_read_b128 v[182:185], v189 offset:17408
	ds_read_b128 v[200:203], v189 offset:18432
	ds_read_b128 v[204:207], v189 offset:19456
	s_add_i32 m0, s38, 0x10000
	s_nop 0
	global_load_lds_dwordx4 v0, s[90:91]
	s_add_i32 m0, s38, 0x12000
	s_nop 0
	global_load_lds_dwordx4 v194, s[90:91]
	s_barrier
	s_waitcnt lgkmcnt(0)
	v_mfma_f32_16x16x32_bf16 v[118:121], v[178:181], v[146:149], 0
	v_mfma_f32_16x16x32_bf16 v[114:117], v[200:203], v[146:149], 0
	v_mfma_f32_16x16x32_bf16 v[102:105], v[178:181], v[154:157], 0
	v_mfma_f32_16x16x32_bf16 v[98:101], v[200:203], v[154:157], 0
	v_mfma_f32_16x16x32_bf16 v[86:89], v[178:181], v[162:165], 0
	v_mfma_f32_16x16x32_bf16 v[82:85], v[200:203], v[162:165], 0
	v_mfma_f32_16x16x32_bf16 v[70:73], v[178:181], v[170:173], 0
	v_mfma_f32_16x16x32_bf16 v[66:69], v[200:203], v[170:173], 0
	v_mfma_f32_16x16x32_bf16 v[118:121], v[182:185], v[150:153], v[118:121]
	v_mfma_f32_16x16x32_bf16 v[114:117], v[204:207], v[150:153], v[114:117]
	v_mfma_f32_16x16x32_bf16 v[102:105], v[182:185], v[158:161], v[102:105]
	v_mfma_f32_16x16x32_bf16 v[98:101], v[204:207], v[158:161], v[98:101]
	v_mfma_f32_16x16x32_bf16 v[86:89], v[182:185], v[166:169], v[86:89]
	v_mfma_f32_16x16x32_bf16 v[82:85], v[204:207], v[166:169], v[82:85]
	v_mfma_f32_16x16x32_bf16 v[70:73], v[182:185], v[174:177], v[70:73]
	v_mfma_f32_16x16x32_bf16 v[66:69], v[204:207], v[174:177], v[66:69]
	s_mov_b32 m0, s39
	s_barrier
	ds_read_b128 v[146:149], v213 offset:16384
	ds_read_b128 v[150:153], v213 offset:17408
	ds_read_b128 v[154:157], v213 offset:18432
	ds_read_b128 v[158:161], v213 offset:19456
	ds_read_b128 v[162:165], v213 offset:20480
	ds_read_b128 v[166:169], v213 offset:21504
	ds_read_b128 v[170:173], v213 offset:22528
	global_load_lds_dwordx4 v190, s[92:93]
	s_mov_b32 m0, s42
	ds_read_b128 v[174:177], v213 offset:23552
	global_load_lds_dwordx4 v192, s[92:93]
	s_waitcnt vmcnt(10)
	s_barrier
	s_waitcnt lgkmcnt(0)
	v_mfma_f32_16x16x32_bf16 v[62:65], v[130:133], v[146:149], 0
	v_mfma_f32_16x16x32_bf16 v[58:61], v[138:141], v[146:149], 0
	v_mfma_f32_16x16x32_bf16 v[46:49], v[130:133], v[154:157], 0
	v_mfma_f32_16x16x32_bf16 v[42:45], v[138:141], v[154:157], 0
	v_mfma_f32_16x16x32_bf16 v[30:33], v[130:133], v[162:165], 0
	v_mfma_f32_16x16x32_bf16 v[26:29], v[138:141], v[162:165], 0
	v_mfma_f32_16x16x32_bf16 v[14:17], v[130:133], v[170:173], 0
	v_mfma_f32_16x16x32_bf16 v[10:13], v[138:141], v[170:173], 0
	v_mfma_f32_16x16x32_bf16 v[62:65], v[134:137], v[150:153], v[62:65]
	v_mfma_f32_16x16x32_bf16 v[58:61], v[142:145], v[150:153], v[58:61]
	v_mfma_f32_16x16x32_bf16 v[46:49], v[134:137], v[158:161], v[46:49]
	v_mfma_f32_16x16x32_bf16 v[42:45], v[142:145], v[158:161], v[42:45]
	v_mfma_f32_16x16x32_bf16 v[30:33], v[134:137], v[166:169], v[30:33]
	v_mfma_f32_16x16x32_bf16 v[26:29], v[142:145], v[166:169], v[26:29]
	v_mfma_f32_16x16x32_bf16 v[14:17], v[134:137], v[174:177], v[14:17]
	v_mfma_f32_16x16x32_bf16 v[10:13], v[142:145], v[174:177], v[10:13]
	s_barrier
	s_add_u32 s88, s90, 0x40000
	s_addc_u32 s89, s91, 0
	s_add_i32 m0, s38, 0x14000
	s_nop 0
	global_load_lds_dwordx4 v0, s[88:89]
	s_add_i32 m0, s38, 0x16000
	s_nop 0
	global_load_lds_dwordx4 v194, s[88:89]
	s_add_i32 s79, 0, 0x18000
	v_add_u32_e32 v142, s79, v212
	ds_read_b128 v[130:133], v142
	ds_read_b128 v[134:137], v142 offset:1024
	ds_read_b128 v[138:141], v142 offset:2048
	ds_read_b128 v[142:145], v142 offset:3072
	s_waitcnt vmcnt(6)
	s_barrier
	v_mfma_f32_16x16x32_bf16 v[54:57], v[178:181], v[146:149], 0
	v_mfma_f32_16x16x32_bf16 v[50:53], v[200:203], v[146:149], 0
	v_mfma_f32_16x16x32_bf16 v[38:41], v[178:181], v[154:157], 0
	v_mfma_f32_16x16x32_bf16 v[34:37], v[200:203], v[154:157], 0
	v_mfma_f32_16x16x32_bf16 v[22:25], v[178:181], v[162:165], 0
	v_mfma_f32_16x16x32_bf16 v[18:21], v[200:203], v[162:165], 0
	v_mfma_f32_16x16x32_bf16 v[6:9], v[178:181], v[170:173], 0
	v_mfma_f32_16x16x32_bf16 v[2:5], v[200:203], v[170:173], 0
	v_mfma_f32_16x16x32_bf16 v[54:57], v[182:185], v[150:153], v[54:57]
	v_mfma_f32_16x16x32_bf16 v[50:53], v[204:207], v[150:153], v[50:53]
	v_mfma_f32_16x16x32_bf16 v[38:41], v[182:185], v[158:161], v[38:41]
	v_mfma_f32_16x16x32_bf16 v[34:37], v[204:207], v[158:161], v[34:37]
	v_mfma_f32_16x16x32_bf16 v[22:25], v[182:185], v[166:169], v[22:25]
	v_mfma_f32_16x16x32_bf16 v[18:21], v[204:207], v[166:169], v[18:21]
	v_mfma_f32_16x16x32_bf16 v[6:9], v[182:185], v[174:177], v[6:9]
	v_mfma_f32_16x16x32_bf16 v[2:5], v[204:207], v[174:177], v[2:5]
	s_barrier
	s_add_u32 s88, s92, 0xc0000
	s_addc_u32 s89, s93, 0
	s_mov_b32 m0, s43
	ds_read_b128 v[146:149], v213 offset:32768
	ds_read_b128 v[150:153], v213 offset:33792
	ds_read_b128 v[154:157], v213 offset:34816
	ds_read_b128 v[158:161], v213 offset:35840
	ds_read_b128 v[162:165], v213 offset:36864
	ds_read_b128 v[166:169], v213 offset:37888
	ds_read_b128 v[170:173], v213 offset:38912
	global_load_lds_dwordx4 v190, s[88:89]
	s_mov_b32 m0, s44
	ds_read_b128 v[174:177], v213 offset:39936
	global_load_lds_dwordx4 v192, s[88:89]
	s_waitcnt lgkmcnt(8)
	s_barrier
	s_waitcnt lgkmcnt(0)
	v_mfma_f32_16x16x32_bf16 v[126:129], v[130:133], v[146:149], v[126:129]
	v_mfma_f32_16x16x32_bf16 v[122:125], v[138:141], v[146:149], v[122:125]
	v_mfma_f32_16x16x32_bf16 v[110:113], v[130:133], v[154:157], v[110:113]
	v_mfma_f32_16x16x32_bf16 v[106:109], v[138:141], v[154:157], v[106:109]
	v_mfma_f32_16x16x32_bf16 v[94:97], v[130:133], v[162:165], v[94:97]
	v_mfma_f32_16x16x32_bf16 v[90:93], v[138:141], v[162:165], v[90:93]
	v_mfma_f32_16x16x32_bf16 v[78:81], v[130:133], v[170:173], v[78:81]
	v_mfma_f32_16x16x32_bf16 v[74:77], v[138:141], v[170:173], v[74:77]
	v_mfma_f32_16x16x32_bf16 v[126:129], v[134:137], v[150:153], v[126:129]
	v_mfma_f32_16x16x32_bf16 v[122:125], v[142:145], v[150:153], v[122:125]
	v_mfma_f32_16x16x32_bf16 v[110:113], v[134:137], v[158:161], v[110:113]
	v_mfma_f32_16x16x32_bf16 v[106:109], v[142:145], v[158:161], v[106:109]
	v_mfma_f32_16x16x32_bf16 v[94:97], v[134:137], v[166:169], v[94:97]
	v_mfma_f32_16x16x32_bf16 v[90:93], v[142:145], v[166:169], v[90:93]
	v_mfma_f32_16x16x32_bf16 v[78:81], v[134:137], v[174:177], v[78:81]
	v_mfma_f32_16x16x32_bf16 v[74:77], v[142:145], v[174:177], v[74:77]
	s_barrier
	s_add_i32 s87, 0, 0x1c000
	v_add_u32_e32 v204, s87, v212
	s_add_i32 m0, s38, 0x18000
	ds_read_b128 v[178:181], v204
	ds_read_b128 v[182:185], v204 offset:1024
	ds_read_b128 v[200:203], v204 offset:2048
	ds_read_b128 v[204:207], v204 offset:3072
	s_add_u32 s98, s90, s40
	s_addc_u32 s99, s91, s41
	global_load_lds_dwordx4 v0, s[98:99]
	s_add_i32 m0, s38, 0x1a000
	s_nop 0
	global_load_lds_dwordx4 v194, s[98:99]
	s_barrier
	s_waitcnt lgkmcnt(0)
	v_mfma_f32_16x16x32_bf16 v[118:121], v[178:181], v[146:149], v[118:121]
	v_mfma_f32_16x16x32_bf16 v[114:117], v[200:203], v[146:149], v[114:117]
	v_mfma_f32_16x16x32_bf16 v[102:105], v[178:181], v[154:157], v[102:105]
	v_mfma_f32_16x16x32_bf16 v[98:101], v[200:203], v[154:157], v[98:101]
	v_mfma_f32_16x16x32_bf16 v[86:89], v[178:181], v[162:165], v[86:89]
	v_mfma_f32_16x16x32_bf16 v[82:85], v[200:203], v[162:165], v[82:85]
	v_mfma_f32_16x16x32_bf16 v[70:73], v[178:181], v[170:173], v[70:73]
	v_mfma_f32_16x16x32_bf16 v[66:69], v[200:203], v[170:173], v[66:69]
	v_mfma_f32_16x16x32_bf16 v[118:121], v[182:185], v[150:153], v[118:121]
	v_mfma_f32_16x16x32_bf16 v[114:117], v[204:207], v[150:153], v[114:117]
	v_mfma_f32_16x16x32_bf16 v[102:105], v[182:185], v[158:161], v[102:105]
	v_mfma_f32_16x16x32_bf16 v[98:101], v[204:207], v[158:161], v[98:101]
	v_mfma_f32_16x16x32_bf16 v[86:89], v[182:185], v[166:169], v[86:89]
	v_mfma_f32_16x16x32_bf16 v[82:85], v[204:207], v[166:169], v[82:85]
	v_mfma_f32_16x16x32_bf16 v[70:73], v[182:185], v[174:177], v[70:73]
	v_mfma_f32_16x16x32_bf16 v[66:69], v[204:207], v[174:177], v[66:69]
	s_mov_b32 m0, s60
	s_barrier
	ds_read_b128 v[146:149], v213 offset:49152
	ds_read_b128 v[150:153], v213 offset:50176
	ds_read_b128 v[154:157], v213 offset:51200
	ds_read_b128 v[158:161], v213 offset:52224
	ds_read_b128 v[162:165], v213 offset:53248
	ds_read_b128 v[166:169], v213 offset:54272
	ds_read_b128 v[170:173], v213 offset:55296
	ds_read_b128 v[174:177], v213 offset:56320
	s_add_u32 s98, s92, s40
	s_addc_u32 s99, s93, s41
	global_load_lds_dwordx4 v190, s[98:99]
	s_mov_b32 m0, s61
	s_nop 0
	global_load_lds_dwordx4 v192, s[98:99]
	s_waitcnt vmcnt(10)
	s_barrier
	s_waitcnt lgkmcnt(0)
	v_mfma_f32_16x16x32_bf16 v[62:65], v[130:133], v[146:149], v[62:65]
	v_mfma_f32_16x16x32_bf16 v[58:61], v[138:141], v[146:149], v[58:61]
	v_mfma_f32_16x16x32_bf16 v[46:49], v[130:133], v[154:157], v[46:49]
	v_mfma_f32_16x16x32_bf16 v[42:45], v[138:141], v[154:157], v[42:45]
	v_mfma_f32_16x16x32_bf16 v[30:33], v[130:133], v[162:165], v[30:33]
	v_mfma_f32_16x16x32_bf16 v[26:29], v[138:141], v[162:165], v[26:29]
	v_mfma_f32_16x16x32_bf16 v[14:17], v[130:133], v[170:173], v[14:17]
	v_mfma_f32_16x16x32_bf16 v[10:13], v[138:141], v[170:173], v[10:13]
	v_mfma_f32_16x16x32_bf16 v[62:65], v[134:137], v[150:153], v[62:65]
	v_mfma_f32_16x16x32_bf16 v[58:61], v[142:145], v[150:153], v[58:61]
	v_mfma_f32_16x16x32_bf16 v[46:49], v[134:137], v[158:161], v[46:49]
	v_mfma_f32_16x16x32_bf16 v[42:45], v[142:145], v[158:161], v[42:45]
	v_mfma_f32_16x16x32_bf16 v[30:33], v[134:137], v[166:169], v[30:33]
	v_mfma_f32_16x16x32_bf16 v[26:29], v[142:145], v[166:169], v[26:29]
	v_mfma_f32_16x16x32_bf16 v[14:17], v[134:137], v[174:177], v[14:17]
	v_mfma_f32_16x16x32_bf16 v[10:13], v[142:145], v[174:177], v[10:13]
	s_barrier
	s_add_u32 s88, s90, 0x40080
	s_addc_u32 s89, s91, 0
	s_add_i32 m0, s38, 0x1c000
	s_nop 0
	global_load_lds_dwordx4 v0, s[88:89]
	s_add_i32 m0, s38, 0x1e000
	s_nop 0
	global_load_lds_dwordx4 v194, s[88:89]
	ds_read_b128 v[130:133], v189
	ds_read_b128 v[134:137], v189 offset:1024
	ds_read_b128 v[138:141], v189 offset:2048
	ds_read_b128 v[142:145], v189 offset:3072
	s_waitcnt vmcnt(6)
	s_barrier
	v_mfma_f32_16x16x32_bf16 v[54:57], v[178:181], v[146:149], v[54:57]
	v_mfma_f32_16x16x32_bf16 v[50:53], v[200:203], v[146:149], v[50:53]
	v_mfma_f32_16x16x32_bf16 v[38:41], v[178:181], v[154:157], v[38:41]
	v_mfma_f32_16x16x32_bf16 v[34:37], v[200:203], v[154:157], v[34:37]
	v_mfma_f32_16x16x32_bf16 v[22:25], v[178:181], v[162:165], v[22:25]
	v_mfma_f32_16x16x32_bf16 v[18:21], v[200:203], v[162:165], v[18:21]
	v_mfma_f32_16x16x32_bf16 v[6:9], v[178:181], v[170:173], v[6:9]
	v_mfma_f32_16x16x32_bf16 v[2:5], v[200:203], v[170:173], v[2:5]
	v_mfma_f32_16x16x32_bf16 v[54:57], v[182:185], v[150:153], v[54:57]
	s_add_i32 s78, s78, 2
	s_add_u32 s34, s34, 0x100
	v_mfma_f32_16x16x32_bf16 v[50:53], v[204:207], v[150:153], v[50:53]
	s_addc_u32 s75, s75, 0
	s_mov_b64 s[88:89], s[4:5]
	v_mfma_f32_16x16x32_bf16 v[38:41], v[182:185], v[158:161], v[38:41]
	s_add_u32 s4, s88, 0x100
	s_addc_u32 s5, s89, 0
	v_mfma_f32_16x16x32_bf16 v[34:37], v[204:207], v[158:161], v[34:37]
	s_cmp_eq_u32 s78, 12
	s_cselect_b32 s93, s17, s5
	v_mfma_f32_16x16x32_bf16 v[22:25], v[182:185], v[166:169], v[22:25]
	s_cselect_b32 s92, s16, s4
	s_cselect_b32 s91, s15, s75
	v_mfma_f32_16x16x32_bf16 v[18:21], v[204:207], v[166:169], v[18:21]
	s_cselect_b32 s90, s23, s34
	s_cmp_gt_u32 s78, 13
	v_mfma_f32_16x16x32_bf16 v[6:9], v[182:185], v[174:177], v[6:9]
	v_mfma_f32_16x16x32_bf16 v[2:5], v[204:207], v[174:177], v[2:5]
	s_barrier
	.p2align 3
.LBB0_838:
	v_lshl_add_u64 v[178:179], s[88:89], 0, v[196:197]
	s_add_i32 m0, s39, 0xc000
	ds_read_b128 v[146:149], v213
	ds_read_b128 v[150:153], v213 offset:1024
	ds_read_b128 v[154:157], v213 offset:2048
	ds_read_b128 v[158:161], v213 offset:3072
	ds_read_b128 v[162:165], v213 offset:4096
	ds_read_b128 v[166:169], v213 offset:5120
	ds_read_b128 v[170:173], v213 offset:6144
	ds_read_b128 v[174:177], v213 offset:7168
	global_load_lds_dwordx4 v[178:179], off
	s_add_i32 m0, s39, 0xe000
	v_lshl_add_u64 v[178:179], s[88:89], 0, v[198:199]
	global_load_lds_dwordx4 v[178:179], off
	s_waitcnt lgkmcnt(8)
	s_barrier
	s_waitcnt lgkmcnt(0)
	v_mfma_f32_16x16x32_bf16 v[126:129], v[130:133], v[146:149], v[126:129]
	v_mfma_f32_16x16x32_bf16 v[122:125], v[138:141], v[146:149], v[122:125]
	v_mfma_f32_16x16x32_bf16 v[110:113], v[130:133], v[154:157], v[110:113]
	v_mfma_f32_16x16x32_bf16 v[106:109], v[138:141], v[154:157], v[106:109]
	v_mfma_f32_16x16x32_bf16 v[94:97], v[130:133], v[162:165], v[94:97]
	v_mfma_f32_16x16x32_bf16 v[90:93], v[138:141], v[162:165], v[90:93]
	v_mfma_f32_16x16x32_bf16 v[78:81], v[130:133], v[170:173], v[78:81]
	v_mfma_f32_16x16x32_bf16 v[74:77], v[138:141], v[170:173], v[74:77]
	v_mfma_f32_16x16x32_bf16 v[126:129], v[134:137], v[150:153], v[126:129]
	v_mfma_f32_16x16x32_bf16 v[122:125], v[142:145], v[150:153], v[122:125]
	v_mfma_f32_16x16x32_bf16 v[110:113], v[134:137], v[158:161], v[110:113]
	v_mfma_f32_16x16x32_bf16 v[106:109], v[142:145], v[158:161], v[106:109]
	v_mfma_f32_16x16x32_bf16 v[94:97], v[134:137], v[166:169], v[94:97]
	v_mfma_f32_16x16x32_bf16 v[90:93], v[142:145], v[166:169], v[90:93]
	v_mfma_f32_16x16x32_bf16 v[78:81], v[134:137], v[174:177], v[78:81]
	v_mfma_f32_16x16x32_bf16 v[74:77], v[142:145], v[174:177], v[74:77]
	s_barrier
	ds_read_b128 v[178:181], v189 offset:16384
	ds_read_b128 v[182:185], v189 offset:17408
	ds_read_b128 v[200:203], v189 offset:18432
	ds_read_b128 v[204:207], v189 offset:19456
	s_add_i32 m0, s38, 0x10000
	s_nop 0
	global_load_lds_dwordx4 v0, s[90:91]
	s_add_i32 m0, s38, 0x12000
	s_nop 0
	global_load_lds_dwordx4 v194, s[90:91]
	s_barrier
	s_waitcnt lgkmcnt(0)
	v_mfma_f32_16x16x32_bf16 v[118:121], v[178:181], v[146:149], v[118:121]
	v_mfma_f32_16x16x32_bf16 v[114:117], v[200:203], v[146:149], v[114:117]
	v_mfma_f32_16x16x32_bf16 v[102:105], v[178:181], v[154:157], v[102:105]
	v_mfma_f32_16x16x32_bf16 v[98:101], v[200:203], v[154:157], v[98:101]
	v_mfma_f32_16x16x32_bf16 v[86:89], v[178:181], v[162:165], v[86:89]
	v_mfma_f32_16x16x32_bf16 v[82:85], v[200:203], v[162:165], v[82:85]
	v_mfma_f32_16x16x32_bf16 v[70:73], v[178:181], v[170:173], v[70:73]
	v_mfma_f32_16x16x32_bf16 v[66:69], v[200:203], v[170:173], v[66:69]
	v_mfma_f32_16x16x32_bf16 v[118:121], v[182:185], v[150:153], v[118:121]
	v_mfma_f32_16x16x32_bf16 v[114:117], v[204:207], v[150:153], v[114:117]
	v_mfma_f32_16x16x32_bf16 v[102:105], v[182:185], v[158:161], v[102:105]
	v_mfma_f32_16x16x32_bf16 v[98:101], v[204:207], v[158:161], v[98:101]
	v_mfma_f32_16x16x32_bf16 v[86:89], v[182:185], v[166:169], v[86:89]
	v_mfma_f32_16x16x32_bf16 v[82:85], v[204:207], v[166:169], v[82:85]
	v_mfma_f32_16x16x32_bf16 v[70:73], v[182:185], v[174:177], v[70:73]
	v_mfma_f32_16x16x32_bf16 v[66:69], v[204:207], v[174:177], v[66:69]
	s_mov_b32 m0, s39
	s_barrier
	ds_read_b128 v[146:149], v213 offset:16384
	ds_read_b128 v[150:153], v213 offset:17408
	ds_read_b128 v[154:157], v213 offset:18432
	ds_read_b128 v[158:161], v213 offset:19456
	ds_read_b128 v[162:165], v213 offset:20480
	ds_read_b128 v[166:169], v213 offset:21504
	ds_read_b128 v[170:173], v213 offset:22528
	global_load_lds_dwordx4 v190, s[92:93]
	s_mov_b32 m0, s42
	ds_read_b128 v[174:177], v213 offset:23552
	global_load_lds_dwordx4 v192, s[92:93]
	s_waitcnt vmcnt(10)
	s_barrier
	s_waitcnt lgkmcnt(0)
	v_mfma_f32_16x16x32_bf16 v[62:65], v[130:133], v[146:149], v[62:65]
	v_mfma_f32_16x16x32_bf16 v[58:61], v[138:141], v[146:149], v[58:61]
	v_mfma_f32_16x16x32_bf16 v[46:49], v[130:133], v[154:157], v[46:49]
	v_mfma_f32_16x16x32_bf16 v[42:45], v[138:141], v[154:157], v[42:45]
	v_mfma_f32_16x16x32_bf16 v[30:33], v[130:133], v[162:165], v[30:33]
	v_mfma_f32_16x16x32_bf16 v[26:29], v[138:141], v[162:165], v[26:29]
	v_mfma_f32_16x16x32_bf16 v[14:17], v[130:133], v[170:173], v[14:17]
	v_mfma_f32_16x16x32_bf16 v[10:13], v[138:141], v[170:173], v[10:13]
	v_mfma_f32_16x16x32_bf16 v[62:65], v[134:137], v[150:153], v[62:65]
	v_mfma_f32_16x16x32_bf16 v[58:61], v[142:145], v[150:153], v[58:61]
	v_mfma_f32_16x16x32_bf16 v[46:49], v[134:137], v[158:161], v[46:49]
	v_mfma_f32_16x16x32_bf16 v[42:45], v[142:145], v[158:161], v[42:45]
	v_mfma_f32_16x16x32_bf16 v[30:33], v[134:137], v[166:169], v[30:33]
	v_mfma_f32_16x16x32_bf16 v[26:29], v[142:145], v[166:169], v[26:29]
	v_mfma_f32_16x16x32_bf16 v[14:17], v[134:137], v[174:177], v[14:17]
	v_mfma_f32_16x16x32_bf16 v[10:13], v[142:145], v[174:177], v[10:13]
	s_barrier
	s_add_u32 s88, s90, 0x40000
	s_addc_u32 s89, s91, 0
	s_add_i32 m0, s38, 0x14000
	s_nop 0
	global_load_lds_dwordx4 v0, s[88:89]
	s_add_i32 m0, s38, 0x16000
	s_nop 0
	global_load_lds_dwordx4 v194, s[88:89]
	s_add_i32 s79, 0, 0x18000
	v_add_u32_e32 v142, s79, v212
	ds_read_b128 v[130:133], v142
	ds_read_b128 v[134:137], v142 offset:1024
	ds_read_b128 v[138:141], v142 offset:2048
	ds_read_b128 v[142:145], v142 offset:3072
	s_waitcnt vmcnt(6)
	s_barrier
	v_mfma_f32_16x16x32_bf16 v[54:57], v[178:181], v[146:149], v[54:57]
	v_mfma_f32_16x16x32_bf16 v[50:53], v[200:203], v[146:149], v[50:53]
	v_mfma_f32_16x16x32_bf16 v[38:41], v[178:181], v[154:157], v[38:41]
	v_mfma_f32_16x16x32_bf16 v[34:37], v[200:203], v[154:157], v[34:37]
	v_mfma_f32_16x16x32_bf16 v[22:25], v[178:181], v[162:165], v[22:25]
	v_mfma_f32_16x16x32_bf16 v[18:21], v[200:203], v[162:165], v[18:21]
	v_mfma_f32_16x16x32_bf16 v[6:9], v[178:181], v[170:173], v[6:9]
	v_mfma_f32_16x16x32_bf16 v[2:5], v[200:203], v[170:173], v[2:5]
	v_mfma_f32_16x16x32_bf16 v[54:57], v[182:185], v[150:153], v[54:57]
	v_mfma_f32_16x16x32_bf16 v[50:53], v[204:207], v[150:153], v[50:53]
	v_mfma_f32_16x16x32_bf16 v[38:41], v[182:185], v[158:161], v[38:41]
	v_mfma_f32_16x16x32_bf16 v[34:37], v[204:207], v[158:161], v[34:37]
	v_mfma_f32_16x16x32_bf16 v[22:25], v[182:185], v[166:169], v[22:25]
	v_mfma_f32_16x16x32_bf16 v[18:21], v[204:207], v[166:169], v[18:21]
	v_mfma_f32_16x16x32_bf16 v[6:9], v[182:185], v[174:177], v[6:9]
	v_mfma_f32_16x16x32_bf16 v[2:5], v[204:207], v[174:177], v[2:5]
	s_barrier
	s_add_u32 s88, s92, 0xc0000
	s_addc_u32 s89, s93, 0
	s_mov_b32 m0, s43
	ds_read_b128 v[146:149], v213 offset:32768
	ds_read_b128 v[150:153], v213 offset:33792
	ds_read_b128 v[154:157], v213 offset:34816
	ds_read_b128 v[158:161], v213 offset:35840
	ds_read_b128 v[162:165], v213 offset:36864
	ds_read_b128 v[166:169], v213 offset:37888
	ds_read_b128 v[170:173], v213 offset:38912
	global_load_lds_dwordx4 v190, s[88:89]
	s_mov_b32 m0, s44
	ds_read_b128 v[174:177], v213 offset:39936
	global_load_lds_dwordx4 v192, s[88:89]
	s_waitcnt lgkmcnt(8)
	s_barrier
	s_waitcnt lgkmcnt(0)
	v_mfma_f32_16x16x32_bf16 v[126:129], v[130:133], v[146:149], v[126:129]
	v_mfma_f32_16x16x32_bf16 v[122:125], v[138:141], v[146:149], v[122:125]
	v_mfma_f32_16x16x32_bf16 v[110:113], v[130:133], v[154:157], v[110:113]
	v_mfma_f32_16x16x32_bf16 v[106:109], v[138:141], v[154:157], v[106:109]
	v_mfma_f32_16x16x32_bf16 v[94:97], v[130:133], v[162:165], v[94:97]
	v_mfma_f32_16x16x32_bf16 v[90:93], v[138:141], v[162:165], v[90:93]
	v_mfma_f32_16x16x32_bf16 v[78:81], v[130:133], v[170:173], v[78:81]
	v_mfma_f32_16x16x32_bf16 v[74:77], v[138:141], v[170:173], v[74:77]
	v_mfma_f32_16x16x32_bf16 v[126:129], v[134:137], v[150:153], v[126:129]
	v_mfma_f32_16x16x32_bf16 v[122:125], v[142:145], v[150:153], v[122:125]
	v_mfma_f32_16x16x32_bf16 v[110:113], v[134:137], v[158:161], v[110:113]
	v_mfma_f32_16x16x32_bf16 v[106:109], v[142:145], v[158:161], v[106:109]
	v_mfma_f32_16x16x32_bf16 v[94:97], v[134:137], v[166:169], v[94:97]
	v_mfma_f32_16x16x32_bf16 v[90:93], v[142:145], v[166:169], v[90:93]
	v_mfma_f32_16x16x32_bf16 v[78:81], v[134:137], v[174:177], v[78:81]
	v_mfma_f32_16x16x32_bf16 v[74:77], v[142:145], v[174:177], v[74:77]
	s_barrier
	s_add_i32 s87, 0, 0x1c000
	v_add_u32_e32 v204, s87, v212
	s_add_i32 m0, s38, 0x18000
	ds_read_b128 v[178:181], v204
	ds_read_b128 v[182:185], v204 offset:1024
	ds_read_b128 v[200:203], v204 offset:2048
	ds_read_b128 v[204:207], v204 offset:3072
	s_add_u32 s98, s90, s40
	s_addc_u32 s99, s91, s41
	global_load_lds_dwordx4 v0, s[98:99]
	s_add_i32 m0, s38, 0x1a000
	s_nop 0
	global_load_lds_dwordx4 v194, s[98:99]
	s_barrier
	s_waitcnt lgkmcnt(0)
	v_mfma_f32_16x16x32_bf16 v[118:121], v[178:181], v[146:149], v[118:121]
	v_mfma_f32_16x16x32_bf16 v[114:117], v[200:203], v[146:149], v[114:117]
	v_mfma_f32_16x16x32_bf16 v[102:105], v[178:181], v[154:157], v[102:105]
	v_mfma_f32_16x16x32_bf16 v[98:101], v[200:203], v[154:157], v[98:101]
	v_mfma_f32_16x16x32_bf16 v[86:89], v[178:181], v[162:165], v[86:89]
	v_mfma_f32_16x16x32_bf16 v[82:85], v[200:203], v[162:165], v[82:85]
	v_mfma_f32_16x16x32_bf16 v[70:73], v[178:181], v[170:173], v[70:73]
	v_mfma_f32_16x16x32_bf16 v[66:69], v[200:203], v[170:173], v[66:69]
	v_mfma_f32_16x16x32_bf16 v[118:121], v[182:185], v[150:153], v[118:121]
	v_mfma_f32_16x16x32_bf16 v[114:117], v[204:207], v[150:153], v[114:117]
	v_mfma_f32_16x16x32_bf16 v[102:105], v[182:185], v[158:161], v[102:105]
	v_mfma_f32_16x16x32_bf16 v[98:101], v[204:207], v[158:161], v[98:101]
	v_mfma_f32_16x16x32_bf16 v[86:89], v[182:185], v[166:169], v[86:89]
	v_mfma_f32_16x16x32_bf16 v[82:85], v[204:207], v[166:169], v[82:85]
	v_mfma_f32_16x16x32_bf16 v[70:73], v[182:185], v[174:177], v[70:73]
	v_mfma_f32_16x16x32_bf16 v[66:69], v[204:207], v[174:177], v[66:69]
	s_mov_b32 m0, s60
	s_barrier
	ds_read_b128 v[146:149], v213 offset:49152
	ds_read_b128 v[150:153], v213 offset:50176
	ds_read_b128 v[154:157], v213 offset:51200
	ds_read_b128 v[158:161], v213 offset:52224
	ds_read_b128 v[162:165], v213 offset:53248
	ds_read_b128 v[166:169], v213 offset:54272
	ds_read_b128 v[170:173], v213 offset:55296
	ds_read_b128 v[174:177], v213 offset:56320
	s_add_u32 s98, s92, s40
	s_addc_u32 s99, s93, s41
	global_load_lds_dwordx4 v190, s[98:99]
	s_mov_b32 m0, s61
	s_nop 0
	global_load_lds_dwordx4 v192, s[98:99]
	s_waitcnt vmcnt(10)
	s_barrier
	s_waitcnt lgkmcnt(0)
	v_mfma_f32_16x16x32_bf16 v[62:65], v[130:133], v[146:149], v[62:65]
	v_mfma_f32_16x16x32_bf16 v[58:61], v[138:141], v[146:149], v[58:61]
	v_mfma_f32_16x16x32_bf16 v[46:49], v[130:133], v[154:157], v[46:49]
	v_mfma_f32_16x16x32_bf16 v[42:45], v[138:141], v[154:157], v[42:45]
	v_mfma_f32_16x16x32_bf16 v[30:33], v[130:133], v[162:165], v[30:33]
	v_mfma_f32_16x16x32_bf16 v[26:29], v[138:141], v[162:165], v[26:29]
	v_mfma_f32_16x16x32_bf16 v[14:17], v[130:133], v[170:173], v[14:17]
	v_mfma_f32_16x16x32_bf16 v[10:13], v[138:141], v[170:173], v[10:13]
	v_mfma_f32_16x16x32_bf16 v[62:65], v[134:137], v[150:153], v[62:65]
	v_mfma_f32_16x16x32_bf16 v[58:61], v[142:145], v[150:153], v[58:61]
	v_mfma_f32_16x16x32_bf16 v[46:49], v[134:137], v[158:161], v[46:49]
	v_mfma_f32_16x16x32_bf16 v[42:45], v[142:145], v[158:161], v[42:45]
	v_mfma_f32_16x16x32_bf16 v[30:33], v[134:137], v[166:169], v[30:33]
	v_mfma_f32_16x16x32_bf16 v[26:29], v[142:145], v[166:169], v[26:29]
	v_mfma_f32_16x16x32_bf16 v[14:17], v[134:137], v[174:177], v[14:17]
	v_mfma_f32_16x16x32_bf16 v[10:13], v[142:145], v[174:177], v[10:13]
	s_barrier
	s_add_u32 s88, s90, 0x40080
	s_addc_u32 s89, s91, 0
	s_add_i32 m0, s38, 0x1c000
	s_nop 0
	global_load_lds_dwordx4 v0, s[88:89]
	s_add_i32 m0, s38, 0x1e000
	s_nop 0
	global_load_lds_dwordx4 v194, s[88:89]
	ds_read_b128 v[130:133], v189
	ds_read_b128 v[134:137], v189 offset:1024
	ds_read_b128 v[138:141], v189 offset:2048
	ds_read_b128 v[142:145], v189 offset:3072
	s_waitcnt vmcnt(6)
	s_barrier
	v_mfma_f32_16x16x32_bf16 v[54:57], v[178:181], v[146:149], v[54:57]
	v_mfma_f32_16x16x32_bf16 v[50:53], v[200:203], v[146:149], v[50:53]
	v_mfma_f32_16x16x32_bf16 v[38:41], v[178:181], v[154:157], v[38:41]
	v_mfma_f32_16x16x32_bf16 v[34:37], v[200:203], v[154:157], v[34:37]
	v_mfma_f32_16x16x32_bf16 v[22:25], v[178:181], v[162:165], v[22:25]
	v_mfma_f32_16x16x32_bf16 v[18:21], v[200:203], v[162:165], v[18:21]
	v_mfma_f32_16x16x32_bf16 v[6:9], v[178:181], v[170:173], v[6:9]
	v_mfma_f32_16x16x32_bf16 v[2:5], v[200:203], v[170:173], v[2:5]
	v_mfma_f32_16x16x32_bf16 v[54:57], v[182:185], v[150:153], v[54:57]
	s_add_i32 s78, s78, 2
	s_add_u32 s34, s34, 0x100
	v_mfma_f32_16x16x32_bf16 v[50:53], v[204:207], v[150:153], v[50:53]
	s_addc_u32 s75, s75, 0
	s_mov_b64 s[88:89], s[4:5]
	v_mfma_f32_16x16x32_bf16 v[38:41], v[182:185], v[158:161], v[38:41]
	s_add_u32 s4, s88, 0x100
	s_addc_u32 s5, s89, 0
	v_mfma_f32_16x16x32_bf16 v[34:37], v[204:207], v[158:161], v[34:37]
	s_cmp_eq_u32 s78, 12
	s_cselect_b32 s93, s17, s5
	v_mfma_f32_16x16x32_bf16 v[22:25], v[182:185], v[166:169], v[22:25]
	s_cselect_b32 s92, s16, s4
	s_cselect_b32 s91, s15, s75
	v_mfma_f32_16x16x32_bf16 v[18:21], v[204:207], v[166:169], v[18:21]
	s_cselect_b32 s90, s23, s34
	s_cmp_gt_u32 s78, 13
	v_mfma_f32_16x16x32_bf16 v[6:9], v[182:185], v[174:177], v[6:9]
	v_mfma_f32_16x16x32_bf16 v[2:5], v[204:207], v[174:177], v[2:5]
	s_barrier
	s_cbranch_scc0 .LBB0_838
	s_waitcnt lgkmcnt(0)
	s_lshl_b32 s4, s22, 8
	v_mov_b32_e32 v186, v252
	s_add_i32 s4, s4, s47
	s_nop 0
	v_and_or_b32 v202, v186, 15, s4
	s_lshl_b32 s4, s86, 8
	s_or_b32 s4, s4, s55
	v_lshrrev_b32_e32 v130, 1, v186
	v_and_or_b32 v200, v130, 24, s4
	v_ashrrev_i32_e32 v201, 31, v200
	v_ashrrev_i32_e32 v203, 31, v202
	v_lshl_add_u64 v[204:205], v[200:201], 2, s[6:7]
	v_lshlrev_b64 v[130:131], 12, v[202:203]
	v_lshl_add_u64 v[130:131], v[204:205], 0, v[130:131]
	global_load_dwordx4 v[216:219], v[130:131], off offset:16
	global_load_dwordx4 v[220:223], v[130:131], off
	global_load_dwordx4 v[178:181], v[130:131], off offset:528
	global_load_dwordx4 v[182:185], v[130:131], off offset:512
	v_or_b32_e32 v210, 16, v202
	v_ashrrev_i32_e32 v211, 31, v210
	v_lshlrev_b64 v[130:131], 12, v[210:211]
	v_or_b32_e32 v208, 32, v202
	v_lshl_add_u64 v[130:131], v[204:205], 0, v[130:131]
	v_ashrrev_i32_e32 v209, 31, v208
	global_load_dwordx4 v[170:173], v[130:131], off offset:16
	global_load_dwordx4 v[174:177], v[130:131], off
	global_load_dwordx4 v[162:165], v[130:131], off offset:528
	global_load_dwordx4 v[166:169], v[130:131], off offset:512
	v_lshlrev_b64 v[130:131], 12, v[208:209]
	v_or_b32_e32 v206, 48, v202
	v_lshl_add_u64 v[130:131], v[204:205], 0, v[130:131]
	v_ashrrev_i32_e32 v207, 31, v206
	global_load_dwordx4 v[154:157], v[130:131], off offset:16
	global_load_dwordx4 v[158:161], v[130:131], off
	global_load_dwordx4 v[138:141], v[130:131], off offset:528
	global_load_dwordx4 v[142:145], v[130:131], off offset:512
	v_lshlrev_b64 v[130:131], 12, v[206:207]
	v_lshl_add_u64 v[134:135], v[204:205], 0, v[130:131]
	global_load_dwordx4 v[146:149], v[134:135], off offset:16
	global_load_dwordx4 v[150:153], v[134:135], off
	global_load_dwordx4 v[130:133], v[134:135], off offset:528
	s_nop 0
	global_load_dwordx4 v[134:137], v[134:135], off offset:512
	v_and_b32_e32 v186, 63, v186
	v_lshlrev_b32_e32 v187, 2, v186
	v_xor_b32_e32 v215, 64, v187
	v_xor_b32_e32 v214, 0x80, v187
	v_cmp_gt_u32_e32 vcc, 16, v186
	v_lshlrev_b64 v[186:187], 10, v[202:203]
	v_lshl_add_u64 v[186:187], v[186:187], 0, v[200:201]
	s_lshl_b32 s4, s86, 2
	s_ashr_i32 s5, s4, 31
	s_waitcnt vmcnt(0)
	v_pk_add_f32 v[124:125], v[124:125], v[218:219]
	v_pk_add_f32 v[128:129], v[128:129], v[222:223]
	v_pk_add_f32 v[126:127], v[126:127], v[220:221]
	v_pk_mul_f32 v[218:219], v[128:129], v[128:129]
	v_pk_mul_f32 v[220:221], v[126:127], v[126:127]
	v_pk_add_f32 v[122:123], v[122:123], v[216:217]
	v_lshl_add_u64 v[216:217], v[186:187], 2, s[12:13]
	v_add_f32_e32 v220, v220, v221
	v_add_f32_e32 v218, v218, v219
	global_store_dwordx4 v[216:217], v[126:129], off
	global_store_dwordx4 v[216:217], v[122:125], off offset:16
	v_add_f32_e32 v222, v220, v218
	v_pk_mul_f32 v[220:221], v[122:123], v[122:123]
	v_cvt_pk_bf16_f32 v126, v126, v127
	v_cvt_pk_bf16_f32 v127, v128, v129
	v_cvt_pk_bf16_f32 v128, v122, v123
	v_cvt_pk_bf16_f32 v129, v124, v125
	v_lshl_add_u64 v[122:123], v[186:187], 1, s[8:9]
	v_pk_add_f32 v[120:121], v[120:121], v[184:185]
	v_pk_add_f32 v[118:119], v[118:119], v[182:183]
	v_pk_mul_f32 v[218:219], v[124:125], v[124:125]
	global_store_dwordx4 v[122:123], v[126:129], off
	v_pk_mul_f32 v[124:125], v[120:121], v[120:121]
	v_pk_add_f32 v[116:117], v[116:117], v[180:181]
	v_pk_mul_f32 v[126:127], v[118:119], v[118:119]
	v_pk_add_f32 v[114:115], v[114:115], v[178:179]
	v_add_f32_e32 v126, v126, v127
	v_add_f32_e32 v124, v124, v125
	v_add_f32_e32 v128, v126, v124
	v_pk_mul_f32 v[124:125], v[116:117], v[116:117]
	v_pk_mul_f32 v[126:127], v[114:115], v[114:115]
	v_add_f32_e32 v220, v220, v221
	v_add_f32_e32 v218, v218, v219
	v_add_f32_e32 v126, v126, v127
	v_add_f32_e32 v124, v124, v125
	v_add_f32_e32 v218, v220, v218
	v_add_f32_e32 v124, v126, v124
	v_add_f32_e32 v218, v222, v218
	v_add_f32_e32 v124, v128, v124
	v_add_f32_e32 v124, v218, v124
	global_store_dwordx4 v[216:217], v[118:121], off offset:512
	global_store_dwordx4 v[216:217], v[114:117], off offset:528
	s_nop 0
	v_cvt_pk_bf16_f32 v118, v118, v119
	v_cvt_pk_bf16_f32 v119, v120, v121
	v_cvt_pk_bf16_f32 v120, v114, v115
	ds_bpermute_b32 v114, v215, v124
	v_cvt_pk_bf16_f32 v121, v116, v117
	global_store_dwordx4 v[122:123], v[118:121], off offset:256
	s_waitcnt lgkmcnt(0)
	v_add_f32_e32 v114, v124, v114
	ds_bpermute_b32 v115, v214, v114
	s_and_saveexec_b64 s[22:23], vcc
	s_cbranch_execz .LBB0_841
	v_lshlrev_b64 v[116:117], 6, v[202:203]
	v_lshl_add_u64 v[116:117], s[10:11], 0, v[116:117]
	v_lshl_add_u64 v[116:117], s[4:5], 2, v[116:117]
	s_lshl_b32 s34, s45, 2
	v_lshl_add_u64 v[116:117], v[116:117], 0, s[34:35]
	s_waitcnt lgkmcnt(0)
	v_add_f32_e32 v114, v114, v115
	global_store_dword v[116:117], v114, off

.LBB0_918:
	s_ashr_i32 s17, s16, 31
	s_lshl_b64 s[22:23], s[16:17], 19
	v_mov_b64_e32 v[2:3], 0xb00
	s_add_u32 s84, s8, s22
	v_cmp_lt_i64_e32 vcc, s[28:29], v[2:3]
	s_addc_u32 s85, s9, s23
	s_and_b64 s[22:23], vcc, exec
	s_cselect_b32 s17, s85, s7
	s_cselect_b32 s22, s84, s6
	s_ashr_i32 s15, s14, 31
	s_lshl_b64 s[28:29], s[14:15], 19
	s_add_u32 s86, s37, s28
	s_addc_u32 s87, s38, s29
	s_and_b64 s[28:29], vcc, exec
	s_cselect_b32 s15, s87, s89
	s_cselect_b32 s23, s86, s88
	s_add_u32 s28, s88, 0x100
	s_addc_u32 s29, s89, 0
	s_mov_b32 s45, -2
	s_add_i32 vcc_lo, 0, 0x10000
	v_add_u32_e32 v0, vcc_lo, v254
	v_add_u32_e32 v189, 0x10000, v254
	ds_read_b128 v[130:133], v0
	ds_read_b128 v[134:137], v0 offset:1024
	ds_read_b128 v[138:141], v0 offset:2048
	ds_read_b128 v[142:145], v0 offset:3072
	s_add_u32 s88, s6, 0x100
	s_addc_u32 s89, s7, 0
	s_cmp_eq_u32 s45, 12
	s_cselect_b32 s93, s17, s89
	s_cselect_b32 s92, s22, s88
	s_cselect_b32 s91, s15, s29
	s_cselect_b32 s90, s23, s28
	s_add_i32 m0, s43, 0xc000
	ds_read_b128 v[146:149], v253
	ds_read_b128 v[150:153], v253 offset:1024
	ds_read_b128 v[168:171], v253 offset:2048
	ds_read_b128 v[172:175], v253 offset:3072
	ds_read_b128 v[176:179], v253 offset:4096
	ds_read_b128 v[180:183], v253 offset:5120
	ds_read_b128 v[184:187], v253 offset:6144
	ds_read_b128 v[190:193], v253 offset:7168
	global_load_lds_dwordx4 v164, s[6:7]
	s_add_i32 m0, s43, 0xe000
	v_lshl_add_u64 v[154:155], s[6:7], 0, v[166:167]
	global_load_lds_dwordx4 v[154:155], off
	s_waitcnt lgkmcnt(8)
	s_barrier
	s_waitcnt lgkmcnt(0)
	v_mfma_f32_16x16x32_bf16 v[126:129], v[130:133], v[146:149], 0
	v_mfma_f32_16x16x32_bf16 v[70:73], v[138:141], v[146:149], 0
	v_mfma_f32_16x16x32_bf16 v[122:125], v[130:133], v[168:171], 0
	v_mfma_f32_16x16x32_bf16 v[74:77], v[138:141], v[168:171], 0
	v_mfma_f32_16x16x32_bf16 v[114:117], v[130:133], v[176:179], 0
	v_mfma_f32_16x16x32_bf16 v[66:69], v[138:141], v[176:179], 0
	v_mfma_f32_16x16x32_bf16 v[110:113], v[130:133], v[184:187], 0
	v_mfma_f32_16x16x32_bf16 v[78:81], v[138:141], v[184:187], 0
	v_mfma_f32_16x16x32_bf16 v[126:129], v[134:137], v[150:153], v[126:129]
	v_mfma_f32_16x16x32_bf16 v[70:73], v[142:145], v[150:153], v[70:73]
	v_mfma_f32_16x16x32_bf16 v[122:125], v[134:137], v[172:175], v[122:125]
	v_mfma_f32_16x16x32_bf16 v[74:77], v[142:145], v[172:175], v[74:77]
	v_mfma_f32_16x16x32_bf16 v[114:117], v[134:137], v[180:183], v[114:117]
	v_mfma_f32_16x16x32_bf16 v[66:69], v[142:145], v[180:183], v[66:69]
	v_mfma_f32_16x16x32_bf16 v[110:113], v[134:137], v[190:193], v[110:113]
	v_mfma_f32_16x16x32_bf16 v[78:81], v[142:145], v[190:193], v[78:81]
	s_barrier
	s_add_i32 m0, s39, 0x10000
	ds_read_b128 v[194:197], v189 offset:16384
	ds_read_b128 v[198:201], v189 offset:17408
	ds_read_b128 v[202:205], v189 offset:18432
	global_load_lds_dwordx4 v160, s[90:91]
	s_add_i32 m0, s39, 0x12000
	ds_read_b128 v[206:209], v189 offset:19456
	global_load_lds_dwordx4 v156, s[90:91]
	s_barrier
	s_waitcnt lgkmcnt(0)
	v_mfma_f32_16x16x32_bf16 v[118:121], v[194:197], v[146:149], 0
	v_mfma_f32_16x16x32_bf16 v[94:97], v[202:205], v[146:149], 0
	v_mfma_f32_16x16x32_bf16 v[106:109], v[194:197], v[168:171], 0
	v_mfma_f32_16x16x32_bf16 v[90:93], v[202:205], v[168:171], 0
	v_mfma_f32_16x16x32_bf16 v[102:105], v[194:197], v[176:179], 0
	v_mfma_f32_16x16x32_bf16 v[82:85], v[202:205], v[176:179], 0
	v_mfma_f32_16x16x32_bf16 v[98:101], v[194:197], v[184:187], 0
	v_mfma_f32_16x16x32_bf16 v[86:89], v[202:205], v[184:187], 0
	v_mfma_f32_16x16x32_bf16 v[118:121], v[198:201], v[150:153], v[118:121]
	v_mfma_f32_16x16x32_bf16 v[94:97], v[206:209], v[150:153], v[94:97]
	v_mfma_f32_16x16x32_bf16 v[106:109], v[198:201], v[172:175], v[106:109]
	v_mfma_f32_16x16x32_bf16 v[90:93], v[206:209], v[172:175], v[90:93]
	v_mfma_f32_16x16x32_bf16 v[102:105], v[198:201], v[180:183], v[102:105]
	v_mfma_f32_16x16x32_bf16 v[82:85], v[206:209], v[180:183], v[82:85]
	v_mfma_f32_16x16x32_bf16 v[98:101], v[198:201], v[190:193], v[98:101]
	v_mfma_f32_16x16x32_bf16 v[86:89], v[206:209], v[190:193], v[86:89]
	s_mov_b32 m0, s43
	s_mov_b64 s[100:101], s[92:93]
	s_barrier
	ds_read_b128 v[146:149], v253 offset:16384
	ds_read_b128 v[150:153], v253 offset:17408
	ds_read_b128 v[168:171], v253 offset:18432
	ds_read_b128 v[172:175], v253 offset:19456
	ds_read_b128 v[176:179], v253 offset:20480
	ds_read_b128 v[180:183], v253 offset:21504
	ds_read_b128 v[184:187], v253 offset:22528
	global_load_lds_dwordx4 v162, s[100:101]
	s_mov_b32 m0, s60
	ds_read_b128 v[190:193], v253 offset:23552
	global_load_lds_dwordx4 v158, s[100:101]
	s_waitcnt vmcnt(10)
	s_barrier
	s_waitcnt lgkmcnt(0)
	v_mfma_f32_16x16x32_bf16 v[62:65], v[130:133], v[146:149], 0
	v_mfma_f32_16x16x32_bf16 v[10:13], v[138:141], v[146:149], 0
	v_mfma_f32_16x16x32_bf16 v[58:61], v[130:133], v[168:171], 0
	v_mfma_f32_16x16x32_bf16 v[14:17], v[138:141], v[168:171], 0
	v_mfma_f32_16x16x32_bf16 v[54:57], v[130:133], v[176:179], 0
	v_mfma_f32_16x16x32_bf16 v[6:9], v[138:141], v[176:179], 0
	v_mfma_f32_16x16x32_bf16 v[42:45], v[130:133], v[184:187], 0
	v_mfma_f32_16x16x32_bf16 v[2:5], v[138:141], v[184:187], 0
	v_mfma_f32_16x16x32_bf16 v[62:65], v[134:137], v[150:153], v[62:65]
	v_mfma_f32_16x16x32_bf16 v[10:13], v[142:145], v[150:153], v[10:13]
	v_mfma_f32_16x16x32_bf16 v[58:61], v[134:137], v[172:175], v[58:61]
	v_mfma_f32_16x16x32_bf16 v[14:17], v[142:145], v[172:175], v[14:17]
	v_mfma_f32_16x16x32_bf16 v[54:57], v[134:137], v[180:183], v[54:57]
	v_mfma_f32_16x16x32_bf16 v[6:9], v[142:145], v[180:183], v[6:9]
	v_mfma_f32_16x16x32_bf16 v[42:45], v[134:137], v[190:193], v[42:45]
	v_mfma_f32_16x16x32_bf16 v[2:5], v[142:145], v[190:193], v[2:5]
	s_barrier
	s_add_u32 s6, s90, 0x40000
	s_addc_u32 s7, s91, 0
	s_add_i32 m0, s39, 0x14000
	s_nop 0
	global_load_lds_dwordx4 v160, s[6:7]
	s_add_i32 m0, s39, 0x16000
	s_nop 0
	global_load_lds_dwordx4 v156, s[6:7]
	ds_read_b128 v[130:133], v189 offset:32768
	ds_read_b128 v[134:137], v189 offset:33792
	ds_read_b128 v[138:141], v189 offset:34816
	ds_read_b128 v[142:145], v189 offset:35840
	s_waitcnt vmcnt(6)
	s_barrier
	v_mfma_f32_16x16x32_bf16 v[50:53], v[194:197], v[146:149], 0
	v_mfma_f32_16x16x32_bf16 v[26:29], v[202:205], v[146:149], 0
	v_mfma_f32_16x16x32_bf16 v[46:49], v[194:197], v[168:171], 0
	v_mfma_f32_16x16x32_bf16 v[30:33], v[202:205], v[168:171], 0
	v_mfma_f32_16x16x32_bf16 v[38:41], v[194:197], v[176:179], 0
	v_mfma_f32_16x16x32_bf16 v[22:25], v[202:205], v[176:179], 0
	v_mfma_f32_16x16x32_bf16 v[34:37], v[194:197], v[184:187], 0
	v_mfma_f32_16x16x32_bf16 v[18:21], v[202:205], v[184:187], 0
	v_mfma_f32_16x16x32_bf16 v[50:53], v[198:201], v[150:153], v[50:53]
	v_mfma_f32_16x16x32_bf16 v[26:29], v[206:209], v[150:153], v[26:29]
	v_mfma_f32_16x16x32_bf16 v[46:49], v[198:201], v[172:175], v[46:49]
	v_mfma_f32_16x16x32_bf16 v[30:33], v[206:209], v[172:175], v[30:33]
	v_mfma_f32_16x16x32_bf16 v[38:41], v[198:201], v[180:183], v[38:41]
	v_mfma_f32_16x16x32_bf16 v[22:25], v[206:209], v[180:183], v[22:25]
	v_mfma_f32_16x16x32_bf16 v[34:37], v[198:201], v[190:193], v[34:37]
	v_mfma_f32_16x16x32_bf16 v[18:21], v[206:209], v[190:193], v[18:21]
	s_barrier
	s_add_u32 s6, s92, 0x40000
	s_addc_u32 s7, s93, 0
	s_mov_b32 m0, s61
	ds_read_b128 v[146:149], v253 offset:32768
	ds_read_b128 v[150:153], v253 offset:33792
	ds_read_b128 v[168:171], v253 offset:34816
	ds_read_b128 v[172:175], v253 offset:35840
	ds_read_b128 v[176:179], v253 offset:36864
	ds_read_b128 v[180:183], v253 offset:37888
	ds_read_b128 v[184:187], v253 offset:38912
	global_load_lds_dwordx4 v162, s[6:7]
	s_mov_b32 m0, s72
	ds_read_b128 v[190:193], v253 offset:39936
	global_load_lds_dwordx4 v158, s[6:7]
	s_waitcnt lgkmcnt(8)
	s_barrier
	s_waitcnt lgkmcnt(0)
	v_mfma_f32_16x16x32_bf16 v[126:129], v[130:133], v[146:149], v[126:129]
	v_mfma_f32_16x16x32_bf16 v[70:73], v[138:141], v[146:149], v[70:73]
	v_mfma_f32_16x16x32_bf16 v[122:125], v[130:133], v[168:171], v[122:125]
	v_mfma_f32_16x16x32_bf16 v[74:77], v[138:141], v[168:171], v[74:77]
	v_mfma_f32_16x16x32_bf16 v[114:117], v[130:133], v[176:179], v[114:117]
	v_mfma_f32_16x16x32_bf16 v[66:69], v[138:141], v[176:179], v[66:69]
	v_mfma_f32_16x16x32_bf16 v[110:113], v[130:133], v[184:187], v[110:113]
	v_mfma_f32_16x16x32_bf16 v[78:81], v[138:141], v[184:187], v[78:81]
	v_mfma_f32_16x16x32_bf16 v[126:129], v[134:137], v[150:153], v[126:129]
	v_mfma_f32_16x16x32_bf16 v[70:73], v[142:145], v[150:153], v[70:73]
	v_mfma_f32_16x16x32_bf16 v[122:125], v[134:137], v[172:175], v[122:125]
	v_mfma_f32_16x16x32_bf16 v[74:77], v[142:145], v[172:175], v[74:77]
	v_mfma_f32_16x16x32_bf16 v[114:117], v[134:137], v[180:183], v[114:117]
	v_mfma_f32_16x16x32_bf16 v[66:69], v[142:145], v[180:183], v[66:69]
	v_mfma_f32_16x16x32_bf16 v[110:113], v[134:137], v[190:193], v[110:113]
	v_mfma_f32_16x16x32_bf16 v[78:81], v[142:145], v[190:193], v[78:81]
	s_barrier
	s_add_i32 m0, s39, 0x18000
	ds_read_b128 v[194:197], v189 offset:49152
	ds_read_b128 v[198:201], v189 offset:50176
	ds_read_b128 v[202:205], v189 offset:51200
	ds_read_b128 v[206:209], v189 offset:52224
	s_add_u32 s98, s90, s40
	s_addc_u32 s99, s91, s41
	global_load_lds_dwordx4 v160, s[98:99]
	s_add_i32 m0, s39, 0x1a000
	s_nop 0
	global_load_lds_dwordx4 v156, s[98:99]
	s_barrier
	s_waitcnt lgkmcnt(0)
	v_mfma_f32_16x16x32_bf16 v[118:121], v[194:197], v[146:149], v[118:121]
	v_mfma_f32_16x16x32_bf16 v[94:97], v[202:205], v[146:149], v[94:97]
	v_mfma_f32_16x16x32_bf16 v[106:109], v[194:197], v[168:171], v[106:109]
	v_mfma_f32_16x16x32_bf16 v[90:93], v[202:205], v[168:171], v[90:93]
	v_mfma_f32_16x16x32_bf16 v[102:105], v[194:197], v[176:179], v[102:105]
	v_mfma_f32_16x16x32_bf16 v[82:85], v[202:205], v[176:179], v[82:85]
	v_mfma_f32_16x16x32_bf16 v[98:101], v[194:197], v[184:187], v[98:101]
	v_mfma_f32_16x16x32_bf16 v[86:89], v[202:205], v[184:187], v[86:89]
	v_mfma_f32_16x16x32_bf16 v[118:121], v[198:201], v[150:153], v[118:121]
	v_mfma_f32_16x16x32_bf16 v[94:97], v[206:209], v[150:153], v[94:97]
	v_mfma_f32_16x16x32_bf16 v[106:109], v[198:201], v[172:175], v[106:109]
	v_mfma_f32_16x16x32_bf16 v[90:93], v[206:209], v[172:175], v[90:93]
	v_mfma_f32_16x16x32_bf16 v[102:105], v[198:201], v[180:183], v[102:105]
	v_mfma_f32_16x16x32_bf16 v[82:85], v[206:209], v[180:183], v[82:85]
	v_mfma_f32_16x16x32_bf16 v[98:101], v[198:201], v[190:193], v[98:101]
	v_mfma_f32_16x16x32_bf16 v[86:89], v[206:209], v[190:193], v[86:89]
	s_mov_b32 m0, s95
	s_barrier
	ds_read_b128 v[146:149], v253 offset:49152
	ds_read_b128 v[150:153], v253 offset:50176
	ds_read_b128 v[168:171], v253 offset:51200
	ds_read_b128 v[172:175], v253 offset:52224
	ds_read_b128 v[176:179], v253 offset:53248
	ds_read_b128 v[180:183], v253 offset:54272
	ds_read_b128 v[184:187], v253 offset:55296
	ds_read_b128 v[190:193], v253 offset:56320
	s_add_u32 s98, s100, s40
	s_addc_u32 s99, s101, s41
	global_load_lds_dwordx4 v162, s[98:99]
	s_mov_b32 m0, s96
	s_nop 0
	global_load_lds_dwordx4 v158, s[98:99]
	s_waitcnt vmcnt(10)
	s_barrier
	s_waitcnt lgkmcnt(0)
	v_mfma_f32_16x16x32_bf16 v[62:65], v[130:133], v[146:149], v[62:65]
	v_mfma_f32_16x16x32_bf16 v[10:13], v[138:141], v[146:149], v[10:13]
	v_mfma_f32_16x16x32_bf16 v[58:61], v[130:133], v[168:171], v[58:61]
	v_mfma_f32_16x16x32_bf16 v[14:17], v[138:141], v[168:171], v[14:17]
	v_mfma_f32_16x16x32_bf16 v[54:57], v[130:133], v[176:179], v[54:57]
	v_mfma_f32_16x16x32_bf16 v[6:9], v[138:141], v[176:179], v[6:9]
	v_mfma_f32_16x16x32_bf16 v[42:45], v[130:133], v[184:187], v[42:45]
	v_mfma_f32_16x16x32_bf16 v[2:5], v[138:141], v[184:187], v[2:5]
	v_mfma_f32_16x16x32_bf16 v[62:65], v[134:137], v[150:153], v[62:65]
	v_mfma_f32_16x16x32_bf16 v[10:13], v[142:145], v[150:153], v[10:13]
	v_mfma_f32_16x16x32_bf16 v[58:61], v[134:137], v[172:175], v[58:61]
	v_mfma_f32_16x16x32_bf16 v[14:17], v[142:145], v[172:175], v[14:17]
	v_mfma_f32_16x16x32_bf16 v[54:57], v[134:137], v[180:183], v[54:57]
	v_mfma_f32_16x16x32_bf16 v[6:9], v[142:145], v[180:183], v[6:9]
	v_mfma_f32_16x16x32_bf16 v[42:45], v[134:137], v[190:193], v[42:45]
	v_mfma_f32_16x16x32_bf16 v[2:5], v[142:145], v[190:193], v[2:5]
	s_barrier
	s_add_u32 s6, s90, 0x40080
	s_addc_u32 s7, s91, 0
	s_add_i32 m0, s39, 0x1c000
	s_nop 0
	global_load_lds_dwordx4 v160, s[6:7]
	s_add_i32 m0, s39, 0x1e000
	s_nop 0
	global_load_lds_dwordx4 v156, s[6:7]
	ds_read_b128 v[130:133], v189
	ds_read_b128 v[134:137], v189 offset:1024
	ds_read_b128 v[138:141], v189 offset:2048
	ds_read_b128 v[142:145], v189 offset:3072
	s_waitcnt vmcnt(6)
	s_barrier
	v_mfma_f32_16x16x32_bf16 v[50:53], v[194:197], v[146:149], v[50:53]
	v_mfma_f32_16x16x32_bf16 v[26:29], v[202:205], v[146:149], v[26:29]
	v_mfma_f32_16x16x32_bf16 v[46:49], v[194:197], v[168:171], v[46:49]
	v_mfma_f32_16x16x32_bf16 v[30:33], v[202:205], v[168:171], v[30:33]
	v_mfma_f32_16x16x32_bf16 v[38:41], v[194:197], v[176:179], v[38:41]
	v_mfma_f32_16x16x32_bf16 v[22:25], v[202:205], v[176:179], v[22:25]
	v_mfma_f32_16x16x32_bf16 v[34:37], v[194:197], v[184:187], v[34:37]
	v_mfma_f32_16x16x32_bf16 v[18:21], v[202:205], v[184:187], v[18:21]
	v_mfma_f32_16x16x32_bf16 v[50:53], v[198:201], v[150:153], v[50:53]
	s_add_i32 s45, s45, 2
	s_add_u32 s28, s28, 0x100
	v_mfma_f32_16x16x32_bf16 v[26:29], v[206:209], v[150:153], v[26:29]
	s_addc_u32 s29, s29, 0
	s_mov_b64 s[6:7], s[88:89]
	v_mfma_f32_16x16x32_bf16 v[46:49], v[198:201], v[172:175], v[46:49]
	s_add_u32 s88, s6, 0x100
	s_addc_u32 s89, s7, 0
	v_mfma_f32_16x16x32_bf16 v[30:33], v[206:209], v[172:175], v[30:33]
	s_cmp_eq_u32 s45, 12
	s_cselect_b32 s93, s17, s89
	v_mfma_f32_16x16x32_bf16 v[38:41], v[198:201], v[180:183], v[38:41]
	s_cselect_b32 s92, s22, s88
	s_cselect_b32 s91, s15, s29
	v_mfma_f32_16x16x32_bf16 v[22:25], v[206:209], v[180:183], v[22:25]
	s_cselect_b32 s90, s23, s28
	s_cmp_gt_u32 s45, 13
	v_mfma_f32_16x16x32_bf16 v[34:37], v[198:201], v[190:193], v[34:37]
	v_mfma_f32_16x16x32_bf16 v[18:21], v[206:209], v[190:193], v[18:21]
	s_barrier
	.p2align 3
.LBB0_919:
	s_add_i32 m0, s43, 0xc000
	ds_read_b128 v[146:149], v253
	ds_read_b128 v[150:153], v253 offset:1024
	ds_read_b128 v[168:171], v253 offset:2048
	ds_read_b128 v[172:175], v253 offset:3072
	ds_read_b128 v[176:179], v253 offset:4096
	ds_read_b128 v[180:183], v253 offset:5120
	ds_read_b128 v[184:187], v253 offset:6144
	ds_read_b128 v[190:193], v253 offset:7168
	global_load_lds_dwordx4 v164, s[6:7]
	s_add_i32 m0, s43, 0xe000
	v_lshl_add_u64 v[154:155], s[6:7], 0, v[166:167]
	global_load_lds_dwordx4 v[154:155], off
	s_waitcnt lgkmcnt(8)
	s_barrier
	s_waitcnt lgkmcnt(0)
	v_mfma_f32_16x16x32_bf16 v[126:129], v[130:133], v[146:149], v[126:129]
	v_mfma_f32_16x16x32_bf16 v[70:73], v[138:141], v[146:149], v[70:73]
	v_mfma_f32_16x16x32_bf16 v[122:125], v[130:133], v[168:171], v[122:125]
	v_mfma_f32_16x16x32_bf16 v[74:77], v[138:141], v[168:171], v[74:77]
	v_mfma_f32_16x16x32_bf16 v[114:117], v[130:133], v[176:179], v[114:117]
	v_mfma_f32_16x16x32_bf16 v[66:69], v[138:141], v[176:179], v[66:69]
	v_mfma_f32_16x16x32_bf16 v[110:113], v[130:133], v[184:187], v[110:113]
	v_mfma_f32_16x16x32_bf16 v[78:81], v[138:141], v[184:187], v[78:81]
	v_mfma_f32_16x16x32_bf16 v[126:129], v[134:137], v[150:153], v[126:129]
	v_mfma_f32_16x16x32_bf16 v[70:73], v[142:145], v[150:153], v[70:73]
	v_mfma_f32_16x16x32_bf16 v[122:125], v[134:137], v[172:175], v[122:125]
	v_mfma_f32_16x16x32_bf16 v[74:77], v[142:145], v[172:175], v[74:77]
	v_mfma_f32_16x16x32_bf16 v[114:117], v[134:137], v[180:183], v[114:117]
	v_mfma_f32_16x16x32_bf16 v[66:69], v[142:145], v[180:183], v[66:69]
	v_mfma_f32_16x16x32_bf16 v[110:113], v[134:137], v[190:193], v[110:113]
	v_mfma_f32_16x16x32_bf16 v[78:81], v[142:145], v[190:193], v[78:81]
	s_barrier
	s_add_i32 m0, s39, 0x10000
	ds_read_b128 v[194:197], v189 offset:16384
	ds_read_b128 v[198:201], v189 offset:17408
	ds_read_b128 v[202:205], v189 offset:18432
	global_load_lds_dwordx4 v160, s[90:91]
	s_add_i32 m0, s39, 0x12000
	ds_read_b128 v[206:209], v189 offset:19456
	global_load_lds_dwordx4 v156, s[90:91]
	s_barrier
	s_waitcnt lgkmcnt(0)
	v_mfma_f32_16x16x32_bf16 v[118:121], v[194:197], v[146:149], v[118:121]
	v_mfma_f32_16x16x32_bf16 v[94:97], v[202:205], v[146:149], v[94:97]
	v_mfma_f32_16x16x32_bf16 v[106:109], v[194:197], v[168:171], v[106:109]
	v_mfma_f32_16x16x32_bf16 v[90:93], v[202:205], v[168:171], v[90:93]
	v_mfma_f32_16x16x32_bf16 v[102:105], v[194:197], v[176:179], v[102:105]
	v_mfma_f32_16x16x32_bf16 v[82:85], v[202:205], v[176:179], v[82:85]
	v_mfma_f32_16x16x32_bf16 v[98:101], v[194:197], v[184:187], v[98:101]
	v_mfma_f32_16x16x32_bf16 v[86:89], v[202:205], v[184:187], v[86:89]
	v_mfma_f32_16x16x32_bf16 v[118:121], v[198:201], v[150:153], v[118:121]
	v_mfma_f32_16x16x32_bf16 v[94:97], v[206:209], v[150:153], v[94:97]
	v_mfma_f32_16x16x32_bf16 v[106:109], v[198:201], v[172:175], v[106:109]
	v_mfma_f32_16x16x32_bf16 v[90:93], v[206:209], v[172:175], v[90:93]
	v_mfma_f32_16x16x32_bf16 v[102:105], v[198:201], v[180:183], v[102:105]
	v_mfma_f32_16x16x32_bf16 v[82:85], v[206:209], v[180:183], v[82:85]
	v_mfma_f32_16x16x32_bf16 v[98:101], v[198:201], v[190:193], v[98:101]
	v_mfma_f32_16x16x32_bf16 v[86:89], v[206:209], v[190:193], v[86:89]
	s_mov_b32 m0, s43
	s_mov_b64 s[100:101], s[92:93]
	s_barrier
	ds_read_b128 v[146:149], v253 offset:16384
	ds_read_b128 v[150:153], v253 offset:17408
	ds_read_b128 v[168:171], v253 offset:18432
	ds_read_b128 v[172:175], v253 offset:19456
	ds_read_b128 v[176:179], v253 offset:20480
	ds_read_b128 v[180:183], v253 offset:21504
	ds_read_b128 v[184:187], v253 offset:22528
	global_load_lds_dwordx4 v162, s[100:101]
	s_mov_b32 m0, s60
	ds_read_b128 v[190:193], v253 offset:23552
	global_load_lds_dwordx4 v158, s[100:101]
	s_waitcnt vmcnt(10)
	s_barrier
	s_waitcnt lgkmcnt(0)
	v_mfma_f32_16x16x32_bf16 v[62:65], v[130:133], v[146:149], v[62:65]
	v_mfma_f32_16x16x32_bf16 v[10:13], v[138:141], v[146:149], v[10:13]
	v_mfma_f32_16x16x32_bf16 v[58:61], v[130:133], v[168:171], v[58:61]
	v_mfma_f32_16x16x32_bf16 v[14:17], v[138:141], v[168:171], v[14:17]
	v_mfma_f32_16x16x32_bf16 v[54:57], v[130:133], v[176:179], v[54:57]
	v_mfma_f32_16x16x32_bf16 v[6:9], v[138:141], v[176:179], v[6:9]
	v_mfma_f32_16x16x32_bf16 v[42:45], v[130:133], v[184:187], v[42:45]
	v_mfma_f32_16x16x32_bf16 v[2:5], v[138:141], v[184:187], v[2:5]
	v_mfma_f32_16x16x32_bf16 v[62:65], v[134:137], v[150:153], v[62:65]
	v_mfma_f32_16x16x32_bf16 v[10:13], v[142:145], v[150:153], v[10:13]
	v_mfma_f32_16x16x32_bf16 v[58:61], v[134:137], v[172:175], v[58:61]
	v_mfma_f32_16x16x32_bf16 v[14:17], v[142:145], v[172:175], v[14:17]
	v_mfma_f32_16x16x32_bf16 v[54:57], v[134:137], v[180:183], v[54:57]
	v_mfma_f32_16x16x32_bf16 v[6:9], v[142:145], v[180:183], v[6:9]
	v_mfma_f32_16x16x32_bf16 v[42:45], v[134:137], v[190:193], v[42:45]
	v_mfma_f32_16x16x32_bf16 v[2:5], v[142:145], v[190:193], v[2:5]
	s_barrier
	s_add_u32 s6, s90, 0x40000
	s_addc_u32 s7, s91, 0
	s_add_i32 m0, s39, 0x14000
	s_nop 0
	global_load_lds_dwordx4 v160, s[6:7]
	s_add_i32 m0, s39, 0x16000
	s_nop 0
	global_load_lds_dwordx4 v156, s[6:7]
	ds_read_b128 v[130:133], v189 offset:32768
	ds_read_b128 v[134:137], v189 offset:33792
	ds_read_b128 v[138:141], v189 offset:34816
	ds_read_b128 v[142:145], v189 offset:35840
	s_waitcnt vmcnt(6)
	s_barrier
	v_mfma_f32_16x16x32_bf16 v[50:53], v[194:197], v[146:149], v[50:53]
	v_mfma_f32_16x16x32_bf16 v[26:29], v[202:205], v[146:149], v[26:29]
	v_mfma_f32_16x16x32_bf16 v[46:49], v[194:197], v[168:171], v[46:49]
	v_mfma_f32_16x16x32_bf16 v[30:33], v[202:205], v[168:171], v[30:33]
	v_mfma_f32_16x16x32_bf16 v[38:41], v[194:197], v[176:179], v[38:41]
	v_mfma_f32_16x16x32_bf16 v[22:25], v[202:205], v[176:179], v[22:25]
	v_mfma_f32_16x16x32_bf16 v[34:37], v[194:197], v[184:187], v[34:37]
	v_mfma_f32_16x16x32_bf16 v[18:21], v[202:205], v[184:187], v[18:21]
	v_mfma_f32_16x16x32_bf16 v[50:53], v[198:201], v[150:153], v[50:53]
	v_mfma_f32_16x16x32_bf16 v[26:29], v[206:209], v[150:153], v[26:29]
	v_mfma_f32_16x16x32_bf16 v[46:49], v[198:201], v[172:175], v[46:49]
	v_mfma_f32_16x16x32_bf16 v[30:33], v[206:209], v[172:175], v[30:33]
	v_mfma_f32_16x16x32_bf16 v[38:41], v[198:201], v[180:183], v[38:41]
	v_mfma_f32_16x16x32_bf16 v[22:25], v[206:209], v[180:183], v[22:25]
	v_mfma_f32_16x16x32_bf16 v[34:37], v[198:201], v[190:193], v[34:37]
	v_mfma_f32_16x16x32_bf16 v[18:21], v[206:209], v[190:193], v[18:21]
	s_barrier
	s_add_u32 s6, s92, 0x40000
	s_addc_u32 s7, s93, 0
	s_mov_b32 m0, s61
	ds_read_b128 v[146:149], v253 offset:32768
	ds_read_b128 v[150:153], v253 offset:33792
	ds_read_b128 v[168:171], v253 offset:34816
	ds_read_b128 v[172:175], v253 offset:35840
	ds_read_b128 v[176:179], v253 offset:36864
	ds_read_b128 v[180:183], v253 offset:37888
	ds_read_b128 v[184:187], v253 offset:38912
	global_load_lds_dwordx4 v162, s[6:7]
	s_mov_b32 m0, s72
	ds_read_b128 v[190:193], v253 offset:39936
	global_load_lds_dwordx4 v158, s[6:7]
	s_waitcnt lgkmcnt(8)
	s_barrier
	s_waitcnt lgkmcnt(0)
	v_mfma_f32_16x16x32_bf16 v[126:129], v[130:133], v[146:149], v[126:129]
	v_mfma_f32_16x16x32_bf16 v[70:73], v[138:141], v[146:149], v[70:73]
	v_mfma_f32_16x16x32_bf16 v[122:125], v[130:133], v[168:171], v[122:125]
	v_mfma_f32_16x16x32_bf16 v[74:77], v[138:141], v[168:171], v[74:77]
	v_mfma_f32_16x16x32_bf16 v[114:117], v[130:133], v[176:179], v[114:117]
	v_mfma_f32_16x16x32_bf16 v[66:69], v[138:141], v[176:179], v[66:69]
	v_mfma_f32_16x16x32_bf16 v[110:113], v[130:133], v[184:187], v[110:113]
	v_mfma_f32_16x16x32_bf16 v[78:81], v[138:141], v[184:187], v[78:81]
	v_mfma_f32_16x16x32_bf16 v[126:129], v[134:137], v[150:153], v[126:129]
	v_mfma_f32_16x16x32_bf16 v[70:73], v[142:145], v[150:153], v[70:73]
	v_mfma_f32_16x16x32_bf16 v[122:125], v[134:137], v[172:175], v[122:125]
	v_mfma_f32_16x16x32_bf16 v[74:77], v[142:145], v[172:175], v[74:77]
	v_mfma_f32_16x16x32_bf16 v[114:117], v[134:137], v[180:183], v[114:117]
	v_mfma_f32_16x16x32_bf16 v[66:69], v[142:145], v[180:183], v[66:69]
	v_mfma_f32_16x16x32_bf16 v[110:113], v[134:137], v[190:193], v[110:113]
	v_mfma_f32_16x16x32_bf16 v[78:81], v[142:145], v[190:193], v[78:81]
	s_barrier
	s_add_i32 m0, s39, 0x18000
	ds_read_b128 v[194:197], v189 offset:49152
	ds_read_b128 v[198:201], v189 offset:50176
	ds_read_b128 v[202:205], v189 offset:51200
	ds_read_b128 v[206:209], v189 offset:52224
	s_add_u32 s98, s90, s40
	s_addc_u32 s99, s91, s41
	global_load_lds_dwordx4 v160, s[98:99]
	s_add_i32 m0, s39, 0x1a000
	s_nop 0
	global_load_lds_dwordx4 v156, s[98:99]
	s_barrier
	s_waitcnt lgkmcnt(0)
	v_mfma_f32_16x16x32_bf16 v[118:121], v[194:197], v[146:149], v[118:121]
	v_mfma_f32_16x16x32_bf16 v[94:97], v[202:205], v[146:149], v[94:97]
	v_mfma_f32_16x16x32_bf16 v[106:109], v[194:197], v[168:171], v[106:109]
	v_mfma_f32_16x16x32_bf16 v[90:93], v[202:205], v[168:171], v[90:93]
	v_mfma_f32_16x16x32_bf16 v[102:105], v[194:197], v[176:179], v[102:105]
	v_mfma_f32_16x16x32_bf16 v[82:85], v[202:205], v[176:179], v[82:85]
	v_mfma_f32_16x16x32_bf16 v[98:101], v[194:197], v[184:187], v[98:101]
	v_mfma_f32_16x16x32_bf16 v[86:89], v[202:205], v[184:187], v[86:89]
	v_mfma_f32_16x16x32_bf16 v[118:121], v[198:201], v[150:153], v[118:121]
	v_mfma_f32_16x16x32_bf16 v[94:97], v[206:209], v[150:153], v[94:97]
	v_mfma_f32_16x16x32_bf16 v[106:109], v[198:201], v[172:175], v[106:109]
	v_mfma_f32_16x16x32_bf16 v[90:93], v[206:209], v[172:175], v[90:93]
	v_mfma_f32_16x16x32_bf16 v[102:105], v[198:201], v[180:183], v[102:105]
	v_mfma_f32_16x16x32_bf16 v[82:85], v[206:209], v[180:183], v[82:85]
	v_mfma_f32_16x16x32_bf16 v[98:101], v[198:201], v[190:193], v[98:101]
	v_mfma_f32_16x16x32_bf16 v[86:89], v[206:209], v[190:193], v[86:89]
	s_mov_b32 m0, s95
	s_barrier
	ds_read_b128 v[146:149], v253 offset:49152
	ds_read_b128 v[150:153], v253 offset:50176
	ds_read_b128 v[168:171], v253 offset:51200
	ds_read_b128 v[172:175], v253 offset:52224
	ds_read_b128 v[176:179], v253 offset:53248
	ds_read_b128 v[180:183], v253 offset:54272
	ds_read_b128 v[184:187], v253 offset:55296
	ds_read_b128 v[190:193], v253 offset:56320
	s_add_u32 s98, s100, s40
	s_addc_u32 s99, s101, s41
	global_load_lds_dwordx4 v162, s[98:99]
	s_mov_b32 m0, s96
	s_nop 0
	global_load_lds_dwordx4 v158, s[98:99]
	s_waitcnt vmcnt(10)
	s_barrier
	s_waitcnt lgkmcnt(0)
	v_mfma_f32_16x16x32_bf16 v[62:65], v[130:133], v[146:149], v[62:65]
	v_mfma_f32_16x16x32_bf16 v[10:13], v[138:141], v[146:149], v[10:13]
	v_mfma_f32_16x16x32_bf16 v[58:61], v[130:133], v[168:171], v[58:61]
	v_mfma_f32_16x16x32_bf16 v[14:17], v[138:141], v[168:171], v[14:17]
	v_mfma_f32_16x16x32_bf16 v[54:57], v[130:133], v[176:179], v[54:57]
	v_mfma_f32_16x16x32_bf16 v[6:9], v[138:141], v[176:179], v[6:9]
	v_mfma_f32_16x16x32_bf16 v[42:45], v[130:133], v[184:187], v[42:45]
	v_mfma_f32_16x16x32_bf16 v[2:5], v[138:141], v[184:187], v[2:5]
	v_mfma_f32_16x16x32_bf16 v[62:65], v[134:137], v[150:153], v[62:65]
	v_mfma_f32_16x16x32_bf16 v[10:13], v[142:145], v[150:153], v[10:13]
	v_mfma_f32_16x16x32_bf16 v[58:61], v[134:137], v[172:175], v[58:61]
	v_mfma_f32_16x16x32_bf16 v[14:17], v[142:145], v[172:175], v[14:17]
	v_mfma_f32_16x16x32_bf16 v[54:57], v[134:137], v[180:183], v[54:57]
	v_mfma_f32_16x16x32_bf16 v[6:9], v[142:145], v[180:183], v[6:9]
	v_mfma_f32_16x16x32_bf16 v[42:45], v[134:137], v[190:193], v[42:45]
	v_mfma_f32_16x16x32_bf16 v[2:5], v[142:145], v[190:193], v[2:5]
	s_barrier
	s_add_u32 s6, s90, 0x40080
	s_addc_u32 s7, s91, 0
	s_add_i32 m0, s39, 0x1c000
	s_nop 0
	global_load_lds_dwordx4 v160, s[6:7]
	s_add_i32 m0, s39, 0x1e000
	s_nop 0
	global_load_lds_dwordx4 v156, s[6:7]
	ds_read_b128 v[130:133], v189
	ds_read_b128 v[134:137], v189 offset:1024
	ds_read_b128 v[138:141], v189 offset:2048
	ds_read_b128 v[142:145], v189 offset:3072
	s_waitcnt vmcnt(6)
	s_barrier
	v_mfma_f32_16x16x32_bf16 v[50:53], v[194:197], v[146:149], v[50:53]
	v_mfma_f32_16x16x32_bf16 v[26:29], v[202:205], v[146:149], v[26:29]
	v_mfma_f32_16x16x32_bf16 v[46:49], v[194:197], v[168:171], v[46:49]
	v_mfma_f32_16x16x32_bf16 v[30:33], v[202:205], v[168:171], v[30:33]
	v_mfma_f32_16x16x32_bf16 v[38:41], v[194:197], v[176:179], v[38:41]
	v_mfma_f32_16x16x32_bf16 v[22:25], v[202:205], v[176:179], v[22:25]
	v_mfma_f32_16x16x32_bf16 v[34:37], v[194:197], v[184:187], v[34:37]
	v_mfma_f32_16x16x32_bf16 v[18:21], v[202:205], v[184:187], v[18:21]
	v_mfma_f32_16x16x32_bf16 v[50:53], v[198:201], v[150:153], v[50:53]
	s_add_i32 s45, s45, 2
	s_add_u32 s28, s28, 0x100
	v_mfma_f32_16x16x32_bf16 v[26:29], v[206:209], v[150:153], v[26:29]
	s_addc_u32 s29, s29, 0
	s_mov_b64 s[6:7], s[88:89]
	v_mfma_f32_16x16x32_bf16 v[46:49], v[198:201], v[172:175], v[46:49]
	s_add_u32 s88, s6, 0x100
	s_addc_u32 s89, s7, 0
	v_mfma_f32_16x16x32_bf16 v[30:33], v[206:209], v[172:175], v[30:33]
	s_cmp_eq_u32 s45, 12
	s_cselect_b32 s93, s17, s89
	v_mfma_f32_16x16x32_bf16 v[38:41], v[198:201], v[180:183], v[38:41]
	s_cselect_b32 s92, s22, s88
	s_cselect_b32 s91, s15, s29
	v_mfma_f32_16x16x32_bf16 v[22:25], v[206:209], v[180:183], v[22:25]
	s_cselect_b32 s90, s23, s28
	s_cmp_gt_u32 s45, 13
	v_mfma_f32_16x16x32_bf16 v[34:37], v[198:201], v[190:193], v[34:37]
	v_mfma_f32_16x16x32_bf16 v[18:21], v[206:209], v[190:193], v[18:21]
	s_barrier
	s_cbranch_scc0 .LBB0_919
	s_waitcnt lgkmcnt(0)
	v_mov_b32_e32 v131, v252
	s_lshl_b32 s88, s5, 7
	v_bfe_u32 v130, v131, 4, 2
	v_and_b32_e32 v134, 15, v131
	v_lshlrev_b32_e32 v0, 4, v130
	s_ashr_i32 s89, s88, 31
	s_lshl_b32 s15, s4, 8
	v_or3_b32 v135, v0, s97, v134
	s_lshl_b64 s[4:5], s[88:89], 2
	v_lshrrev_b32_e32 v140, 1, v135
	s_add_u32 s4, s73, s4
	s_addc_u32 s5, s74, s5
	v_lshlrev_b32_e32 v0, 2, v140
	v_and_b32_e32 v144, 1, v131
	v_lshl_add_u64 v[132:133], s[4:5], 0, v[0:1]
	v_cmp_eq_u32_e32 vcc, 1, v144
	v_mov_b32_e32 v0, 0xb00
	s_movk_i32 s4, 0x5000
	v_cndmask_b32_e32 v141, 0, v0, vcc
	v_lshlrev_b32_e32 v0, 2, v141
	v_lshl_add_u64 v[132:133], v[132:133], 0, v[0:1]
	v_add_co_u32_e32 v138, vcc, s4, v132
	s_mov_b32 s4, 0xb000
	s_nop 0
	v_addc_co_u32_e32 v139, vcc, 0, v133, vcc
	global_load_dword v136, v[132:133], off
	global_load_dword v137, v[138:139], off offset:2048
	v_add_co_u32_e32 v132, vcc, s4, v132
	v_add_u32_e32 v0, s88, v141
	s_nop 0
	v_addc_co_u32_e32 v133, vcc, 0, v133, vcc
	global_load_dword v138, v[132:133], off
	v_or_b32_e32 v132, v140, v0
	v_ashrrev_i32_e32 v133, 31, v132
	v_lshl_add_u64 v[132:133], v[132:133], 2, s[12:13]
	global_load_dword v139, v[132:133], off
	v_lshl_add_u32 v152, v135, 4, s78
	v_and_b32_e32 v135, 63, v131
	v_cmp_eq_u32_e32 vcc, 0, v144
	v_or_b32_e32 v0, s97, v135
	v_lshrrev_b32_e32 v0, 1, v0
	v_and_or_b32 v131, v0, 63, s55
	v_add_u32_e32 v132, s15, v131
	v_ashrrev_i32_e32 v133, 31, v132
	v_lshlrev_b64 v[132:133], 6, v[132:133]
	v_lshl_add_u64 v[132:133], s[10:11], 0, v[132:133]
	v_lshlrev_b32_e32 v0, 5, v144
	v_lshl_add_u64 v[132:133], v[132:133], 0, v[0:1]
	global_load_dwordx4 v[148:151], v[132:133], off offset:16
	global_load_dwordx4 v[140:143], v[132:133], off
	s_waitcnt vmcnt(2)
	ds_write_b128 v152, v[136:139]
	s_waitcnt vmcnt(0)
	v_add_f32_e32 v133, v150, v151
	v_add_f32_e32 v0, v140, v141
	v_add_f32_e32 v132, v142, v143
	v_add_f32_e32 v0, v0, v132
	v_add_f32_e32 v132, v148, v149
	v_add_f32_e32 v132, v132, v133
	v_add_f32_e32 v0, v0, v132
	v_lshlrev_b32_e32 v132, 2, v135
	v_xor_b32_e32 v132, 4, v132
	ds_bpermute_b32 v132, v132, v0
	s_and_saveexec_b64 s[4:5], vcc
	s_cbranch_execz .LBB0_922
	s_waitcnt lgkmcnt(0)
	v_add_f32_e32 v0, v0, v132
	v_mov_b32_e32 v132, 0x358637bd
	v_fmamk_f32 v0, v0, 0x3a800000, v132
	s_mov_b32 s6, 0x800000
	v_mul_f32_e32 v132, 0x4b800000, v0
	v_cmp_gt_f32_e32 vcc, s6, v0
	v_lshl_add_u32 v131, v131, 2, 0
	v_add_u32_e32 v131, 0x20000, v131
	v_cndmask_b32_e32 v0, v0, v132, vcc
	v_rsq_f32_e32 v0, v0
	s_nop 0
	v_mul_f32_e32 v132, 0x45800000, v0
	v_cndmask_b32_e32 v0, v0, v132, vcc
	ds_write_b32 v131, v0

.LBB0_1089:
	s_add_u32 s34, s84, 0x100
	s_addc_u32 s78, s85, 0
	s_mov_b32 s79, -2
	s_waitcnt lgkmcnt(0)
	s_add_i32 s90, 0, 0x10000
	v_add_u32_e32 v142, s90, v212
	v_add_u32_e32 v189, 0x10000, v212
	ds_read_b128 v[130:133], v142
	ds_read_b128 v[134:137], v142 offset:1024
	ds_read_b128 v[138:141], v142 offset:2048
	ds_read_b128 v[142:145], v142 offset:3072
	s_add_u32 s84, s16, 0x100
	s_addc_u32 s85, s17, 0
	s_cmp_eq_u32 s79, 40
	s_cselect_b32 s89, s5, s85
	s_cselect_b32 s88, s4, s84
	s_cselect_b32 s87, s7, s78
	s_cselect_b32 s86, s6, s34
	v_lshl_add_u64 v[178:179], s[16:17], 0, v[196:197]
	s_add_i32 m0, s39, 0xc000
	ds_read_b128 v[146:149], v213
	ds_read_b128 v[150:153], v213 offset:1024
	ds_read_b128 v[154:157], v213 offset:2048
	ds_read_b128 v[158:161], v213 offset:3072
	ds_read_b128 v[162:165], v213 offset:4096
	ds_read_b128 v[166:169], v213 offset:5120
	ds_read_b128 v[170:173], v213 offset:6144
	ds_read_b128 v[174:177], v213 offset:7168
	global_load_lds_dwordx4 v[178:179], off
	s_add_i32 m0, s39, 0xe000
	v_lshl_add_u64 v[178:179], s[16:17], 0, v[198:199]
	global_load_lds_dwordx4 v[178:179], off
	s_waitcnt lgkmcnt(8)
	s_barrier
	s_waitcnt lgkmcnt(0)
	v_mfma_f32_16x16x32_bf16 v[126:129], v[130:133], v[146:149], 0
	v_mfma_f32_16x16x32_bf16 v[122:125], v[138:141], v[146:149], 0
	v_mfma_f32_16x16x32_bf16 v[110:113], v[130:133], v[154:157], 0
	v_mfma_f32_16x16x32_bf16 v[106:109], v[138:141], v[154:157], 0
	v_mfma_f32_16x16x32_bf16 v[94:97], v[130:133], v[162:165], 0
	v_mfma_f32_16x16x32_bf16 v[90:93], v[138:141], v[162:165], 0
	v_mfma_f32_16x16x32_bf16 v[78:81], v[130:133], v[170:173], 0
	v_mfma_f32_16x16x32_bf16 v[74:77], v[138:141], v[170:173], 0
	v_mfma_f32_16x16x32_bf16 v[126:129], v[134:137], v[150:153], v[126:129]
	v_mfma_f32_16x16x32_bf16 v[122:125], v[142:145], v[150:153], v[122:125]
	v_mfma_f32_16x16x32_bf16 v[110:113], v[134:137], v[158:161], v[110:113]
	v_mfma_f32_16x16x32_bf16 v[106:109], v[142:145], v[158:161], v[106:109]
	v_mfma_f32_16x16x32_bf16 v[94:97], v[134:137], v[166:169], v[94:97]
	v_mfma_f32_16x16x32_bf16 v[90:93], v[142:145], v[166:169], v[90:93]
	v_mfma_f32_16x16x32_bf16 v[78:81], v[134:137], v[174:177], v[78:81]
	v_mfma_f32_16x16x32_bf16 v[74:77], v[142:145], v[174:177], v[74:77]
	s_barrier
	ds_read_b128 v[178:181], v189 offset:16384
	ds_read_b128 v[182:185], v189 offset:17408
	ds_read_b128 v[200:203], v189 offset:18432
	ds_read_b128 v[204:207], v189 offset:19456
	s_add_i32 m0, s38, 0x10000
	s_nop 0
	global_load_lds_dwordx4 v0, s[86:87]
	s_add_i32 m0, s38, 0x12000
	s_nop 0
	global_load_lds_dwordx4 v194, s[86:87]
	s_barrier
	s_waitcnt lgkmcnt(0)
	v_mfma_f32_16x16x32_bf16 v[118:121], v[178:181], v[146:149], 0
	v_mfma_f32_16x16x32_bf16 v[114:117], v[200:203], v[146:149], 0
	v_mfma_f32_16x16x32_bf16 v[102:105], v[178:181], v[154:157], 0
	v_mfma_f32_16x16x32_bf16 v[98:101], v[200:203], v[154:157], 0
	v_mfma_f32_16x16x32_bf16 v[86:89], v[178:181], v[162:165], 0
	v_mfma_f32_16x16x32_bf16 v[82:85], v[200:203], v[162:165], 0
	v_mfma_f32_16x16x32_bf16 v[70:73], v[178:181], v[170:173], 0
	v_mfma_f32_16x16x32_bf16 v[66:69], v[200:203], v[170:173], 0
	v_mfma_f32_16x16x32_bf16 v[118:121], v[182:185], v[150:153], v[118:121]
	v_mfma_f32_16x16x32_bf16 v[114:117], v[204:207], v[150:153], v[114:117]
	v_mfma_f32_16x16x32_bf16 v[102:105], v[182:185], v[158:161], v[102:105]
	v_mfma_f32_16x16x32_bf16 v[98:101], v[204:207], v[158:161], v[98:101]
	v_mfma_f32_16x16x32_bf16 v[86:89], v[182:185], v[166:169], v[86:89]
	v_mfma_f32_16x16x32_bf16 v[82:85], v[204:207], v[166:169], v[82:85]
	v_mfma_f32_16x16x32_bf16 v[70:73], v[182:185], v[174:177], v[70:73]
	v_mfma_f32_16x16x32_bf16 v[66:69], v[204:207], v[174:177], v[66:69]
	s_mov_b32 m0, s39
	s_mov_b64 s[100:101], s[88:89]
	s_barrier
	ds_read_b128 v[146:149], v213 offset:16384
	ds_read_b128 v[150:153], v213 offset:17408
	ds_read_b128 v[154:157], v213 offset:18432
	ds_read_b128 v[158:161], v213 offset:19456
	ds_read_b128 v[162:165], v213 offset:20480
	ds_read_b128 v[166:169], v213 offset:21504
	ds_read_b128 v[170:173], v213 offset:22528
	global_load_lds_dwordx4 v190, s[100:101]
	s_mov_b32 m0, s42
	ds_read_b128 v[174:177], v213 offset:23552
	global_load_lds_dwordx4 v192, s[100:101]
	s_waitcnt vmcnt(10)
	s_barrier
	s_waitcnt lgkmcnt(0)
	v_mfma_f32_16x16x32_bf16 v[62:65], v[130:133], v[146:149], 0
	v_mfma_f32_16x16x32_bf16 v[58:61], v[138:141], v[146:149], 0
	v_mfma_f32_16x16x32_bf16 v[46:49], v[130:133], v[154:157], 0
	v_mfma_f32_16x16x32_bf16 v[42:45], v[138:141], v[154:157], 0
	v_mfma_f32_16x16x32_bf16 v[30:33], v[130:133], v[162:165], 0
	v_mfma_f32_16x16x32_bf16 v[26:29], v[138:141], v[162:165], 0
	v_mfma_f32_16x16x32_bf16 v[14:17], v[130:133], v[170:173], 0
	v_mfma_f32_16x16x32_bf16 v[10:13], v[138:141], v[170:173], 0
	v_mfma_f32_16x16x32_bf16 v[62:65], v[134:137], v[150:153], v[62:65]
	v_mfma_f32_16x16x32_bf16 v[58:61], v[142:145], v[150:153], v[58:61]
	v_mfma_f32_16x16x32_bf16 v[46:49], v[134:137], v[158:161], v[46:49]
	v_mfma_f32_16x16x32_bf16 v[42:45], v[142:145], v[158:161], v[42:45]
	v_mfma_f32_16x16x32_bf16 v[30:33], v[134:137], v[166:169], v[30:33]
	v_mfma_f32_16x16x32_bf16 v[26:29], v[142:145], v[166:169], v[26:29]
	v_mfma_f32_16x16x32_bf16 v[14:17], v[134:137], v[174:177], v[14:17]
	v_mfma_f32_16x16x32_bf16 v[10:13], v[142:145], v[174:177], v[10:13]
	s_barrier
	s_add_u32 s16, s86, 0xb0000
	s_addc_u32 s17, s87, 0
	s_add_i32 m0, s38, 0x14000
	s_nop 0
	global_load_lds_dwordx4 v0, s[16:17]
	s_add_i32 m0, s38, 0x16000
	s_nop 0
	global_load_lds_dwordx4 v194, s[16:17]
	s_add_i32 s90, 0, 0x18000
	v_add_u32_e32 v142, s90, v212
	ds_read_b128 v[130:133], v142
	ds_read_b128 v[134:137], v142 offset:1024
	ds_read_b128 v[138:141], v142 offset:2048
	ds_read_b128 v[142:145], v142 offset:3072
	s_waitcnt vmcnt(6)
	s_barrier
	v_mfma_f32_16x16x32_bf16 v[54:57], v[178:181], v[146:149], 0
	v_mfma_f32_16x16x32_bf16 v[50:53], v[200:203], v[146:149], 0
	v_mfma_f32_16x16x32_bf16 v[38:41], v[178:181], v[154:157], 0
	v_mfma_f32_16x16x32_bf16 v[34:37], v[200:203], v[154:157], 0
	v_mfma_f32_16x16x32_bf16 v[22:25], v[178:181], v[162:165], 0
	v_mfma_f32_16x16x32_bf16 v[18:21], v[200:203], v[162:165], 0
	v_mfma_f32_16x16x32_bf16 v[6:9], v[178:181], v[170:173], 0
	v_mfma_f32_16x16x32_bf16 v[2:5], v[200:203], v[170:173], 0
	v_mfma_f32_16x16x32_bf16 v[54:57], v[182:185], v[150:153], v[54:57]
	v_mfma_f32_16x16x32_bf16 v[50:53], v[204:207], v[150:153], v[50:53]
	v_mfma_f32_16x16x32_bf16 v[38:41], v[182:185], v[158:161], v[38:41]
	v_mfma_f32_16x16x32_bf16 v[34:37], v[204:207], v[158:161], v[34:37]
	v_mfma_f32_16x16x32_bf16 v[22:25], v[182:185], v[166:169], v[22:25]
	v_mfma_f32_16x16x32_bf16 v[18:21], v[204:207], v[166:169], v[18:21]
	v_mfma_f32_16x16x32_bf16 v[6:9], v[182:185], v[174:177], v[6:9]
	v_mfma_f32_16x16x32_bf16 v[2:5], v[204:207], v[174:177], v[2:5]
	s_barrier
	s_add_u32 s16, s88, 0xb0000
	s_addc_u32 s17, s89, 0
	s_mov_b32 m0, s43
	ds_read_b128 v[146:149], v213 offset:32768
	ds_read_b128 v[150:153], v213 offset:33792
	ds_read_b128 v[154:157], v213 offset:34816
	ds_read_b128 v[158:161], v213 offset:35840
	ds_read_b128 v[162:165], v213 offset:36864
	ds_read_b128 v[166:169], v213 offset:37888
	ds_read_b128 v[170:173], v213 offset:38912
	global_load_lds_dwordx4 v190, s[16:17]
	s_mov_b32 m0, s44
	ds_read_b128 v[174:177], v213 offset:39936
	global_load_lds_dwordx4 v192, s[16:17]
	s_waitcnt lgkmcnt(8)
	s_barrier
	s_waitcnt lgkmcnt(0)
	v_mfma_f32_16x16x32_bf16 v[126:129], v[130:133], v[146:149], v[126:129]
	v_mfma_f32_16x16x32_bf16 v[122:125], v[138:141], v[146:149], v[122:125]
	v_mfma_f32_16x16x32_bf16 v[110:113], v[130:133], v[154:157], v[110:113]
	v_mfma_f32_16x16x32_bf16 v[106:109], v[138:141], v[154:157], v[106:109]
	v_mfma_f32_16x16x32_bf16 v[94:97], v[130:133], v[162:165], v[94:97]
	v_mfma_f32_16x16x32_bf16 v[90:93], v[138:141], v[162:165], v[90:93]
	v_mfma_f32_16x16x32_bf16 v[78:81], v[130:133], v[170:173], v[78:81]
	v_mfma_f32_16x16x32_bf16 v[74:77], v[138:141], v[170:173], v[74:77]
	v_mfma_f32_16x16x32_bf16 v[126:129], v[134:137], v[150:153], v[126:129]
	v_mfma_f32_16x16x32_bf16 v[122:125], v[142:145], v[150:153], v[122:125]
	v_mfma_f32_16x16x32_bf16 v[110:113], v[134:137], v[158:161], v[110:113]
	v_mfma_f32_16x16x32_bf16 v[106:109], v[142:145], v[158:161], v[106:109]
	v_mfma_f32_16x16x32_bf16 v[94:97], v[134:137], v[166:169], v[94:97]
	v_mfma_f32_16x16x32_bf16 v[90:93], v[142:145], v[166:169], v[90:93]
	v_mfma_f32_16x16x32_bf16 v[78:81], v[134:137], v[174:177], v[78:81]
	v_mfma_f32_16x16x32_bf16 v[74:77], v[142:145], v[174:177], v[74:77]
	s_barrier
	s_add_i32 s88, 0, 0x1c000
	v_add_u32_e32 v204, s88, v212
	s_add_i32 m0, s38, 0x18000
	ds_read_b128 v[178:181], v204
	ds_read_b128 v[182:185], v204 offset:1024
	ds_read_b128 v[200:203], v204 offset:2048
	ds_read_b128 v[204:207], v204 offset:3072
	s_add_u32 s98, s86, s40
	s_addc_u32 s99, s87, s41
	global_load_lds_dwordx4 v0, s[98:99]
	s_add_i32 m0, s38, 0x1a000
	s_nop 0
	global_load_lds_dwordx4 v194, s[98:99]
	s_barrier
	s_waitcnt lgkmcnt(0)
	v_mfma_f32_16x16x32_bf16 v[118:121], v[178:181], v[146:149], v[118:121]
	v_mfma_f32_16x16x32_bf16 v[114:117], v[200:203], v[146:149], v[114:117]
	v_mfma_f32_16x16x32_bf16 v[102:105], v[178:181], v[154:157], v[102:105]
	v_mfma_f32_16x16x32_bf16 v[98:101], v[200:203], v[154:157], v[98:101]
	v_mfma_f32_16x16x32_bf16 v[86:89], v[178:181], v[162:165], v[86:89]
	v_mfma_f32_16x16x32_bf16 v[82:85], v[200:203], v[162:165], v[82:85]
	v_mfma_f32_16x16x32_bf16 v[70:73], v[178:181], v[170:173], v[70:73]
	v_mfma_f32_16x16x32_bf16 v[66:69], v[200:203], v[170:173], v[66:69]
	v_mfma_f32_16x16x32_bf16 v[118:121], v[182:185], v[150:153], v[118:121]
	v_mfma_f32_16x16x32_bf16 v[114:117], v[204:207], v[150:153], v[114:117]
	v_mfma_f32_16x16x32_bf16 v[102:105], v[182:185], v[158:161], v[102:105]
	v_mfma_f32_16x16x32_bf16 v[98:101], v[204:207], v[158:161], v[98:101]
	v_mfma_f32_16x16x32_bf16 v[86:89], v[182:185], v[166:169], v[86:89]
	v_mfma_f32_16x16x32_bf16 v[82:85], v[204:207], v[166:169], v[82:85]
	v_mfma_f32_16x16x32_bf16 v[70:73], v[182:185], v[174:177], v[70:73]
	v_mfma_f32_16x16x32_bf16 v[66:69], v[204:207], v[174:177], v[66:69]
	s_mov_b32 m0, s60
	s_barrier
	ds_read_b128 v[146:149], v213 offset:49152
	ds_read_b128 v[150:153], v213 offset:50176
	ds_read_b128 v[154:157], v213 offset:51200
	ds_read_b128 v[158:161], v213 offset:52224
	ds_read_b128 v[162:165], v213 offset:53248
	ds_read_b128 v[166:169], v213 offset:54272
	ds_read_b128 v[170:173], v213 offset:55296
	ds_read_b128 v[174:177], v213 offset:56320
	s_add_u32 s98, s100, s40
	s_addc_u32 s99, s101, s41
	global_load_lds_dwordx4 v190, s[98:99]
	s_mov_b32 m0, s61
	s_nop 0
	global_load_lds_dwordx4 v192, s[98:99]
	s_waitcnt vmcnt(10)
	s_barrier
	s_waitcnt lgkmcnt(0)
	v_mfma_f32_16x16x32_bf16 v[62:65], v[130:133], v[146:149], v[62:65]
	v_mfma_f32_16x16x32_bf16 v[58:61], v[138:141], v[146:149], v[58:61]
	v_mfma_f32_16x16x32_bf16 v[46:49], v[130:133], v[154:157], v[46:49]
	v_mfma_f32_16x16x32_bf16 v[42:45], v[138:141], v[154:157], v[42:45]
	v_mfma_f32_16x16x32_bf16 v[30:33], v[130:133], v[162:165], v[30:33]
	v_mfma_f32_16x16x32_bf16 v[26:29], v[138:141], v[162:165], v[26:29]
	v_mfma_f32_16x16x32_bf16 v[14:17], v[130:133], v[170:173], v[14:17]
	v_mfma_f32_16x16x32_bf16 v[10:13], v[138:141], v[170:173], v[10:13]
	v_mfma_f32_16x16x32_bf16 v[62:65], v[134:137], v[150:153], v[62:65]
	v_mfma_f32_16x16x32_bf16 v[58:61], v[142:145], v[150:153], v[58:61]
	v_mfma_f32_16x16x32_bf16 v[46:49], v[134:137], v[158:161], v[46:49]
	v_mfma_f32_16x16x32_bf16 v[42:45], v[142:145], v[158:161], v[42:45]
	v_mfma_f32_16x16x32_bf16 v[30:33], v[134:137], v[166:169], v[30:33]
	v_mfma_f32_16x16x32_bf16 v[26:29], v[142:145], v[166:169], v[26:29]
	v_mfma_f32_16x16x32_bf16 v[14:17], v[134:137], v[174:177], v[14:17]
	v_mfma_f32_16x16x32_bf16 v[10:13], v[142:145], v[174:177], v[10:13]
	s_barrier
	s_add_u32 s16, s86, 0xb0080
	s_addc_u32 s17, s87, 0
	s_add_i32 m0, s38, 0x1c000
	s_nop 0
	global_load_lds_dwordx4 v0, s[16:17]
	s_add_i32 m0, s38, 0x1e000
	s_nop 0
	global_load_lds_dwordx4 v194, s[16:17]
	ds_read_b128 v[130:133], v189
	ds_read_b128 v[134:137], v189 offset:1024
	ds_read_b128 v[138:141], v189 offset:2048
	ds_read_b128 v[142:145], v189 offset:3072
	s_waitcnt vmcnt(6)
	s_barrier
	v_mfma_f32_16x16x32_bf16 v[54:57], v[178:181], v[146:149], v[54:57]
	v_mfma_f32_16x16x32_bf16 v[50:53], v[200:203], v[146:149], v[50:53]
	v_mfma_f32_16x16x32_bf16 v[38:41], v[178:181], v[154:157], v[38:41]
	v_mfma_f32_16x16x32_bf16 v[34:37], v[200:203], v[154:157], v[34:37]
	v_mfma_f32_16x16x32_bf16 v[22:25], v[178:181], v[162:165], v[22:25]
	v_mfma_f32_16x16x32_bf16 v[18:21], v[200:203], v[162:165], v[18:21]
	v_mfma_f32_16x16x32_bf16 v[6:9], v[178:181], v[170:173], v[6:9]
	v_mfma_f32_16x16x32_bf16 v[2:5], v[200:203], v[170:173], v[2:5]
	v_mfma_f32_16x16x32_bf16 v[54:57], v[182:185], v[150:153], v[54:57]
	s_add_i32 s79, s79, 2
	s_add_u32 s34, s34, 0x100
	v_mfma_f32_16x16x32_bf16 v[50:53], v[204:207], v[150:153], v[50:53]
	s_addc_u32 s78, s78, 0
	s_mov_b64 s[16:17], s[84:85]
	v_mfma_f32_16x16x32_bf16 v[38:41], v[182:185], v[158:161], v[38:41]
	s_add_u32 s84, s16, 0x100
	s_addc_u32 s85, s17, 0
	v_mfma_f32_16x16x32_bf16 v[34:37], v[204:207], v[158:161], v[34:37]
	s_cmp_eq_u32 s79, 40
	s_cselect_b32 s89, s5, s85
	v_mfma_f32_16x16x32_bf16 v[22:25], v[182:185], v[166:169], v[22:25]
	s_cselect_b32 s88, s4, s84
	s_cselect_b32 s87, s7, s78
	v_mfma_f32_16x16x32_bf16 v[18:21], v[204:207], v[166:169], v[18:21]
	s_cselect_b32 s86, s6, s34
	s_cmp_gt_u32 s79, 41
	v_mfma_f32_16x16x32_bf16 v[6:9], v[182:185], v[174:177], v[6:9]
	v_mfma_f32_16x16x32_bf16 v[2:5], v[204:207], v[174:177], v[2:5]
	s_barrier
	.p2align 3
.LBB0_1090:
	v_lshl_add_u64 v[178:179], s[16:17], 0, v[196:197]
	s_add_i32 m0, s39, 0xc000
	ds_read_b128 v[146:149], v213
	ds_read_b128 v[150:153], v213 offset:1024
	ds_read_b128 v[154:157], v213 offset:2048
	ds_read_b128 v[158:161], v213 offset:3072
	ds_read_b128 v[162:165], v213 offset:4096
	ds_read_b128 v[166:169], v213 offset:5120
	ds_read_b128 v[170:173], v213 offset:6144
	ds_read_b128 v[174:177], v213 offset:7168
	global_load_lds_dwordx4 v[178:179], off
	s_add_i32 m0, s39, 0xe000
	v_lshl_add_u64 v[178:179], s[16:17], 0, v[198:199]
	global_load_lds_dwordx4 v[178:179], off
	s_waitcnt lgkmcnt(8)
	s_barrier
	s_waitcnt lgkmcnt(0)
	v_mfma_f32_16x16x32_bf16 v[126:129], v[130:133], v[146:149], v[126:129]
	v_mfma_f32_16x16x32_bf16 v[122:125], v[138:141], v[146:149], v[122:125]
	v_mfma_f32_16x16x32_bf16 v[110:113], v[130:133], v[154:157], v[110:113]
	v_mfma_f32_16x16x32_bf16 v[106:109], v[138:141], v[154:157], v[106:109]
	v_mfma_f32_16x16x32_bf16 v[94:97], v[130:133], v[162:165], v[94:97]
	v_mfma_f32_16x16x32_bf16 v[90:93], v[138:141], v[162:165], v[90:93]
	v_mfma_f32_16x16x32_bf16 v[78:81], v[130:133], v[170:173], v[78:81]
	v_mfma_f32_16x16x32_bf16 v[74:77], v[138:141], v[170:173], v[74:77]
	v_mfma_f32_16x16x32_bf16 v[126:129], v[134:137], v[150:153], v[126:129]
	v_mfma_f32_16x16x32_bf16 v[122:125], v[142:145], v[150:153], v[122:125]
	v_mfma_f32_16x16x32_bf16 v[110:113], v[134:137], v[158:161], v[110:113]
	v_mfma_f32_16x16x32_bf16 v[106:109], v[142:145], v[158:161], v[106:109]
	v_mfma_f32_16x16x32_bf16 v[94:97], v[134:137], v[166:169], v[94:97]
	v_mfma_f32_16x16x32_bf16 v[90:93], v[142:145], v[166:169], v[90:93]
	v_mfma_f32_16x16x32_bf16 v[78:81], v[134:137], v[174:177], v[78:81]
	v_mfma_f32_16x16x32_bf16 v[74:77], v[142:145], v[174:177], v[74:77]
	s_barrier
	ds_read_b128 v[178:181], v189 offset:16384
	ds_read_b128 v[182:185], v189 offset:17408
	ds_read_b128 v[200:203], v189 offset:18432
	ds_read_b128 v[204:207], v189 offset:19456
	s_add_i32 m0, s38, 0x10000
	s_nop 0
	global_load_lds_dwordx4 v0, s[86:87]
	s_add_i32 m0, s38, 0x12000
	s_nop 0
	global_load_lds_dwordx4 v194, s[86:87]
	s_barrier
	s_waitcnt lgkmcnt(0)
	v_mfma_f32_16x16x32_bf16 v[118:121], v[178:181], v[146:149], v[118:121]
	v_mfma_f32_16x16x32_bf16 v[114:117], v[200:203], v[146:149], v[114:117]
	v_mfma_f32_16x16x32_bf16 v[102:105], v[178:181], v[154:157], v[102:105]
	v_mfma_f32_16x16x32_bf16 v[98:101], v[200:203], v[154:157], v[98:101]
	v_mfma_f32_16x16x32_bf16 v[86:89], v[178:181], v[162:165], v[86:89]
	v_mfma_f32_16x16x32_bf16 v[82:85], v[200:203], v[162:165], v[82:85]
	v_mfma_f32_16x16x32_bf16 v[70:73], v[178:181], v[170:173], v[70:73]
	v_mfma_f32_16x16x32_bf16 v[66:69], v[200:203], v[170:173], v[66:69]
	v_mfma_f32_16x16x32_bf16 v[118:121], v[182:185], v[150:153], v[118:121]
	v_mfma_f32_16x16x32_bf16 v[114:117], v[204:207], v[150:153], v[114:117]
	v_mfma_f32_16x16x32_bf16 v[102:105], v[182:185], v[158:161], v[102:105]
	v_mfma_f32_16x16x32_bf16 v[98:101], v[204:207], v[158:161], v[98:101]
	v_mfma_f32_16x16x32_bf16 v[86:89], v[182:185], v[166:169], v[86:89]
	v_mfma_f32_16x16x32_bf16 v[82:85], v[204:207], v[166:169], v[82:85]
	v_mfma_f32_16x16x32_bf16 v[70:73], v[182:185], v[174:177], v[70:73]
	v_mfma_f32_16x16x32_bf16 v[66:69], v[204:207], v[174:177], v[66:69]
	s_mov_b32 m0, s39
	s_mov_b64 s[100:101], s[88:89]
	s_barrier
	ds_read_b128 v[146:149], v213 offset:16384
	ds_read_b128 v[150:153], v213 offset:17408
	ds_read_b128 v[154:157], v213 offset:18432
	ds_read_b128 v[158:161], v213 offset:19456
	ds_read_b128 v[162:165], v213 offset:20480
	ds_read_b128 v[166:169], v213 offset:21504
	ds_read_b128 v[170:173], v213 offset:22528
	global_load_lds_dwordx4 v190, s[100:101]
	s_mov_b32 m0, s42
	ds_read_b128 v[174:177], v213 offset:23552
	global_load_lds_dwordx4 v192, s[100:101]
	s_waitcnt vmcnt(10)
	s_barrier
	s_waitcnt lgkmcnt(0)
	v_mfma_f32_16x16x32_bf16 v[62:65], v[130:133], v[146:149], v[62:65]
	v_mfma_f32_16x16x32_bf16 v[58:61], v[138:141], v[146:149], v[58:61]
	v_mfma_f32_16x16x32_bf16 v[46:49], v[130:133], v[154:157], v[46:49]
	v_mfma_f32_16x16x32_bf16 v[42:45], v[138:141], v[154:157], v[42:45]
	v_mfma_f32_16x16x32_bf16 v[30:33], v[130:133], v[162:165], v[30:33]
	v_mfma_f32_16x16x32_bf16 v[26:29], v[138:141], v[162:165], v[26:29]
	v_mfma_f32_16x16x32_bf16 v[14:17], v[130:133], v[170:173], v[14:17]
	v_mfma_f32_16x16x32_bf16 v[10:13], v[138:141], v[170:173], v[10:13]
	v_mfma_f32_16x16x32_bf16 v[62:65], v[134:137], v[150:153], v[62:65]
	v_mfma_f32_16x16x32_bf16 v[58:61], v[142:145], v[150:153], v[58:61]
	v_mfma_f32_16x16x32_bf16 v[46:49], v[134:137], v[158:161], v[46:49]
	v_mfma_f32_16x16x32_bf16 v[42:45], v[142:145], v[158:161], v[42:45]
	v_mfma_f32_16x16x32_bf16 v[30:33], v[134:137], v[166:169], v[30:33]
	v_mfma_f32_16x16x32_bf16 v[26:29], v[142:145], v[166:169], v[26:29]
	v_mfma_f32_16x16x32_bf16 v[14:17], v[134:137], v[174:177], v[14:17]
	v_mfma_f32_16x16x32_bf16 v[10:13], v[142:145], v[174:177], v[10:13]
	s_barrier
	s_add_u32 s16, s86, 0xb0000
	s_addc_u32 s17, s87, 0
	s_add_i32 m0, s38, 0x14000
	s_nop 0
	global_load_lds_dwordx4 v0, s[16:17]
	s_add_i32 m0, s38, 0x16000
	s_nop 0
	global_load_lds_dwordx4 v194, s[16:17]
	s_add_i32 s90, 0, 0x18000
	v_add_u32_e32 v142, s90, v212
	ds_read_b128 v[130:133], v142
	ds_read_b128 v[134:137], v142 offset:1024
	ds_read_b128 v[138:141], v142 offset:2048
	ds_read_b128 v[142:145], v142 offset:3072
	s_waitcnt vmcnt(6)
	s_barrier
	v_mfma_f32_16x16x32_bf16 v[54:57], v[178:181], v[146:149], v[54:57]
	v_mfma_f32_16x16x32_bf16 v[50:53], v[200:203], v[146:149], v[50:53]
	v_mfma_f32_16x16x32_bf16 v[38:41], v[178:181], v[154:157], v[38:41]
	v_mfma_f32_16x16x32_bf16 v[34:37], v[200:203], v[154:157], v[34:37]
	v_mfma_f32_16x16x32_bf16 v[22:25], v[178:181], v[162:165], v[22:25]
	v_mfma_f32_16x16x32_bf16 v[18:21], v[200:203], v[162:165], v[18:21]
	v_mfma_f32_16x16x32_bf16 v[6:9], v[178:181], v[170:173], v[6:9]
	v_mfma_f32_16x16x32_bf16 v[2:5], v[200:203], v[170:173], v[2:5]
	v_mfma_f32_16x16x32_bf16 v[54:57], v[182:185], v[150:153], v[54:57]
	v_mfma_f32_16x16x32_bf16 v[50:53], v[204:207], v[150:153], v[50:53]
	v_mfma_f32_16x16x32_bf16 v[38:41], v[182:185], v[158:161], v[38:41]
	v_mfma_f32_16x16x32_bf16 v[34:37], v[204:207], v[158:161], v[34:37]
	v_mfma_f32_16x16x32_bf16 v[22:25], v[182:185], v[166:169], v[22:25]
	v_mfma_f32_16x16x32_bf16 v[18:21], v[204:207], v[166:169], v[18:21]
	v_mfma_f32_16x16x32_bf16 v[6:9], v[182:185], v[174:177], v[6:9]
	v_mfma_f32_16x16x32_bf16 v[2:5], v[204:207], v[174:177], v[2:5]
	s_barrier
	s_add_u32 s16, s88, 0xb0000
	s_addc_u32 s17, s89, 0
	s_mov_b32 m0, s43
	ds_read_b128 v[146:149], v213 offset:32768
	ds_read_b128 v[150:153], v213 offset:33792
	ds_read_b128 v[154:157], v213 offset:34816
	ds_read_b128 v[158:161], v213 offset:35840
	ds_read_b128 v[162:165], v213 offset:36864
	ds_read_b128 v[166:169], v213 offset:37888
	ds_read_b128 v[170:173], v213 offset:38912
	global_load_lds_dwordx4 v190, s[16:17]
	s_mov_b32 m0, s44
	ds_read_b128 v[174:177], v213 offset:39936
	global_load_lds_dwordx4 v192, s[16:17]
	s_waitcnt lgkmcnt(8)
	s_barrier
	s_waitcnt lgkmcnt(0)
	v_mfma_f32_16x16x32_bf16 v[126:129], v[130:133], v[146:149], v[126:129]
	v_mfma_f32_16x16x32_bf16 v[122:125], v[138:141], v[146:149], v[122:125]
	v_mfma_f32_16x16x32_bf16 v[110:113], v[130:133], v[154:157], v[110:113]
	v_mfma_f32_16x16x32_bf16 v[106:109], v[138:141], v[154:157], v[106:109]
	v_mfma_f32_16x16x32_bf16 v[94:97], v[130:133], v[162:165], v[94:97]
	v_mfma_f32_16x16x32_bf16 v[90:93], v[138:141], v[162:165], v[90:93]
	v_mfma_f32_16x16x32_bf16 v[78:81], v[130:133], v[170:173], v[78:81]
	v_mfma_f32_16x16x32_bf16 v[74:77], v[138:141], v[170:173], v[74:77]
	v_mfma_f32_16x16x32_bf16 v[126:129], v[134:137], v[150:153], v[126:129]
	v_mfma_f32_16x16x32_bf16 v[122:125], v[142:145], v[150:153], v[122:125]
	v_mfma_f32_16x16x32_bf16 v[110:113], v[134:137], v[158:161], v[110:113]
	v_mfma_f32_16x16x32_bf16 v[106:109], v[142:145], v[158:161], v[106:109]
	v_mfma_f32_16x16x32_bf16 v[94:97], v[134:137], v[166:169], v[94:97]
	v_mfma_f32_16x16x32_bf16 v[90:93], v[142:145], v[166:169], v[90:93]
	v_mfma_f32_16x16x32_bf16 v[78:81], v[134:137], v[174:177], v[78:81]
	v_mfma_f32_16x16x32_bf16 v[74:77], v[142:145], v[174:177], v[74:77]
	s_barrier
	s_add_i32 s88, 0, 0x1c000
	v_add_u32_e32 v204, s88, v212
	s_add_i32 m0, s38, 0x18000
	ds_read_b128 v[178:181], v204
	ds_read_b128 v[182:185], v204 offset:1024
	ds_read_b128 v[200:203], v204 offset:2048
	ds_read_b128 v[204:207], v204 offset:3072
	s_add_u32 s98, s86, s40
	s_addc_u32 s99, s87, s41
	global_load_lds_dwordx4 v0, s[98:99]
	s_add_i32 m0, s38, 0x1a000
	s_nop 0
	global_load_lds_dwordx4 v194, s[98:99]
	s_barrier
	s_waitcnt lgkmcnt(0)
	v_mfma_f32_16x16x32_bf16 v[118:121], v[178:181], v[146:149], v[118:121]
	v_mfma_f32_16x16x32_bf16 v[114:117], v[200:203], v[146:149], v[114:117]
	v_mfma_f32_16x16x32_bf16 v[102:105], v[178:181], v[154:157], v[102:105]
	v_mfma_f32_16x16x32_bf16 v[98:101], v[200:203], v[154:157], v[98:101]
	v_mfma_f32_16x16x32_bf16 v[86:89], v[178:181], v[162:165], v[86:89]
	v_mfma_f32_16x16x32_bf16 v[82:85], v[200:203], v[162:165], v[82:85]
	v_mfma_f32_16x16x32_bf16 v[70:73], v[178:181], v[170:173], v[70:73]
	v_mfma_f32_16x16x32_bf16 v[66:69], v[200:203], v[170:173], v[66:69]
	v_mfma_f32_16x16x32_bf16 v[118:121], v[182:185], v[150:153], v[118:121]
	v_mfma_f32_16x16x32_bf16 v[114:117], v[204:207], v[150:153], v[114:117]
	v_mfma_f32_16x16x32_bf16 v[102:105], v[182:185], v[158:161], v[102:105]
	v_mfma_f32_16x16x32_bf16 v[98:101], v[204:207], v[158:161], v[98:101]
	v_mfma_f32_16x16x32_bf16 v[86:89], v[182:185], v[166:169], v[86:89]
	v_mfma_f32_16x16x32_bf16 v[82:85], v[204:207], v[166:169], v[82:85]
	v_mfma_f32_16x16x32_bf16 v[70:73], v[182:185], v[174:177], v[70:73]
	v_mfma_f32_16x16x32_bf16 v[66:69], v[204:207], v[174:177], v[66:69]
	s_mov_b32 m0, s60
	s_barrier
	ds_read_b128 v[146:149], v213 offset:49152
	ds_read_b128 v[150:153], v213 offset:50176
	ds_read_b128 v[154:157], v213 offset:51200
	ds_read_b128 v[158:161], v213 offset:52224
	ds_read_b128 v[162:165], v213 offset:53248
	ds_read_b128 v[166:169], v213 offset:54272
	ds_read_b128 v[170:173], v213 offset:55296
	ds_read_b128 v[174:177], v213 offset:56320
	s_add_u32 s98, s100, s40
	s_addc_u32 s99, s101, s41
	global_load_lds_dwordx4 v190, s[98:99]
	s_mov_b32 m0, s61
	s_nop 0
	global_load_lds_dwordx4 v192, s[98:99]
	s_waitcnt vmcnt(10)
	s_barrier
	s_waitcnt lgkmcnt(0)
	v_mfma_f32_16x16x32_bf16 v[62:65], v[130:133], v[146:149], v[62:65]
	v_mfma_f32_16x16x32_bf16 v[58:61], v[138:141], v[146:149], v[58:61]
	v_mfma_f32_16x16x32_bf16 v[46:49], v[130:133], v[154:157], v[46:49]
	v_mfma_f32_16x16x32_bf16 v[42:45], v[138:141], v[154:157], v[42:45]
	v_mfma_f32_16x16x32_bf16 v[30:33], v[130:133], v[162:165], v[30:33]
	v_mfma_f32_16x16x32_bf16 v[26:29], v[138:141], v[162:165], v[26:29]
	v_mfma_f32_16x16x32_bf16 v[14:17], v[130:133], v[170:173], v[14:17]
	v_mfma_f32_16x16x32_bf16 v[10:13], v[138:141], v[170:173], v[10:13]
	v_mfma_f32_16x16x32_bf16 v[62:65], v[134:137], v[150:153], v[62:65]
	v_mfma_f32_16x16x32_bf16 v[58:61], v[142:145], v[150:153], v[58:61]
	v_mfma_f32_16x16x32_bf16 v[46:49], v[134:137], v[158:161], v[46:49]
	v_mfma_f32_16x16x32_bf16 v[42:45], v[142:145], v[158:161], v[42:45]
	v_mfma_f32_16x16x32_bf16 v[30:33], v[134:137], v[166:169], v[30:33]
	v_mfma_f32_16x16x32_bf16 v[26:29], v[142:145], v[166:169], v[26:29]
	v_mfma_f32_16x16x32_bf16 v[14:17], v[134:137], v[174:177], v[14:17]
	v_mfma_f32_16x16x32_bf16 v[10:13], v[142:145], v[174:177], v[10:13]
	s_barrier
	s_add_u32 s16, s86, 0xb0080
	s_addc_u32 s17, s87, 0
	s_add_i32 m0, s38, 0x1c000
	s_nop 0
	global_load_lds_dwordx4 v0, s[16:17]
	s_add_i32 m0, s38, 0x1e000
	s_nop 0
	global_load_lds_dwordx4 v194, s[16:17]
	ds_read_b128 v[130:133], v189
	ds_read_b128 v[134:137], v189 offset:1024
	ds_read_b128 v[138:141], v189 offset:2048
	ds_read_b128 v[142:145], v189 offset:3072
	s_waitcnt vmcnt(6)
	s_barrier
	v_mfma_f32_16x16x32_bf16 v[54:57], v[178:181], v[146:149], v[54:57]
	v_mfma_f32_16x16x32_bf16 v[50:53], v[200:203], v[146:149], v[50:53]
	v_mfma_f32_16x16x32_bf16 v[38:41], v[178:181], v[154:157], v[38:41]
	v_mfma_f32_16x16x32_bf16 v[34:37], v[200:203], v[154:157], v[34:37]
	v_mfma_f32_16x16x32_bf16 v[22:25], v[178:181], v[162:165], v[22:25]
	v_mfma_f32_16x16x32_bf16 v[18:21], v[200:203], v[162:165], v[18:21]
	v_mfma_f32_16x16x32_bf16 v[6:9], v[178:181], v[170:173], v[6:9]
	v_mfma_f32_16x16x32_bf16 v[2:5], v[200:203], v[170:173], v[2:5]
	v_mfma_f32_16x16x32_bf16 v[54:57], v[182:185], v[150:153], v[54:57]
	s_add_i32 s79, s79, 2
	s_add_u32 s34, s34, 0x100
	v_mfma_f32_16x16x32_bf16 v[50:53], v[204:207], v[150:153], v[50:53]
	s_addc_u32 s78, s78, 0
	s_mov_b64 s[16:17], s[84:85]
	v_mfma_f32_16x16x32_bf16 v[38:41], v[182:185], v[158:161], v[38:41]
	s_add_u32 s84, s16, 0x100
	s_addc_u32 s85, s17, 0
	v_mfma_f32_16x16x32_bf16 v[34:37], v[204:207], v[158:161], v[34:37]
	s_cmp_eq_u32 s79, 40
	s_cselect_b32 s89, s5, s85
	v_mfma_f32_16x16x32_bf16 v[22:25], v[182:185], v[166:169], v[22:25]
	s_cselect_b32 s88, s4, s84
	s_cselect_b32 s87, s7, s78
	v_mfma_f32_16x16x32_bf16 v[18:21], v[204:207], v[166:169], v[18:21]
	s_cselect_b32 s86, s6, s34
	s_cmp_gt_u32 s79, 41
	v_mfma_f32_16x16x32_bf16 v[6:9], v[182:185], v[174:177], v[6:9]
	v_mfma_f32_16x16x32_bf16 v[2:5], v[204:207], v[174:177], v[2:5]
	s_barrier
	s_cbranch_scc0 .LBB0_1090
	s_waitcnt lgkmcnt(0)
	s_lshl_b32 s16, s23, 8
	v_mov_b32_e32 v186, v252
	s_add_i32 s16, s16, s47
	s_nop 0
	v_and_or_b32 v202, v186, 15, s16
	s_lshl_b32 s16, s22, 8
	s_or_b32 s16, s16, s55
	v_lshrrev_b32_e32 v130, 1, v186
	v_and_or_b32 v200, v130, 24, s16
	v_ashrrev_i32_e32 v201, 31, v200
	v_ashrrev_i32_e32 v203, 31, v202
	v_lshl_add_u64 v[204:205], v[200:201], 2, s[12:13]
	v_lshlrev_b64 v[130:131], 12, v[202:203]
	v_lshl_add_u64 v[130:131], v[204:205], 0, v[130:131]
	global_load_dwordx4 v[216:219], v[130:131], off offset:16
	global_load_dwordx4 v[220:223], v[130:131], off
	global_load_dwordx4 v[178:181], v[130:131], off offset:528
	global_load_dwordx4 v[182:185], v[130:131], off offset:512
	v_or_b32_e32 v210, 16, v202
	v_ashrrev_i32_e32 v211, 31, v210
	v_lshlrev_b64 v[130:131], 12, v[210:211]
	v_or_b32_e32 v208, 32, v202
	v_lshl_add_u64 v[130:131], v[204:205], 0, v[130:131]
	v_ashrrev_i32_e32 v209, 31, v208
	global_load_dwordx4 v[170:173], v[130:131], off offset:16
	global_load_dwordx4 v[174:177], v[130:131], off
	global_load_dwordx4 v[162:165], v[130:131], off offset:528
	global_load_dwordx4 v[166:169], v[130:131], off offset:512
	v_lshlrev_b64 v[130:131], 12, v[208:209]
	v_or_b32_e32 v206, 48, v202
	v_lshl_add_u64 v[130:131], v[204:205], 0, v[130:131]
	v_ashrrev_i32_e32 v207, 31, v206
	global_load_dwordx4 v[154:157], v[130:131], off offset:16
	global_load_dwordx4 v[158:161], v[130:131], off
	global_load_dwordx4 v[138:141], v[130:131], off offset:528
	global_load_dwordx4 v[142:145], v[130:131], off offset:512
	v_lshlrev_b64 v[130:131], 12, v[206:207]
	v_lshl_add_u64 v[134:135], v[204:205], 0, v[130:131]
	global_load_dwordx4 v[146:149], v[134:135], off offset:16
	global_load_dwordx4 v[150:153], v[134:135], off
	global_load_dwordx4 v[130:133], v[134:135], off offset:528
	s_nop 0
	global_load_dwordx4 v[134:137], v[134:135], off offset:512
	v_and_b32_e32 v186, 63, v186
	v_lshlrev_b32_e32 v187, 2, v186
	v_xor_b32_e32 v215, 64, v187
	v_xor_b32_e32 v214, 0x80, v187
	v_cmp_gt_u32_e32 vcc, 16, v186
	v_lshlrev_b64 v[186:187], 10, v[202:203]
	v_lshl_add_u64 v[186:187], v[186:187], 0, v[200:201]
	s_lshl_b32 s16, s22, 2
	s_ashr_i32 s17, s16, 31
	s_waitcnt vmcnt(0)
	v_pk_add_f32 v[124:125], v[124:125], v[218:219]
	v_pk_add_f32 v[128:129], v[128:129], v[222:223]
	v_pk_add_f32 v[126:127], v[126:127], v[220:221]
	v_pk_mul_f32 v[218:219], v[128:129], v[128:129]
	v_pk_mul_f32 v[220:221], v[126:127], v[126:127]
	v_pk_add_f32 v[122:123], v[122:123], v[216:217]
	v_lshl_add_u64 v[216:217], v[186:187], 2, s[14:15]
	v_add_f32_e32 v220, v220, v221
	v_add_f32_e32 v218, v218, v219
	global_store_dwordx4 v[216:217], v[126:129], off
	global_store_dwordx4 v[216:217], v[122:125], off offset:16
	v_add_f32_e32 v222, v220, v218
	v_pk_mul_f32 v[220:221], v[122:123], v[122:123]
	v_cvt_pk_bf16_f32 v126, v126, v127
	v_cvt_pk_bf16_f32 v127, v128, v129
	v_cvt_pk_bf16_f32 v128, v122, v123
	v_cvt_pk_bf16_f32 v129, v124, v125
	v_lshl_add_u64 v[122:123], v[186:187], 1, s[80:81]
	v_pk_add_f32 v[120:121], v[120:121], v[184:185]
	v_pk_add_f32 v[118:119], v[118:119], v[182:183]
	v_pk_mul_f32 v[218:219], v[124:125], v[124:125]
	global_store_dwordx4 v[122:123], v[126:129], off
	v_pk_mul_f32 v[124:125], v[120:121], v[120:121]
	v_pk_add_f32 v[116:117], v[116:117], v[180:181]
	v_pk_mul_f32 v[126:127], v[118:119], v[118:119]
	v_pk_add_f32 v[114:115], v[114:115], v[178:179]
	v_add_f32_e32 v126, v126, v127
	v_add_f32_e32 v124, v124, v125
	v_add_f32_e32 v128, v126, v124
	v_pk_mul_f32 v[124:125], v[116:117], v[116:117]
	v_pk_mul_f32 v[126:127], v[114:115], v[114:115]
	v_add_f32_e32 v220, v220, v221
	v_add_f32_e32 v218, v218, v219
	v_add_f32_e32 v126, v126, v127
	v_add_f32_e32 v124, v124, v125
	v_add_f32_e32 v218, v220, v218
	v_add_f32_e32 v124, v126, v124
	v_add_f32_e32 v218, v222, v218
	v_add_f32_e32 v124, v128, v124
	v_add_f32_e32 v124, v218, v124
	global_store_dwordx4 v[216:217], v[118:121], off offset:512
	global_store_dwordx4 v[216:217], v[114:117], off offset:528
	s_nop 0
	v_cvt_pk_bf16_f32 v118, v118, v119
	v_cvt_pk_bf16_f32 v119, v120, v121
	v_cvt_pk_bf16_f32 v120, v114, v115
	ds_bpermute_b32 v114, v215, v124
	v_cvt_pk_bf16_f32 v121, v116, v117
	global_store_dwordx4 v[122:123], v[118:121], off offset:256
	s_waitcnt lgkmcnt(0)
	v_add_f32_e32 v114, v124, v114
	ds_bpermute_b32 v115, v214, v114
	s_and_saveexec_b64 s[22:23], vcc
	s_cbranch_execz .LBB0_1093
	v_lshlrev_b64 v[116:117], 6, v[202:203]
	v_lshl_add_u64 v[116:117], s[82:83], 0, v[116:117]
	v_lshl_add_u64 v[116:117], s[16:17], 2, v[116:117]
	s_lshl_b32 s34, s45, 2
	v_lshl_add_u64 v[116:117], v[116:117], 0, s[34:35]
	s_waitcnt lgkmcnt(0)
	v_add_f32_e32 v114, v114, v115
	global_store_dword v[116:117], v114, off

.LBB0_1208:
	s_ashr_i32 s13, s12, 31
	v_cmp_lt_i64_e32 vcc, s[14:15], v[230:231]
	s_lshl_b64 s[14:15], s[12:13], 19
	s_add_u32 s14, s80, s14
	s_addc_u32 s15, s81, s15
	s_and_b64 s[16:17], vcc, exec
	s_cselect_b32 s13, s15, s89
	s_cselect_b32 s22, s14, s88
	s_ashr_i32 s7, s6, 31
	s_lshl_b64 s[16:17], s[6:7], 19
	s_add_u32 s16, s36, s16
	s_addc_u32 s17, s37, s17
	s_and_b64 s[92:93], vcc, exec
	s_cselect_b32 s7, s17, s91
	s_cselect_b32 s23, s16, s90
	s_add_u32 s88, s88, 0x40080
	s_addc_u32 s89, s89, 0
	s_add_u32 s34, s90, 0x100
	s_addc_u32 s79, s91, 0
	s_mov_b32 s85, -2
	s_waitcnt lgkmcnt(0)
	s_add_i32 s94, 0, 0x10000
	v_add_u32_e32 v0, s94, v170
	v_add_u32_e32 v189, 0x10000, v170
	ds_read_b128 v[130:133], v0
	ds_read_b128 v[134:137], v0 offset:1024
	ds_read_b128 v[138:141], v0 offset:2048
	ds_read_b128 v[142:145], v0 offset:3072
	s_add_u32 s87, s88, 0xfffc0080
	s_addc_u32 s90, s89, -1
	s_cmp_eq_u32 s85, 12
	s_cselect_b32 s93, s13, s90
	s_cselect_b32 s92, s22, s87
	s_cselect_b32 s91, s7, s79
	s_cselect_b32 s90, s23, s34
	s_waitcnt lgkmcnt(0)
	s_add_i32 m0, s39, 0xc000
	ds_read_b128 v[158:161], v171
	ds_read_b128 v[162:165], v171 offset:1024
	ds_read_b128 v[166:169], v171 offset:2048
	ds_read_b128 v[172:175], v171 offset:3072
	ds_read_b128 v[176:179], v171 offset:4096
	ds_read_b128 v[180:183], v171 offset:5120
	ds_read_b128 v[184:187], v171 offset:6144
	global_load_lds_dwordx4 v154, s[88:89]
	s_add_i32 m0, s39, 0xe000
	ds_read_b128 v[190:193], v171 offset:7168
	global_load_lds_dwordx4 v156, s[88:89]
	s_waitcnt lgkmcnt(8)
	s_barrier
	s_waitcnt lgkmcnt(0)
	v_mfma_f32_16x16x32_bf16 v[126:129], v[130:133], v[158:161], 0
	v_mfma_f32_16x16x32_bf16 v[122:125], v[138:141], v[158:161], 0
	v_mfma_f32_16x16x32_bf16 v[110:113], v[130:133], v[166:169], 0
	v_mfma_f32_16x16x32_bf16 v[106:109], v[138:141], v[166:169], 0
	v_mfma_f32_16x16x32_bf16 v[94:97], v[130:133], v[176:179], 0
	v_mfma_f32_16x16x32_bf16 v[90:93], v[138:141], v[176:179], 0
	v_mfma_f32_16x16x32_bf16 v[78:81], v[130:133], v[184:187], 0
	v_mfma_f32_16x16x32_bf16 v[74:77], v[138:141], v[184:187], 0
	v_mfma_f32_16x16x32_bf16 v[126:129], v[134:137], v[162:165], v[126:129]
	v_mfma_f32_16x16x32_bf16 v[122:125], v[142:145], v[162:165], v[122:125]
	v_mfma_f32_16x16x32_bf16 v[110:113], v[134:137], v[172:175], v[110:113]
	v_mfma_f32_16x16x32_bf16 v[106:109], v[142:145], v[172:175], v[106:109]
	v_mfma_f32_16x16x32_bf16 v[94:97], v[134:137], v[180:183], v[94:97]
	v_mfma_f32_16x16x32_bf16 v[90:93], v[142:145], v[180:183], v[90:93]
	v_mfma_f32_16x16x32_bf16 v[78:81], v[134:137], v[190:193], v[78:81]
	v_mfma_f32_16x16x32_bf16 v[74:77], v[142:145], v[190:193], v[74:77]
	s_barrier
	s_add_i32 m0, s38, 0x10000
	ds_read_b128 v[194:197], v189 offset:16384
	ds_read_b128 v[198:201], v189 offset:17408
	ds_read_b128 v[202:205], v189 offset:18432
	global_load_lds_dwordx4 v148, s[90:91]
	s_add_i32 m0, s38, 0x12000
	ds_read_b128 v[206:209], v189 offset:19456
	global_load_lds_dwordx4 v152, s[90:91]
	s_barrier
	s_waitcnt lgkmcnt(0)
	v_mfma_f32_16x16x32_bf16 v[118:121], v[194:197], v[158:161], 0
	v_mfma_f32_16x16x32_bf16 v[114:117], v[202:205], v[158:161], 0
	v_mfma_f32_16x16x32_bf16 v[102:105], v[194:197], v[166:169], 0
	v_mfma_f32_16x16x32_bf16 v[98:101], v[202:205], v[166:169], 0
	v_mfma_f32_16x16x32_bf16 v[86:89], v[194:197], v[176:179], 0
	v_mfma_f32_16x16x32_bf16 v[82:85], v[202:205], v[176:179], 0
	v_mfma_f32_16x16x32_bf16 v[70:73], v[194:197], v[184:187], 0
	v_mfma_f32_16x16x32_bf16 v[66:69], v[202:205], v[184:187], 0
	v_mfma_f32_16x16x32_bf16 v[118:121], v[198:201], v[162:165], v[118:121]
	v_mfma_f32_16x16x32_bf16 v[114:117], v[206:209], v[162:165], v[114:117]
	v_mfma_f32_16x16x32_bf16 v[102:105], v[198:201], v[172:175], v[102:105]
	v_mfma_f32_16x16x32_bf16 v[98:101], v[206:209], v[172:175], v[98:101]
	v_mfma_f32_16x16x32_bf16 v[86:89], v[198:201], v[180:183], v[86:89]
	v_mfma_f32_16x16x32_bf16 v[82:85], v[206:209], v[180:183], v[82:85]
	v_mfma_f32_16x16x32_bf16 v[70:73], v[198:201], v[190:193], v[70:73]
	v_mfma_f32_16x16x32_bf16 v[66:69], v[206:209], v[190:193], v[66:69]
	s_mov_b32 m0, s39
	s_mov_b64 s[100:101], s[92:93]
	s_barrier
	ds_read_b128 v[158:161], v171 offset:16384
	ds_read_b128 v[162:165], v171 offset:17408
	ds_read_b128 v[166:169], v171 offset:18432
	ds_read_b128 v[172:175], v171 offset:19456
	ds_read_b128 v[176:179], v171 offset:20480
	ds_read_b128 v[180:183], v171 offset:21504
	ds_read_b128 v[184:187], v171 offset:22528
	global_load_lds_dwordx4 v146, s[100:101]
	s_mov_b32 m0, s42
	ds_read_b128 v[190:193], v171 offset:23552
	global_load_lds_dwordx4 v150, s[100:101]
	s_waitcnt vmcnt(10)
	s_barrier
	s_waitcnt lgkmcnt(0)
	v_mfma_f32_16x16x32_bf16 v[62:65], v[130:133], v[158:161], 0
	v_mfma_f32_16x16x32_bf16 v[58:61], v[138:141], v[158:161], 0
	v_mfma_f32_16x16x32_bf16 v[46:49], v[130:133], v[166:169], 0
	v_mfma_f32_16x16x32_bf16 v[42:45], v[138:141], v[166:169], 0
	v_mfma_f32_16x16x32_bf16 v[30:33], v[130:133], v[176:179], 0
	v_mfma_f32_16x16x32_bf16 v[26:29], v[138:141], v[176:179], 0
	v_mfma_f32_16x16x32_bf16 v[14:17], v[130:133], v[184:187], 0
	v_mfma_f32_16x16x32_bf16 v[10:13], v[138:141], v[184:187], 0
	v_mfma_f32_16x16x32_bf16 v[62:65], v[134:137], v[162:165], v[62:65]
	v_mfma_f32_16x16x32_bf16 v[58:61], v[142:145], v[162:165], v[58:61]
	v_mfma_f32_16x16x32_bf16 v[46:49], v[134:137], v[172:175], v[46:49]
	v_mfma_f32_16x16x32_bf16 v[42:45], v[142:145], v[172:175], v[42:45]
	v_mfma_f32_16x16x32_bf16 v[30:33], v[134:137], v[180:183], v[30:33]
	v_mfma_f32_16x16x32_bf16 v[26:29], v[142:145], v[180:183], v[26:29]
	v_mfma_f32_16x16x32_bf16 v[14:17], v[134:137], v[190:193], v[14:17]
	v_mfma_f32_16x16x32_bf16 v[10:13], v[142:145], v[190:193], v[10:13]
	s_barrier
	s_add_u32 s94, s90, 0x40000
	s_addc_u32 s95, s91, 0
	s_add_i32 m0, s38, 0x14000
	s_nop 0
	global_load_lds_dwordx4 v148, s[94:95]
	s_add_i32 m0, s38, 0x16000
	s_nop 0
	global_load_lds_dwordx4 v152, s[94:95]
	ds_read_b128 v[130:133], v189 offset:32768
	ds_read_b128 v[134:137], v189 offset:33792
	ds_read_b128 v[138:141], v189 offset:34816
	ds_read_b128 v[142:145], v189 offset:35840
	s_waitcnt vmcnt(6)
	s_barrier
	v_mfma_f32_16x16x32_bf16 v[54:57], v[194:197], v[158:161], 0
	v_mfma_f32_16x16x32_bf16 v[50:53], v[202:205], v[158:161], 0
	v_mfma_f32_16x16x32_bf16 v[38:41], v[194:197], v[166:169], 0
	v_mfma_f32_16x16x32_bf16 v[34:37], v[202:205], v[166:169], 0
	v_mfma_f32_16x16x32_bf16 v[22:25], v[194:197], v[176:179], 0
	v_mfma_f32_16x16x32_bf16 v[18:21], v[202:205], v[176:179], 0
	v_mfma_f32_16x16x32_bf16 v[6:9], v[194:197], v[184:187], 0
	v_mfma_f32_16x16x32_bf16 v[2:5], v[202:205], v[184:187], 0
	v_mfma_f32_16x16x32_bf16 v[54:57], v[198:201], v[162:165], v[54:57]
	v_mfma_f32_16x16x32_bf16 v[50:53], v[206:209], v[162:165], v[50:53]
	v_mfma_f32_16x16x32_bf16 v[38:41], v[198:201], v[172:175], v[38:41]
	v_mfma_f32_16x16x32_bf16 v[34:37], v[206:209], v[172:175], v[34:37]
	v_mfma_f32_16x16x32_bf16 v[22:25], v[198:201], v[180:183], v[22:25]
	v_mfma_f32_16x16x32_bf16 v[18:21], v[206:209], v[180:183], v[18:21]
	v_mfma_f32_16x16x32_bf16 v[6:9], v[198:201], v[190:193], v[6:9]
	v_mfma_f32_16x16x32_bf16 v[2:5], v[206:209], v[190:193], v[2:5]
	s_barrier
	s_add_u32 s92, s92, 0x40000
	s_addc_u32 s93, s93, 0
	s_mov_b32 m0, s43
	ds_read_b128 v[158:161], v171 offset:32768
	ds_read_b128 v[162:165], v171 offset:33792
	ds_read_b128 v[166:169], v171 offset:34816
	ds_read_b128 v[172:175], v171 offset:35840
	ds_read_b128 v[176:179], v171 offset:36864
	ds_read_b128 v[180:183], v171 offset:37888
	ds_read_b128 v[184:187], v171 offset:38912
	global_load_lds_dwordx4 v146, s[92:93]
	s_mov_b32 m0, s44
	ds_read_b128 v[190:193], v171 offset:39936
	global_load_lds_dwordx4 v150, s[92:93]
	s_waitcnt lgkmcnt(8)
	s_barrier
	s_waitcnt lgkmcnt(0)
	v_mfma_f32_16x16x32_bf16 v[126:129], v[130:133], v[158:161], v[126:129]
	v_mfma_f32_16x16x32_bf16 v[122:125], v[138:141], v[158:161], v[122:125]
	v_mfma_f32_16x16x32_bf16 v[110:113], v[130:133], v[166:169], v[110:113]
	v_mfma_f32_16x16x32_bf16 v[106:109], v[138:141], v[166:169], v[106:109]
	v_mfma_f32_16x16x32_bf16 v[94:97], v[130:133], v[176:179], v[94:97]
	v_mfma_f32_16x16x32_bf16 v[90:93], v[138:141], v[176:179], v[90:93]
	v_mfma_f32_16x16x32_bf16 v[78:81], v[130:133], v[184:187], v[78:81]
	v_mfma_f32_16x16x32_bf16 v[74:77], v[138:141], v[184:187], v[74:77]
	v_mfma_f32_16x16x32_bf16 v[126:129], v[134:137], v[162:165], v[126:129]
	v_mfma_f32_16x16x32_bf16 v[122:125], v[142:145], v[162:165], v[122:125]
	v_mfma_f32_16x16x32_bf16 v[110:113], v[134:137], v[172:175], v[110:113]
	v_mfma_f32_16x16x32_bf16 v[106:109], v[142:145], v[172:175], v[106:109]
	v_mfma_f32_16x16x32_bf16 v[94:97], v[134:137], v[180:183], v[94:97]
	v_mfma_f32_16x16x32_bf16 v[90:93], v[142:145], v[180:183], v[90:93]
	v_mfma_f32_16x16x32_bf16 v[78:81], v[134:137], v[190:193], v[78:81]
	v_mfma_f32_16x16x32_bf16 v[74:77], v[142:145], v[190:193], v[74:77]
	s_barrier
	s_add_i32 m0, s38, 0x18000
	ds_read_b128 v[194:197], v189 offset:49152
	ds_read_b128 v[198:201], v189 offset:50176
	ds_read_b128 v[202:205], v189 offset:51200
	ds_read_b128 v[206:209], v189 offset:52224
	s_add_u32 s98, s90, s40
	s_addc_u32 s99, s91, s41
	global_load_lds_dwordx4 v148, s[98:99]
	s_add_i32 m0, s38, 0x1a000
	s_nop 0
	global_load_lds_dwordx4 v152, s[98:99]
	s_barrier
	s_waitcnt lgkmcnt(0)
	v_mfma_f32_16x16x32_bf16 v[118:121], v[194:197], v[158:161], v[118:121]
	v_mfma_f32_16x16x32_bf16 v[114:117], v[202:205], v[158:161], v[114:117]
	v_mfma_f32_16x16x32_bf16 v[102:105], v[194:197], v[166:169], v[102:105]
	v_mfma_f32_16x16x32_bf16 v[98:101], v[202:205], v[166:169], v[98:101]
	v_mfma_f32_16x16x32_bf16 v[86:89], v[194:197], v[176:179], v[86:89]
	v_mfma_f32_16x16x32_bf16 v[82:85], v[202:205], v[176:179], v[82:85]
	v_mfma_f32_16x16x32_bf16 v[70:73], v[194:197], v[184:187], v[70:73]
	v_mfma_f32_16x16x32_bf16 v[66:69], v[202:205], v[184:187], v[66:69]
	v_mfma_f32_16x16x32_bf16 v[118:121], v[198:201], v[162:165], v[118:121]
	v_mfma_f32_16x16x32_bf16 v[114:117], v[206:209], v[162:165], v[114:117]
	v_mfma_f32_16x16x32_bf16 v[102:105], v[198:201], v[172:175], v[102:105]
	v_mfma_f32_16x16x32_bf16 v[98:101], v[206:209], v[172:175], v[98:101]
	v_mfma_f32_16x16x32_bf16 v[86:89], v[198:201], v[180:183], v[86:89]
	v_mfma_f32_16x16x32_bf16 v[82:85], v[206:209], v[180:183], v[82:85]
	v_mfma_f32_16x16x32_bf16 v[70:73], v[198:201], v[190:193], v[70:73]
	v_mfma_f32_16x16x32_bf16 v[66:69], v[206:209], v[190:193], v[66:69]
	s_mov_b32 m0, s60
	s_barrier
	ds_read_b128 v[158:161], v171 offset:49152
	ds_read_b128 v[162:165], v171 offset:50176
	ds_read_b128 v[166:169], v171 offset:51200
	ds_read_b128 v[172:175], v171 offset:52224
	ds_read_b128 v[176:179], v171 offset:53248
	ds_read_b128 v[180:183], v171 offset:54272
	ds_read_b128 v[184:187], v171 offset:55296
	ds_read_b128 v[190:193], v171 offset:56320
	s_add_u32 s98, s100, s40
	s_addc_u32 s99, s101, s41
	global_load_lds_dwordx4 v146, s[98:99]
	s_mov_b32 m0, s61
	s_nop 0
	global_load_lds_dwordx4 v150, s[98:99]
	s_waitcnt vmcnt(10)
	s_barrier
	s_waitcnt lgkmcnt(0)
	v_mfma_f32_16x16x32_bf16 v[62:65], v[130:133], v[158:161], v[62:65]
	v_mfma_f32_16x16x32_bf16 v[58:61], v[138:141], v[158:161], v[58:61]
	v_mfma_f32_16x16x32_bf16 v[46:49], v[130:133], v[166:169], v[46:49]
	v_mfma_f32_16x16x32_bf16 v[42:45], v[138:141], v[166:169], v[42:45]
	v_mfma_f32_16x16x32_bf16 v[30:33], v[130:133], v[176:179], v[30:33]
	v_mfma_f32_16x16x32_bf16 v[26:29], v[138:141], v[176:179], v[26:29]
	v_mfma_f32_16x16x32_bf16 v[14:17], v[130:133], v[184:187], v[14:17]
	v_mfma_f32_16x16x32_bf16 v[10:13], v[138:141], v[184:187], v[10:13]
	v_mfma_f32_16x16x32_bf16 v[62:65], v[134:137], v[162:165], v[62:65]
	v_mfma_f32_16x16x32_bf16 v[58:61], v[142:145], v[162:165], v[58:61]
	v_mfma_f32_16x16x32_bf16 v[46:49], v[134:137], v[172:175], v[46:49]
	v_mfma_f32_16x16x32_bf16 v[42:45], v[142:145], v[172:175], v[42:45]
	v_mfma_f32_16x16x32_bf16 v[30:33], v[134:137], v[180:183], v[30:33]
	v_mfma_f32_16x16x32_bf16 v[26:29], v[142:145], v[180:183], v[26:29]
	v_mfma_f32_16x16x32_bf16 v[14:17], v[134:137], v[190:193], v[14:17]
	v_mfma_f32_16x16x32_bf16 v[10:13], v[142:145], v[190:193], v[10:13]
	s_barrier
	s_add_u32 s90, s90, 0x40080
	s_addc_u32 s91, s91, 0
	s_add_i32 m0, s38, 0x1c000
	s_nop 0
	global_load_lds_dwordx4 v148, s[90:91]
	s_add_i32 m0, s38, 0x1e000
	s_nop 0
	global_load_lds_dwordx4 v152, s[90:91]
	ds_read_b128 v[130:133], v189
	ds_read_b128 v[134:137], v189 offset:1024
	ds_read_b128 v[138:141], v189 offset:2048
	ds_read_b128 v[142:145], v189 offset:3072
	s_waitcnt vmcnt(6)
	s_barrier
	v_mfma_f32_16x16x32_bf16 v[54:57], v[194:197], v[158:161], v[54:57]
	v_mfma_f32_16x16x32_bf16 v[50:53], v[202:205], v[158:161], v[50:53]
	v_mfma_f32_16x16x32_bf16 v[38:41], v[194:197], v[166:169], v[38:41]
	v_mfma_f32_16x16x32_bf16 v[34:37], v[202:205], v[166:169], v[34:37]
	v_mfma_f32_16x16x32_bf16 v[22:25], v[194:197], v[176:179], v[22:25]
	v_mfma_f32_16x16x32_bf16 v[18:21], v[202:205], v[176:179], v[18:21]
	v_mfma_f32_16x16x32_bf16 v[6:9], v[194:197], v[184:187], v[6:9]
	v_mfma_f32_16x16x32_bf16 v[2:5], v[202:205], v[184:187], v[2:5]
	v_mfma_f32_16x16x32_bf16 v[54:57], v[198:201], v[162:165], v[54:57]
	s_add_i32 s85, s85, 2
	s_add_u32 s88, s88, 0x100
	v_mfma_f32_16x16x32_bf16 v[50:53], v[206:209], v[162:165], v[50:53]
	s_addc_u32 s89, s89, 0
	s_add_u32 s34, s34, 0x100
	v_mfma_f32_16x16x32_bf16 v[38:41], v[198:201], v[172:175], v[38:41]
	s_addc_u32 s79, s79, 0
	s_add_u32 s87, s88, 0xfffc0080
	v_mfma_f32_16x16x32_bf16 v[34:37], v[206:209], v[172:175], v[34:37]
	s_addc_u32 s90, s89, -1
	s_cmp_eq_u32 s85, 12
	v_mfma_f32_16x16x32_bf16 v[22:25], v[198:201], v[180:183], v[22:25]
	s_cselect_b32 s93, s13, s90
	s_cselect_b32 s92, s22, s87
	v_mfma_f32_16x16x32_bf16 v[18:21], v[206:209], v[180:183], v[18:21]
	s_cselect_b32 s91, s7, s79
	s_cselect_b32 s90, s23, s34
	v_mfma_f32_16x16x32_bf16 v[6:9], v[198:201], v[190:193], v[6:9]
	s_cmp_gt_u32 s85, 13
	v_mfma_f32_16x16x32_bf16 v[2:5], v[206:209], v[190:193], v[2:5]
	s_barrier
	.p2align 3
.LBB0_1209:
	s_waitcnt lgkmcnt(0)
	s_add_i32 m0, s39, 0xc000
	ds_read_b128 v[158:161], v171
	ds_read_b128 v[162:165], v171 offset:1024
	ds_read_b128 v[166:169], v171 offset:2048
	ds_read_b128 v[172:175], v171 offset:3072
	ds_read_b128 v[176:179], v171 offset:4096
	ds_read_b128 v[180:183], v171 offset:5120
	ds_read_b128 v[184:187], v171 offset:6144
	global_load_lds_dwordx4 v154, s[88:89]
	s_add_i32 m0, s39, 0xe000
	ds_read_b128 v[190:193], v171 offset:7168
	global_load_lds_dwordx4 v156, s[88:89]
	s_waitcnt lgkmcnt(8)
	s_barrier
	s_waitcnt lgkmcnt(0)
	v_mfma_f32_16x16x32_bf16 v[126:129], v[130:133], v[158:161], v[126:129]
	v_mfma_f32_16x16x32_bf16 v[122:125], v[138:141], v[158:161], v[122:125]
	v_mfma_f32_16x16x32_bf16 v[110:113], v[130:133], v[166:169], v[110:113]
	v_mfma_f32_16x16x32_bf16 v[106:109], v[138:141], v[166:169], v[106:109]
	v_mfma_f32_16x16x32_bf16 v[94:97], v[130:133], v[176:179], v[94:97]
	v_mfma_f32_16x16x32_bf16 v[90:93], v[138:141], v[176:179], v[90:93]
	v_mfma_f32_16x16x32_bf16 v[78:81], v[130:133], v[184:187], v[78:81]
	v_mfma_f32_16x16x32_bf16 v[74:77], v[138:141], v[184:187], v[74:77]
	v_mfma_f32_16x16x32_bf16 v[126:129], v[134:137], v[162:165], v[126:129]
	v_mfma_f32_16x16x32_bf16 v[122:125], v[142:145], v[162:165], v[122:125]
	v_mfma_f32_16x16x32_bf16 v[110:113], v[134:137], v[172:175], v[110:113]
	v_mfma_f32_16x16x32_bf16 v[106:109], v[142:145], v[172:175], v[106:109]
	v_mfma_f32_16x16x32_bf16 v[94:97], v[134:137], v[180:183], v[94:97]
	v_mfma_f32_16x16x32_bf16 v[90:93], v[142:145], v[180:183], v[90:93]
	v_mfma_f32_16x16x32_bf16 v[78:81], v[134:137], v[190:193], v[78:81]
	v_mfma_f32_16x16x32_bf16 v[74:77], v[142:145], v[190:193], v[74:77]
	s_barrier
	s_add_i32 m0, s38, 0x10000
	ds_read_b128 v[194:197], v189 offset:16384
	ds_read_b128 v[198:201], v189 offset:17408
	ds_read_b128 v[202:205], v189 offset:18432
	global_load_lds_dwordx4 v148, s[90:91]
	s_add_i32 m0, s38, 0x12000
	ds_read_b128 v[206:209], v189 offset:19456
	global_load_lds_dwordx4 v152, s[90:91]
	s_barrier
	s_waitcnt lgkmcnt(0)
	v_mfma_f32_16x16x32_bf16 v[118:121], v[194:197], v[158:161], v[118:121]
	v_mfma_f32_16x16x32_bf16 v[114:117], v[202:205], v[158:161], v[114:117]
	v_mfma_f32_16x16x32_bf16 v[102:105], v[194:197], v[166:169], v[102:105]
	v_mfma_f32_16x16x32_bf16 v[98:101], v[202:205], v[166:169], v[98:101]
	v_mfma_f32_16x16x32_bf16 v[86:89], v[194:197], v[176:179], v[86:89]
	v_mfma_f32_16x16x32_bf16 v[82:85], v[202:205], v[176:179], v[82:85]
	v_mfma_f32_16x16x32_bf16 v[70:73], v[194:197], v[184:187], v[70:73]
	v_mfma_f32_16x16x32_bf16 v[66:69], v[202:205], v[184:187], v[66:69]
	v_mfma_f32_16x16x32_bf16 v[118:121], v[198:201], v[162:165], v[118:121]
	v_mfma_f32_16x16x32_bf16 v[114:117], v[206:209], v[162:165], v[114:117]
	v_mfma_f32_16x16x32_bf16 v[102:105], v[198:201], v[172:175], v[102:105]
	v_mfma_f32_16x16x32_bf16 v[98:101], v[206:209], v[172:175], v[98:101]
	v_mfma_f32_16x16x32_bf16 v[86:89], v[198:201], v[180:183], v[86:89]
	v_mfma_f32_16x16x32_bf16 v[82:85], v[206:209], v[180:183], v[82:85]
	v_mfma_f32_16x16x32_bf16 v[70:73], v[198:201], v[190:193], v[70:73]
	v_mfma_f32_16x16x32_bf16 v[66:69], v[206:209], v[190:193], v[66:69]
	s_mov_b32 m0, s39
	s_mov_b64 s[100:101], s[92:93]
	s_barrier
	ds_read_b128 v[158:161], v171 offset:16384
	ds_read_b128 v[162:165], v171 offset:17408
	ds_read_b128 v[166:169], v171 offset:18432
	ds_read_b128 v[172:175], v171 offset:19456
	ds_read_b128 v[176:179], v171 offset:20480
	ds_read_b128 v[180:183], v171 offset:21504
	ds_read_b128 v[184:187], v171 offset:22528
	global_load_lds_dwordx4 v146, s[100:101]
	s_mov_b32 m0, s42
	ds_read_b128 v[190:193], v171 offset:23552
	global_load_lds_dwordx4 v150, s[100:101]
	s_waitcnt vmcnt(10)
	s_barrier
	s_waitcnt lgkmcnt(0)
	v_mfma_f32_16x16x32_bf16 v[62:65], v[130:133], v[158:161], v[62:65]
	v_mfma_f32_16x16x32_bf16 v[58:61], v[138:141], v[158:161], v[58:61]
	v_mfma_f32_16x16x32_bf16 v[46:49], v[130:133], v[166:169], v[46:49]
	v_mfma_f32_16x16x32_bf16 v[42:45], v[138:141], v[166:169], v[42:45]
	v_mfma_f32_16x16x32_bf16 v[30:33], v[130:133], v[176:179], v[30:33]
	v_mfma_f32_16x16x32_bf16 v[26:29], v[138:141], v[176:179], v[26:29]
	v_mfma_f32_16x16x32_bf16 v[14:17], v[130:133], v[184:187], v[14:17]
	v_mfma_f32_16x16x32_bf16 v[10:13], v[138:141], v[184:187], v[10:13]
	v_mfma_f32_16x16x32_bf16 v[62:65], v[134:137], v[162:165], v[62:65]
	v_mfma_f32_16x16x32_bf16 v[58:61], v[142:145], v[162:165], v[58:61]
	v_mfma_f32_16x16x32_bf16 v[46:49], v[134:137], v[172:175], v[46:49]
	v_mfma_f32_16x16x32_bf16 v[42:45], v[142:145], v[172:175], v[42:45]
	v_mfma_f32_16x16x32_bf16 v[30:33], v[134:137], v[180:183], v[30:33]
	v_mfma_f32_16x16x32_bf16 v[26:29], v[142:145], v[180:183], v[26:29]
	v_mfma_f32_16x16x32_bf16 v[14:17], v[134:137], v[190:193], v[14:17]
	v_mfma_f32_16x16x32_bf16 v[10:13], v[142:145], v[190:193], v[10:13]
	s_barrier
	s_add_u32 s94, s90, 0x40000
	s_addc_u32 s95, s91, 0
	s_add_i32 m0, s38, 0x14000
	s_nop 0
	global_load_lds_dwordx4 v148, s[94:95]
	s_add_i32 m0, s38, 0x16000
	s_nop 0
	global_load_lds_dwordx4 v152, s[94:95]
	ds_read_b128 v[130:133], v189 offset:32768
	ds_read_b128 v[134:137], v189 offset:33792
	ds_read_b128 v[138:141], v189 offset:34816
	ds_read_b128 v[142:145], v189 offset:35840
	s_waitcnt vmcnt(6)
	s_barrier
	v_mfma_f32_16x16x32_bf16 v[54:57], v[194:197], v[158:161], v[54:57]
	v_mfma_f32_16x16x32_bf16 v[50:53], v[202:205], v[158:161], v[50:53]
	v_mfma_f32_16x16x32_bf16 v[38:41], v[194:197], v[166:169], v[38:41]
	v_mfma_f32_16x16x32_bf16 v[34:37], v[202:205], v[166:169], v[34:37]
	v_mfma_f32_16x16x32_bf16 v[22:25], v[194:197], v[176:179], v[22:25]
	v_mfma_f32_16x16x32_bf16 v[18:21], v[202:205], v[176:179], v[18:21]
	v_mfma_f32_16x16x32_bf16 v[6:9], v[194:197], v[184:187], v[6:9]
	v_mfma_f32_16x16x32_bf16 v[2:5], v[202:205], v[184:187], v[2:5]
	v_mfma_f32_16x16x32_bf16 v[54:57], v[198:201], v[162:165], v[54:57]
	v_mfma_f32_16x16x32_bf16 v[50:53], v[206:209], v[162:165], v[50:53]
	v_mfma_f32_16x16x32_bf16 v[38:41], v[198:201], v[172:175], v[38:41]
	v_mfma_f32_16x16x32_bf16 v[34:37], v[206:209], v[172:175], v[34:37]
	v_mfma_f32_16x16x32_bf16 v[22:25], v[198:201], v[180:183], v[22:25]
	v_mfma_f32_16x16x32_bf16 v[18:21], v[206:209], v[180:183], v[18:21]
	v_mfma_f32_16x16x32_bf16 v[6:9], v[198:201], v[190:193], v[6:9]
	v_mfma_f32_16x16x32_bf16 v[2:5], v[206:209], v[190:193], v[2:5]
	s_barrier
	s_add_u32 s92, s92, 0x40000
	s_addc_u32 s93, s93, 0
	s_mov_b32 m0, s43
	ds_read_b128 v[158:161], v171 offset:32768
	ds_read_b128 v[162:165], v171 offset:33792
	ds_read_b128 v[166:169], v171 offset:34816
	ds_read_b128 v[172:175], v171 offset:35840
	ds_read_b128 v[176:179], v171 offset:36864
	ds_read_b128 v[180:183], v171 offset:37888
	ds_read_b128 v[184:187], v171 offset:38912
	global_load_lds_dwordx4 v146, s[92:93]
	s_mov_b32 m0, s44
	ds_read_b128 v[190:193], v171 offset:39936
	global_load_lds_dwordx4 v150, s[92:93]
	s_waitcnt lgkmcnt(8)
	s_barrier
	s_waitcnt lgkmcnt(0)
	v_mfma_f32_16x16x32_bf16 v[126:129], v[130:133], v[158:161], v[126:129]
	v_mfma_f32_16x16x32_bf16 v[122:125], v[138:141], v[158:161], v[122:125]
	v_mfma_f32_16x16x32_bf16 v[110:113], v[130:133], v[166:169], v[110:113]
	v_mfma_f32_16x16x32_bf16 v[106:109], v[138:141], v[166:169], v[106:109]
	v_mfma_f32_16x16x32_bf16 v[94:97], v[130:133], v[176:179], v[94:97]
	v_mfma_f32_16x16x32_bf16 v[90:93], v[138:141], v[176:179], v[90:93]
	v_mfma_f32_16x16x32_bf16 v[78:81], v[130:133], v[184:187], v[78:81]
	v_mfma_f32_16x16x32_bf16 v[74:77], v[138:141], v[184:187], v[74:77]
	v_mfma_f32_16x16x32_bf16 v[126:129], v[134:137], v[162:165], v[126:129]
	v_mfma_f32_16x16x32_bf16 v[122:125], v[142:145], v[162:165], v[122:125]
	v_mfma_f32_16x16x32_bf16 v[110:113], v[134:137], v[172:175], v[110:113]
	v_mfma_f32_16x16x32_bf16 v[106:109], v[142:145], v[172:175], v[106:109]
	v_mfma_f32_16x16x32_bf16 v[94:97], v[134:137], v[180:183], v[94:97]
	v_mfma_f32_16x16x32_bf16 v[90:93], v[142:145], v[180:183], v[90:93]
	v_mfma_f32_16x16x32_bf16 v[78:81], v[134:137], v[190:193], v[78:81]
	v_mfma_f32_16x16x32_bf16 v[74:77], v[142:145], v[190:193], v[74:77]
	s_barrier
	s_add_i32 m0, s38, 0x18000
	ds_read_b128 v[194:197], v189 offset:49152
	ds_read_b128 v[198:201], v189 offset:50176
	ds_read_b128 v[202:205], v189 offset:51200
	ds_read_b128 v[206:209], v189 offset:52224
	s_add_u32 s98, s90, s40
	s_addc_u32 s99, s91, s41
	global_load_lds_dwordx4 v148, s[98:99]
	s_add_i32 m0, s38, 0x1a000
	s_nop 0
	global_load_lds_dwordx4 v152, s[98:99]
	s_barrier
	s_waitcnt lgkmcnt(0)
	v_mfma_f32_16x16x32_bf16 v[118:121], v[194:197], v[158:161], v[118:121]
	v_mfma_f32_16x16x32_bf16 v[114:117], v[202:205], v[158:161], v[114:117]
	v_mfma_f32_16x16x32_bf16 v[102:105], v[194:197], v[166:169], v[102:105]
	v_mfma_f32_16x16x32_bf16 v[98:101], v[202:205], v[166:169], v[98:101]
	v_mfma_f32_16x16x32_bf16 v[86:89], v[194:197], v[176:179], v[86:89]
	v_mfma_f32_16x16x32_bf16 v[82:85], v[202:205], v[176:179], v[82:85]
	v_mfma_f32_16x16x32_bf16 v[70:73], v[194:197], v[184:187], v[70:73]
	v_mfma_f32_16x16x32_bf16 v[66:69], v[202:205], v[184:187], v[66:69]
	v_mfma_f32_16x16x32_bf16 v[118:121], v[198:201], v[162:165], v[118:121]
	v_mfma_f32_16x16x32_bf16 v[114:117], v[206:209], v[162:165], v[114:117]
	v_mfma_f32_16x16x32_bf16 v[102:105], v[198:201], v[172:175], v[102:105]
	v_mfma_f32_16x16x32_bf16 v[98:101], v[206:209], v[172:175], v[98:101]
	v_mfma_f32_16x16x32_bf16 v[86:89], v[198:201], v[180:183], v[86:89]
	v_mfma_f32_16x16x32_bf16 v[82:85], v[206:209], v[180:183], v[82:85]
	v_mfma_f32_16x16x32_bf16 v[70:73], v[198:201], v[190:193], v[70:73]
	v_mfma_f32_16x16x32_bf16 v[66:69], v[206:209], v[190:193], v[66:69]
	s_mov_b32 m0, s60
	s_barrier
	ds_read_b128 v[158:161], v171 offset:49152
	ds_read_b128 v[162:165], v171 offset:50176
	ds_read_b128 v[166:169], v171 offset:51200
	ds_read_b128 v[172:175], v171 offset:52224
	ds_read_b128 v[176:179], v171 offset:53248
	ds_read_b128 v[180:183], v171 offset:54272
	ds_read_b128 v[184:187], v171 offset:55296
	ds_read_b128 v[190:193], v171 offset:56320
	s_add_u32 s98, s100, s40
	s_addc_u32 s99, s101, s41
	global_load_lds_dwordx4 v146, s[98:99]
	s_mov_b32 m0, s61
	s_nop 0
	global_load_lds_dwordx4 v150, s[98:99]
	s_waitcnt vmcnt(10)
	s_barrier
	s_waitcnt lgkmcnt(0)
	v_mfma_f32_16x16x32_bf16 v[62:65], v[130:133], v[158:161], v[62:65]
	v_mfma_f32_16x16x32_bf16 v[58:61], v[138:141], v[158:161], v[58:61]
	v_mfma_f32_16x16x32_bf16 v[46:49], v[130:133], v[166:169], v[46:49]
	v_mfma_f32_16x16x32_bf16 v[42:45], v[138:141], v[166:169], v[42:45]
	v_mfma_f32_16x16x32_bf16 v[30:33], v[130:133], v[176:179], v[30:33]
	v_mfma_f32_16x16x32_bf16 v[26:29], v[138:141], v[176:179], v[26:29]
	v_mfma_f32_16x16x32_bf16 v[14:17], v[130:133], v[184:187], v[14:17]
	v_mfma_f32_16x16x32_bf16 v[10:13], v[138:141], v[184:187], v[10:13]
	v_mfma_f32_16x16x32_bf16 v[62:65], v[134:137], v[162:165], v[62:65]
	v_mfma_f32_16x16x32_bf16 v[58:61], v[142:145], v[162:165], v[58:61]
	v_mfma_f32_16x16x32_bf16 v[46:49], v[134:137], v[172:175], v[46:49]
	v_mfma_f32_16x16x32_bf16 v[42:45], v[142:145], v[172:175], v[42:45]
	v_mfma_f32_16x16x32_bf16 v[30:33], v[134:137], v[180:183], v[30:33]
	v_mfma_f32_16x16x32_bf16 v[26:29], v[142:145], v[180:183], v[26:29]
	v_mfma_f32_16x16x32_bf16 v[14:17], v[134:137], v[190:193], v[14:17]
	v_mfma_f32_16x16x32_bf16 v[10:13], v[142:145], v[190:193], v[10:13]
	s_barrier
	s_add_u32 s90, s90, 0x40080
	s_addc_u32 s91, s91, 0
	s_add_i32 m0, s38, 0x1c000
	s_nop 0
	global_load_lds_dwordx4 v148, s[90:91]
	s_add_i32 m0, s38, 0x1e000
	s_nop 0
	global_load_lds_dwordx4 v152, s[90:91]
	ds_read_b128 v[130:133], v189
	ds_read_b128 v[134:137], v189 offset:1024
	ds_read_b128 v[138:141], v189 offset:2048
	ds_read_b128 v[142:145], v189 offset:3072
	s_waitcnt vmcnt(6)
	s_barrier
	v_mfma_f32_16x16x32_bf16 v[54:57], v[194:197], v[158:161], v[54:57]
	v_mfma_f32_16x16x32_bf16 v[50:53], v[202:205], v[158:161], v[50:53]
	v_mfma_f32_16x16x32_bf16 v[38:41], v[194:197], v[166:169], v[38:41]
	v_mfma_f32_16x16x32_bf16 v[34:37], v[202:205], v[166:169], v[34:37]
	v_mfma_f32_16x16x32_bf16 v[22:25], v[194:197], v[176:179], v[22:25]
	v_mfma_f32_16x16x32_bf16 v[18:21], v[202:205], v[176:179], v[18:21]
	v_mfma_f32_16x16x32_bf16 v[6:9], v[194:197], v[184:187], v[6:9]
	v_mfma_f32_16x16x32_bf16 v[2:5], v[202:205], v[184:187], v[2:5]
	v_mfma_f32_16x16x32_bf16 v[54:57], v[198:201], v[162:165], v[54:57]
	s_add_i32 s85, s85, 2
	s_add_u32 s88, s88, 0x100
	v_mfma_f32_16x16x32_bf16 v[50:53], v[206:209], v[162:165], v[50:53]
	s_addc_u32 s89, s89, 0
	s_add_u32 s34, s34, 0x100
	v_mfma_f32_16x16x32_bf16 v[38:41], v[198:201], v[172:175], v[38:41]
	s_addc_u32 s79, s79, 0
	s_add_u32 s87, s88, 0xfffc0080
	v_mfma_f32_16x16x32_bf16 v[34:37], v[206:209], v[172:175], v[34:37]
	s_addc_u32 s90, s89, -1
	s_cmp_eq_u32 s85, 12
	v_mfma_f32_16x16x32_bf16 v[22:25], v[198:201], v[180:183], v[22:25]
	s_cselect_b32 s93, s13, s90
	s_cselect_b32 s92, s22, s87
	v_mfma_f32_16x16x32_bf16 v[18:21], v[206:209], v[180:183], v[18:21]
	s_cselect_b32 s91, s7, s79
	s_cselect_b32 s90, s23, s34
	v_mfma_f32_16x16x32_bf16 v[6:9], v[198:201], v[190:193], v[6:9]
	s_cmp_gt_u32 s85, 13
	v_mfma_f32_16x16x32_bf16 v[2:5], v[206:209], v[190:193], v[2:5]
	s_barrier
	s_cbranch_scc0 .LBB0_1209
	s_waitcnt lgkmcnt(0)
	v_mov_b32_e32 v131, v252
	s_lshl_b32 s7, s86, 8
	v_and_b32_e32 v130, 63, v131
	v_or_b32_e32 v0, s72, v130
	v_lshrrev_b32_e32 v0, 1, v0
	v_and_or_b32 v132, v0, 63, s73
	v_add_u32_e32 v134, s7, v132
	v_ashrrev_i32_e32 v135, 31, v134
	v_and_b32_e32 v142, 1, v131
	v_lshlrev_b64 v[134:135], 6, v[134:135]
	v_lshl_add_u64 v[134:135], s[82:83], 0, v[134:135]
	v_lshlrev_b32_e32 v0, 5, v142
	v_lshl_add_u64 v[138:139], v[134:135], 0, v[0:1]
	global_load_dwordx4 v[134:137], v[138:139], off
	s_nop 0
	global_load_dwordx4 v[138:141], v[138:139], off offset:16
	v_lshlrev_b32_e32 v0, 2, v130
	v_cmp_eq_u32_e32 vcc, 0, v142
	s_waitcnt vmcnt(0)
	v_add_f32_e32 v133, v134, v135
	v_add_f32_e32 v134, v136, v137
	v_add_f32_e32 v135, v138, v139
	v_add_f32_e32 v136, v140, v141
	v_add_f32_e32 v133, v133, v134
	v_add_f32_e32 v134, v135, v136
	v_add_f32_e32 v133, v133, v134
	v_xor_b32_e32 v134, 4, v0
	ds_bpermute_b32 v134, v134, v133
	s_and_saveexec_b64 s[22:23], vcc
	s_cbranch_execz .LBB0_1212
	s_waitcnt lgkmcnt(0)
	v_add_f32_e32 v133, v133, v134
	v_fmamk_f32 v133, v133, 0x3a800000, v224
	s_mov_b32 s13, 0x800000
	v_mul_f32_e32 v134, 0x4b800000, v133
	v_cmp_gt_f32_e32 vcc, s13, v133
	v_lshl_add_u32 v132, v132, 2, 0
	v_add_u32_e32 v132, 0x20000, v132
	v_cndmask_b32_e32 v133, v133, v134, vcc
	v_rsq_f32_e32 v133, v133
	s_nop 0
	v_mul_f32_e32 v134, 0x45800000, v133
	v_cndmask_b32_e32 v133, v133, v134, vcc
	ds_write_b32 v132, v133
